# v7 + MFMA k-inner order: each accumulator's k=0 and k=1 MFMAs issued back to back (SrcC forwarding chain)
# speedup vs baseline: 1.0166x; 1.0166x over previous
; #define PG8_STAGE(bufoff, gbase, voff) do { _Pragma("unroll") for (int _i = 0; _i < 2; ++_i) \
;         __builtin_amdgcn_global_load_lds((const unsigned*)((const char*)(gbase) + (voff)[_i]), (PG8_LAS unsigned*)(lds + (bufoff) + ldsw + _i * 8192), 16, 0, 0); } while (0)
; #define PG8_LDA(dst, b, h) do { _Pragma("unroll") for (int m = 0; m < 4; ++m) _Pragma("unroll") for (int k = 0; k < 2; ++k) dst[m][k] = *(const PG8_LAS bf16x8*)(lds + PG8_SA(b, h) + aoff + m * 2048 + k * 1024); } while (0)
; #define PG8_MMA(ai, bj, At, Bt) do { __builtin_amdgcn_s_setprio(3); _Pragma("unroll") for (int m = 0; m < 4; ++m) _Pragma("unroll") for (int n = 0; n < 2; ++n) _Pragma("unroll") for (int k = 0; k < 2; ++k) \
;         acc[ai][bj][m][n] = __builtin_amdgcn_mfma_f32_16x16x32_bf16(Bt[n][k], At[m][k], acc[ai][bj][m][n], 0, 0, 0); __builtin_amdgcn_s_setprio(0); } while (0)
; #define PG8_WAIT_V(n) asm volatile("s_waitcnt vmcnt(" #n ")" ::: "memory")
; #define PG8_WAIT_L(n) asm volatile("s_waitcnt lgkmcnt(" #n ")" ::: "memory")
; #define PG8_BAR __builtin_amdgcn_s_barrier()
; #define PG8_SCHED __builtin_amdgcn_sched_barrier(0)
; template <class Epi, class Sched, bool ALIGN_EPI = false, bool SP2 = false>
; __device__ __forceinline__ void gemm_phase(PG8_LAS unsigned char* lds, const Gemm g, const Sched& S, const Epi& E) {
;     ...
;             PG8_WAIT_V(8); PG8_WAIT_L(0); PG8_BAR; PG8_MMA(0, 0, At, B0); PG8_MMA(0, 1, At, B1); PG8_BAR; PG8_SCHED;
;             PG8_LDA(At, 0, 1); PG8_STAGE(PG8_SB(0, 0), b2, voffB); PG8_STAGE(PG8_SB(0, 1), b2 + hstepB, voffB); PG8_STAGE(PG8_SA(0, 0), a2, voffA);
.Lengw1_e:
	s_waitcnt lgkmcnt(0)
	s_barrier
	s_setprio 3
	s_waitcnt lgkmcnt(0)
	v_mfma_f32_16x16x32_bf16 v[126:129], v[130:133], v[192:195], v[126:129]
	v_mfma_f32_16x16x32_bf16 v[126:129], v[134:137], v[196:199], v[126:129]
	v_mfma_f32_16x16x32_bf16 v[118:121], v[156:159], v[192:195], v[118:121]
	v_mfma_f32_16x16x32_bf16 v[118:121], v[172:175], v[196:199], v[118:121]
	v_mfma_f32_16x16x32_bf16 v[110:113], v[130:133], v[200:203], v[110:113]
	v_mfma_f32_16x16x32_bf16 v[110:113], v[134:137], v[204:207], v[110:113]
	v_mfma_f32_16x16x32_bf16 v[102:105], v[156:159], v[200:203], v[102:105]
	v_mfma_f32_16x16x32_bf16 v[102:105], v[172:175], v[204:207], v[102:105]
	v_mfma_f32_16x16x32_bf16 v[94:97], v[130:133], v[208:211], v[94:97]
	v_mfma_f32_16x16x32_bf16 v[94:97], v[134:137], v[212:215], v[94:97]
	v_mfma_f32_16x16x32_bf16 v[86:89], v[156:159], v[208:211], v[86:89]
	v_mfma_f32_16x16x32_bf16 v[86:89], v[172:175], v[212:215], v[86:89]
	v_mfma_f32_16x16x32_bf16 v[78:81], v[130:133], v[216:219], v[78:81]
	v_mfma_f32_16x16x32_bf16 v[78:81], v[134:137], v[220:223], v[78:81]
	v_mfma_f32_16x16x32_bf16 v[70:73], v[156:159], v[216:219], v[70:73]
	v_mfma_f32_16x16x32_bf16 v[70:73], v[172:175], v[220:223], v[70:73]
	s_setprio 0
	s_setprio 3
	v_mfma_f32_16x16x32_bf16 v[122:125], v[176:179], v[192:195], v[122:125]
	v_mfma_f32_16x16x32_bf16 v[122:125], v[180:183], v[196:199], v[122:125]
	v_mfma_f32_16x16x32_bf16 v[114:117], v[184:187], v[192:195], v[114:117]
	v_mfma_f32_16x16x32_bf16 v[114:117], v[188:191], v[196:199], v[114:117]
	v_mfma_f32_16x16x32_bf16 v[106:109], v[176:179], v[200:203], v[106:109]
	v_mfma_f32_16x16x32_bf16 v[106:109], v[180:183], v[204:207], v[106:109]
	v_mfma_f32_16x16x32_bf16 v[98:101], v[184:187], v[200:203], v[98:101]
	v_mfma_f32_16x16x32_bf16 v[98:101], v[188:191], v[204:207], v[98:101]
	v_mfma_f32_16x16x32_bf16 v[90:93], v[176:179], v[208:211], v[90:93]
	v_mfma_f32_16x16x32_bf16 v[90:93], v[180:183], v[212:215], v[90:93]
	v_mfma_f32_16x16x32_bf16 v[82:85], v[184:187], v[208:211], v[82:85]
	v_mfma_f32_16x16x32_bf16 v[82:85], v[188:191], v[212:215], v[82:85]
	v_mfma_f32_16x16x32_bf16 v[74:77], v[176:179], v[216:219], v[74:77]
	v_mfma_f32_16x16x32_bf16 v[74:77], v[180:183], v[220:223], v[74:77]
	v_mfma_f32_16x16x32_bf16 v[66:69], v[184:187], v[216:219], v[66:69]
	v_mfma_f32_16x16x32_bf16 v[66:69], v[188:191], v[220:223], v[66:69]
	s_setprio 0
	s_barrier
	s_add_i32 s56, s83, s66
	v_lshl_add_u64 v[160:161], s[8:9], 0, v[140:141]
	s_mov_b32 m0, s56
	ds_read_b128 v[192:195], v169 offset:16384
	ds_read_b128 v[196:199], v169 offset:17408
	ds_read_b128 v[200:203], v169 offset:18432
	ds_read_b128 v[204:207], v169 offset:19456
	ds_read_b128 v[208:211], v169 offset:20480
	ds_read_b128 v[212:215], v169 offset:21504
	ds_read_b128 v[216:219], v169 offset:22528
	ds_read_b128 v[220:223], v169 offset:23552
	global_load_lds_dwordx4 v[160:161], off
	s_add_i32 m0, s56, 0x2000
	s_add_u32 s56, s8, 0x100000
	v_lshl_add_u64 v[224:225], s[8:9], 0, v[144:145]
	s_addc_u32 s57, s9, 0
	s_add_i32 s58, s89, s66
	global_load_lds_dwordx4 v[224:225], off
	v_lshl_add_u64 v[226:227], s[56:57], 0, v[140:141]
	s_mov_b32 m0, s58
	v_lshl_add_u64 v[228:229], s[36:37], 0, v[142:143]
	global_load_lds_dwordx4 v[226:227], off
	v_lshl_add_u64 v[226:227], s[56:57], 0, v[144:145]
	s_add_i32 m0, s58, 0x2000
	s_nop 0
	global_load_lds_dwordx4 v[226:227], off
	v_lshl_add_u64 v[226:227], s[36:37], 0, v[138:139]
	s_mov_b32 m0, s55
	s_nop 0
	global_load_lds_dwordx4 v[226:227], off
	s_mov_b32 m0, s67
	s_nop 0
	global_load_lds_dwordx4 v[228:229], off
	s_cmp_eq_u32 s97, 0
	s_cbranch_scc1 .Lengw2_a
	s_cmp_eq_u32 s97, 2
	s_cbranch_scc1 .Lengw2_b
	s_cmp_eq_u32 s97, 4
	s_cbranch_scc1 .Lengw2_c
	s_waitcnt vmcnt(16)
	s_branch .Lengw2_e

; #define PG8_STAGE(bufoff, gbase, voff) do { _Pragma("unroll") for (int _i = 0; _i < 2; ++_i) \
;         __builtin_amdgcn_global_load_lds((const unsigned*)((const char*)(gbase) + (voff)[_i]), (PG8_LAS unsigned*)(lds + (bufoff) + ldsw + _i * 8192), 16, 0, 0); } while (0)
; #define PG8_LDA(dst, b, h) do { _Pragma("unroll") for (int m = 0; m < 4; ++m) _Pragma("unroll") for (int k = 0; k < 2; ++k) dst[m][k] = *(const PG8_LAS bf16x8*)(lds + PG8_SA(b, h) + aoff + m * 2048 + k * 1024); } while (0)
; #define PG8_LDB(dst, b, h) do { _Pragma("unroll") for (int n = 0; n < 2; ++n) _Pragma("unroll") for (int k = 0; k < 2; ++k) dst[n][k] = *(const PG8_LAS bf16x8*)(lds + PG8_SB(b, h) + boff + n * 2048 + k * 1024); } while (0)
; #define PG8_MMA(ai, bj, At, Bt) do { __builtin_amdgcn_s_setprio(3); _Pragma("unroll") for (int m = 0; m < 4; ++m) _Pragma("unroll") for (int n = 0; n < 2; ++n) _Pragma("unroll") for (int k = 0; k < 2; ++k) \
;         acc[ai][bj][m][n] = __builtin_amdgcn_mfma_f32_16x16x32_bf16(Bt[n][k], At[m][k], acc[ai][bj][m][n], 0, 0, 0); __builtin_amdgcn_s_setprio(0); } while (0)
; #define PG8_WAIT_V(n) asm volatile("s_waitcnt vmcnt(" #n ")" ::: "memory")
; #define PG8_WAIT_L(n) asm volatile("s_waitcnt lgkmcnt(" #n ")" ::: "memory")
; #define PG8_BAR __builtin_amdgcn_s_barrier()
; #define PG8_SCHED __builtin_amdgcn_sched_barrier(0)
; template <class Epi, class Sched, bool ALIGN_EPI = false, bool SP2 = false>
; __device__ __forceinline__ void gemm_phase(PG8_LAS unsigned char* lds, const Gemm g, const Sched& S, const Epi& E) {
;     ...
;             PG8_WAIT_V(8); PG8_WAIT_L(0); PG8_BAR; PG8_MMA(1, 0, At, B0); PG8_MMA(1, 1, At, B1); PG8_BAR; PG8_SCHED;
;             PG8_LDB(B0, 1, 0); PG8_LDB(B1, 1, 1); PG8_SCHED; PG8_LDA(At, 1, 0); PG8_STAGE(PG8_SA(0, 1), a2 + hstepA, voffA);
.Lengw2_e:
	s_waitcnt lgkmcnt(0)
	s_barrier
	s_setprio 3
	s_waitcnt lgkmcnt(0)
	v_mfma_f32_16x16x32_bf16 v[62:65], v[130:133], v[192:195], v[62:65]
	v_mfma_f32_16x16x32_bf16 v[62:65], v[134:137], v[196:199], v[62:65]
	v_mfma_f32_16x16x32_bf16 v[54:57], v[156:159], v[192:195], v[54:57]
	v_mfma_f32_16x16x32_bf16 v[54:57], v[172:175], v[196:199], v[54:57]
	v_mfma_f32_16x16x32_bf16 v[46:49], v[130:133], v[200:203], v[46:49]
	v_mfma_f32_16x16x32_bf16 v[46:49], v[134:137], v[204:207], v[46:49]
	v_mfma_f32_16x16x32_bf16 v[38:41], v[156:159], v[200:203], v[38:41]
	v_mfma_f32_16x16x32_bf16 v[38:41], v[172:175], v[204:207], v[38:41]
	v_mfma_f32_16x16x32_bf16 v[30:33], v[130:133], v[208:211], v[30:33]
	v_mfma_f32_16x16x32_bf16 v[30:33], v[134:137], v[212:215], v[30:33]
	v_mfma_f32_16x16x32_bf16 v[22:25], v[156:159], v[208:211], v[22:25]
	v_mfma_f32_16x16x32_bf16 v[22:25], v[172:175], v[212:215], v[22:25]
	v_mfma_f32_16x16x32_bf16 v[14:17], v[130:133], v[216:219], v[14:17]
	v_mfma_f32_16x16x32_bf16 v[14:17], v[134:137], v[220:223], v[14:17]
	v_mfma_f32_16x16x32_bf16 v[6:9], v[156:159], v[216:219], v[6:9]
	v_mfma_f32_16x16x32_bf16 v[6:9], v[172:175], v[220:223], v[6:9]
	s_setprio 0
	s_setprio 3
	v_mfma_f32_16x16x32_bf16 v[58:61], v[176:179], v[192:195], v[58:61]
	v_mfma_f32_16x16x32_bf16 v[58:61], v[180:183], v[196:199], v[58:61]
	v_mfma_f32_16x16x32_bf16 v[50:53], v[184:187], v[192:195], v[50:53]
	v_mfma_f32_16x16x32_bf16 v[50:53], v[188:191], v[196:199], v[50:53]
	v_mfma_f32_16x16x32_bf16 v[42:45], v[176:179], v[200:203], v[42:45]
	v_mfma_f32_16x16x32_bf16 v[42:45], v[180:183], v[204:207], v[42:45]
	v_mfma_f32_16x16x32_bf16 v[34:37], v[184:187], v[200:203], v[34:37]
	v_mfma_f32_16x16x32_bf16 v[34:37], v[188:191], v[204:207], v[34:37]
	v_mfma_f32_16x16x32_bf16 v[26:29], v[176:179], v[208:211], v[26:29]
	v_mfma_f32_16x16x32_bf16 v[26:29], v[180:183], v[212:215], v[26:29]
	v_mfma_f32_16x16x32_bf16 v[18:21], v[184:187], v[208:211], v[18:21]
	v_mfma_f32_16x16x32_bf16 v[18:21], v[188:191], v[212:215], v[18:21]
	v_mfma_f32_16x16x32_bf16 v[10:13], v[176:179], v[216:219], v[10:13]
	v_mfma_f32_16x16x32_bf16 v[10:13], v[180:183], v[220:223], v[10:13]
	v_mfma_f32_16x16x32_bf16 v[2:5], v[184:187], v[216:219], v[2:5]
	v_mfma_f32_16x16x32_bf16 v[2:5], v[188:191], v[220:223], v[2:5]
	s_setprio 0
	s_barrier
	s_add_i32 s56, 0, 0x18000
	v_add_u32_e32 v146, s56, v164
	s_add_i32 s57, 0, 0x1c000
	ds_read_b128 v[130:133], v146
	ds_read_b128 v[134:137], v146 offset:1024
	ds_read_b128 v[156:159], v146 offset:2048
	ds_read_b128 v[172:175], v146 offset:3072
	v_add_u32_e32 v146, s57, v164
	ds_read_b128 v[176:179], v146
	ds_read_b128 v[180:183], v146 offset:1024
	ds_read_b128 v[184:187], v146 offset:2048
	ds_read_b128 v[188:191], v146 offset:3072
	s_add_u32 s36, s36, 0x100000
	s_addc_u32 s37, s37, 0
	s_mov_b32 m0, s72
	v_lshl_add_u64 v[230:231], s[36:37], 0, v[138:139]
	ds_read_b128 v[192:195], v169 offset:32768
	ds_read_b128 v[196:199], v169 offset:33792
	ds_read_b128 v[200:203], v169 offset:34816
	ds_read_b128 v[204:207], v169 offset:35840
	ds_read_b128 v[208:211], v169 offset:36864
	ds_read_b128 v[212:215], v169 offset:37888
	ds_read_b128 v[216:219], v169 offset:38912
	ds_read_b128 v[220:223], v169 offset:39936
	global_load_lds_dwordx4 v[230:231], off
	v_lshl_add_u64 v[230:231], s[36:37], 0, v[142:143]
	s_mov_b32 m0, s73
	s_nop 0
	global_load_lds_dwordx4 v[230:231], off
	s_cmp_eq_u32 s97, 4
	s_cbranch_scc1 .Lengw3_c
	s_cmp_eq_u32 s97, 8
	s_cbranch_scc1 .Lengw3_d
	s_waitcnt vmcnt(8)
	s_branch .Lengw3_e

; #define PG8_STAGE(bufoff, gbase, voff) do { _Pragma("unroll") for (int _i = 0; _i < 2; ++_i) \
;         __builtin_amdgcn_global_load_lds((const unsigned*)((const char*)(gbase) + (voff)[_i]), (PG8_LAS unsigned*)(lds + (bufoff) + ldsw + _i * 8192), 16, 0, 0); } while (0)
; #define PG8_LDA(dst, b, h) do { _Pragma("unroll") for (int m = 0; m < 4; ++m) _Pragma("unroll") for (int k = 0; k < 2; ++k) dst[m][k] = *(const PG8_LAS bf16x8*)(lds + PG8_SA(b, h) + aoff + m * 2048 + k * 1024); } while (0)
; #define PG8_MMA(ai, bj, At, Bt) do { __builtin_amdgcn_s_setprio(3); _Pragma("unroll") for (int m = 0; m < 4; ++m) _Pragma("unroll") for (int n = 0; n < 2; ++n) _Pragma("unroll") for (int k = 0; k < 2; ++k) \
;         acc[ai][bj][m][n] = __builtin_amdgcn_mfma_f32_16x16x32_bf16(Bt[n][k], At[m][k], acc[ai][bj][m][n], 0, 0, 0); __builtin_amdgcn_s_setprio(0); } while (0)
; #define PG8_WAIT_V(n) asm volatile("s_waitcnt vmcnt(" #n ")" ::: "memory")
; #define PG8_WAIT_L(n) asm volatile("s_waitcnt lgkmcnt(" #n ")" ::: "memory")
; #define PG8_BAR __builtin_amdgcn_s_barrier()
; #define PG8_SCHED __builtin_amdgcn_sched_barrier(0)
; template <class Epi, class Sched, bool ALIGN_EPI = false, bool SP2 = false>
; __device__ __forceinline__ void gemm_phase(PG8_LAS unsigned char* lds, const Gemm g, const Sched& S, const Epi& E) {
;     ...
;             PG8_WAIT_V(8); PG8_WAIT_L(0); PG8_BAR; PG8_MMA(0, 0, At, B0); PG8_MMA(0, 1, At, B1); PG8_BAR; PG8_SCHED;
;             PG8_LDA(At, 1, 1); PG8_STAGE(PG8_SB(1, 0), b3, voffB); PG8_STAGE(PG8_SB(1, 1), b3 + hstepB, voffB); PG8_STAGE(PG8_SA(1, 0), a3, voffA);
;             PG8_WAIT_V(8); PG8_WAIT_L(0); PG8_BAR; PG8_MMA(1, 0, At, B0); PG8_MMA(1, 1, At, B1); PG8_BAR; PG8_SCHED;
;     __device__ __forceinline__ void operator()(const f32x4 (&acc)[2][2][4][2], const Unit& u, int wr, int wc, int fr, int fq) const {
;         const int row0 = u.pm * BM + wr * 64 + fr; const int cls = u.pn >> 3;
;         if (u.pn >= 40) {
.Lengw3_e:
	s_waitcnt lgkmcnt(0)
	s_barrier
	s_setprio 3
	s_waitcnt lgkmcnt(0)
	v_mfma_f32_16x16x32_bf16 v[126:129], v[130:133], v[192:195], v[126:129]
	v_mfma_f32_16x16x32_bf16 v[126:129], v[134:137], v[196:199], v[126:129]
	v_mfma_f32_16x16x32_bf16 v[118:121], v[156:159], v[192:195], v[118:121]
	v_mfma_f32_16x16x32_bf16 v[118:121], v[172:175], v[196:199], v[118:121]
	v_mfma_f32_16x16x32_bf16 v[110:113], v[130:133], v[200:203], v[110:113]
	v_mfma_f32_16x16x32_bf16 v[110:113], v[134:137], v[204:207], v[110:113]
	v_mfma_f32_16x16x32_bf16 v[102:105], v[156:159], v[200:203], v[102:105]
	v_mfma_f32_16x16x32_bf16 v[102:105], v[172:175], v[204:207], v[102:105]
	v_mfma_f32_16x16x32_bf16 v[94:97], v[130:133], v[208:211], v[94:97]
	v_mfma_f32_16x16x32_bf16 v[94:97], v[134:137], v[212:215], v[94:97]
	v_mfma_f32_16x16x32_bf16 v[86:89], v[156:159], v[208:211], v[86:89]
	v_mfma_f32_16x16x32_bf16 v[86:89], v[172:175], v[212:215], v[86:89]
	v_mfma_f32_16x16x32_bf16 v[78:81], v[130:133], v[216:219], v[78:81]
	v_mfma_f32_16x16x32_bf16 v[78:81], v[134:137], v[220:223], v[78:81]
	v_mfma_f32_16x16x32_bf16 v[70:73], v[156:159], v[216:219], v[70:73]
	v_mfma_f32_16x16x32_bf16 v[70:73], v[172:175], v[220:223], v[70:73]
	s_setprio 0
	s_setprio 3
	v_mfma_f32_16x16x32_bf16 v[122:125], v[176:179], v[192:195], v[122:125]
	v_mfma_f32_16x16x32_bf16 v[122:125], v[180:183], v[196:199], v[122:125]
	v_mfma_f32_16x16x32_bf16 v[114:117], v[184:187], v[192:195], v[114:117]
	v_mfma_f32_16x16x32_bf16 v[114:117], v[188:191], v[196:199], v[114:117]
	v_mfma_f32_16x16x32_bf16 v[106:109], v[176:179], v[200:203], v[106:109]
	v_mfma_f32_16x16x32_bf16 v[106:109], v[180:183], v[204:207], v[106:109]
	v_mfma_f32_16x16x32_bf16 v[98:101], v[184:187], v[200:203], v[98:101]
	v_mfma_f32_16x16x32_bf16 v[98:101], v[188:191], v[204:207], v[98:101]
	v_mfma_f32_16x16x32_bf16 v[90:93], v[176:179], v[208:211], v[90:93]
	v_mfma_f32_16x16x32_bf16 v[90:93], v[180:183], v[212:215], v[90:93]
	v_mfma_f32_16x16x32_bf16 v[82:85], v[184:187], v[208:211], v[82:85]
	v_mfma_f32_16x16x32_bf16 v[82:85], v[188:191], v[212:215], v[82:85]
	v_mfma_f32_16x16x32_bf16 v[74:77], v[176:179], v[216:219], v[74:77]
	v_mfma_f32_16x16x32_bf16 v[74:77], v[180:183], v[220:223], v[74:77]
	v_mfma_f32_16x16x32_bf16 v[66:69], v[184:187], v[216:219], v[66:69]
	v_mfma_f32_16x16x32_bf16 v[66:69], v[188:191], v[220:223], v[66:69]
	s_setprio 0
	s_barrier
	s_add_i32 s36, s56, s66
	v_lshl_add_u64 v[160:161], v[160:161], 0, s[18:19]
	s_mov_b32 m0, s36
	ds_read_b128 v[192:195], v169 offset:49152
	ds_read_b128 v[196:199], v169 offset:50176
	ds_read_b128 v[200:203], v169 offset:51200
	ds_read_b128 v[204:207], v169 offset:52224
	ds_read_b128 v[208:211], v169 offset:53248
	ds_read_b128 v[212:215], v169 offset:54272
	ds_read_b128 v[216:219], v169 offset:55296
	ds_read_b128 v[220:223], v169 offset:56320
	global_load_lds_dwordx4 v[160:161], off
	s_add_i32 m0, s36, 0x2000
	s_add_u32 s8, s8, 0x100080
	v_lshl_add_u64 v[160:161], v[224:225], 0, s[18:19]
	s_addc_u32 s9, s9, 0
	s_add_i32 s36, s57, s66
	global_load_lds_dwordx4 v[160:161], off
	v_lshl_add_u64 v[160:161], s[8:9], 0, v[140:141]
	s_mov_b32 m0, s36
	s_nop 0
	global_load_lds_dwordx4 v[160:161], off
	v_lshl_add_u64 v[160:161], s[8:9], 0, v[144:145]
	s_add_i32 m0, s36, 0x2000
	s_nop 0
	global_load_lds_dwordx4 v[160:161], off
	v_lshl_add_u64 v[160:161], v[226:227], 0, s[18:19]
	s_mov_b32 m0, s75
	s_nop 0
	global_load_lds_dwordx4 v[160:161], off
	v_lshl_add_u64 v[160:161], v[228:229], 0, s[18:19]
	s_mov_b32 m0, s76
	s_nop 0
	global_load_lds_dwordx4 v[160:161], off
	s_waitcnt vmcnt(8)
	s_waitcnt lgkmcnt(0)
	s_barrier
	s_setprio 3
	s_waitcnt lgkmcnt(0)
	v_mfma_f32_16x16x32_bf16 v[62:65], v[130:133], v[192:195], v[62:65]
	v_mfma_f32_16x16x32_bf16 v[62:65], v[134:137], v[196:199], v[62:65]
	v_mfma_f32_16x16x32_bf16 v[54:57], v[156:159], v[192:195], v[54:57]
	v_mfma_f32_16x16x32_bf16 v[54:57], v[172:175], v[196:199], v[54:57]
	v_mfma_f32_16x16x32_bf16 v[46:49], v[130:133], v[200:203], v[46:49]
	v_mfma_f32_16x16x32_bf16 v[46:49], v[134:137], v[204:207], v[46:49]
	v_mfma_f32_16x16x32_bf16 v[38:41], v[156:159], v[200:203], v[38:41]
	v_mfma_f32_16x16x32_bf16 v[38:41], v[172:175], v[204:207], v[38:41]
	v_mfma_f32_16x16x32_bf16 v[30:33], v[130:133], v[208:211], v[30:33]
	v_mfma_f32_16x16x32_bf16 v[30:33], v[134:137], v[212:215], v[30:33]
	v_mfma_f32_16x16x32_bf16 v[22:25], v[156:159], v[208:211], v[22:25]
	v_mfma_f32_16x16x32_bf16 v[22:25], v[172:175], v[212:215], v[22:25]
	v_mfma_f32_16x16x32_bf16 v[14:17], v[130:133], v[216:219], v[14:17]
	v_mfma_f32_16x16x32_bf16 v[14:17], v[134:137], v[220:223], v[14:17]
	v_mfma_f32_16x16x32_bf16 v[6:9], v[156:159], v[216:219], v[6:9]
	v_mfma_f32_16x16x32_bf16 v[6:9], v[172:175], v[220:223], v[6:9]
	s_setprio 0
	s_setprio 3
	v_mfma_f32_16x16x32_bf16 v[58:61], v[176:179], v[192:195], v[58:61]
	v_mfma_f32_16x16x32_bf16 v[58:61], v[180:183], v[196:199], v[58:61]
	v_mfma_f32_16x16x32_bf16 v[50:53], v[184:187], v[192:195], v[50:53]
	v_mfma_f32_16x16x32_bf16 v[50:53], v[188:191], v[196:199], v[50:53]
	v_mfma_f32_16x16x32_bf16 v[42:45], v[176:179], v[200:203], v[42:45]
	v_mfma_f32_16x16x32_bf16 v[42:45], v[180:183], v[204:207], v[42:45]
	v_mfma_f32_16x16x32_bf16 v[34:37], v[184:187], v[200:203], v[34:37]
	v_mfma_f32_16x16x32_bf16 v[34:37], v[188:191], v[204:207], v[34:37]
	v_mfma_f32_16x16x32_bf16 v[26:29], v[176:179], v[208:211], v[26:29]
	v_mfma_f32_16x16x32_bf16 v[26:29], v[180:183], v[212:215], v[26:29]
	v_mfma_f32_16x16x32_bf16 v[18:21], v[184:187], v[208:211], v[18:21]
	v_mfma_f32_16x16x32_bf16 v[18:21], v[188:191], v[212:215], v[18:21]
	v_mfma_f32_16x16x32_bf16 v[10:13], v[176:179], v[216:219], v[10:13]
	v_mfma_f32_16x16x32_bf16 v[10:13], v[180:183], v[220:223], v[10:13]
	v_mfma_f32_16x16x32_bf16 v[2:5], v[184:187], v[216:219], v[2:5]
	v_mfma_f32_16x16x32_bf16 v[2:5], v[188:191], v[220:223], v[2:5]
	s_setprio 0
	s_barrier
	s_add_i32 s45, s45, 2
	s_add_u32 s6, s6, 0x100
	s_addc_u32 s7, s7, 0
	s_add_u32 s33, s33, 0x100
	s_addc_u32 s44, s44, 0
	s_cmp_gt_u32 s45, 61
	s_cbranch_scc0 .LBB0_143
	s_and_b64 vcc, exec, s[20:21]
	s_cbranch_vccz .LBB0_148
	s_barrier
	v_lshl_add_u32 v156, s0, 8, v163
	s_cmp_lt_i32 s54, 40
	s_mov_b64 s[0:1], -1
	s_cbranch_scc1 .LBB0_149

; #define PG8_STAGE(bufoff, gbase, voff) do { _Pragma("unroll") for (int _i = 0; _i < 2; ++_i) \
;         __builtin_amdgcn_global_load_lds((const unsigned*)((const char*)(gbase) + (voff)[_i]), (PG8_LAS unsigned*)(lds + (bufoff) + ldsw + _i * 8192), 16, 0, 0); } while (0)
; #define PG8_LDA(dst, b, h) do { _Pragma("unroll") for (int m = 0; m < 4; ++m) _Pragma("unroll") for (int k = 0; k < 2; ++k) dst[m][k] = *(const PG8_LAS bf16x8*)(lds + PG8_SA(b, h) + aoff + m * 2048 + k * 1024); } while (0)
; #define PG8_LDB(dst, b, h) do { _Pragma("unroll") for (int n = 0; n < 2; ++n) _Pragma("unroll") for (int k = 0; k < 2; ++k) dst[n][k] = *(const PG8_LAS bf16x8*)(lds + PG8_SB(b, h) + boff + n * 2048 + k * 1024); } while (0)
; #define PG8_MMA(ai, bj, At, Bt) do { __builtin_amdgcn_s_setprio(3); _Pragma("unroll") for (int m = 0; m < 4; ++m) _Pragma("unroll") for (int n = 0; n < 2; ++n) _Pragma("unroll") for (int k = 0; k < 2; ++k) \
;         acc[ai][bj][m][n] = __builtin_amdgcn_mfma_f32_16x16x32_bf16(Bt[n][k], At[m][k], acc[ai][bj][m][n], 0, 0, 0); __builtin_amdgcn_s_setprio(0); } while (0)
; #define PG8_WAIT_V(n) asm volatile("s_waitcnt vmcnt(" #n ")" ::: "memory")
; #define PG8_WAIT_L(n) asm volatile("s_waitcnt lgkmcnt(" #n ")" ::: "memory")
; template <class Epi, class Sched, bool ALIGN_EPI = false, bool SP2 = false>
; __device__ __forceinline__ void gemm_phase(PG8_LAS unsigned char* lds, const Gemm g, const Sched& S, const Epi& E) {
;     ...
;         for (int t = 0; t < nt; t += 2) {
;             const bool last = (t == nt - 2);
;             const char* a1 = cA + (size_t)(t + 1) * kstep;
;             const char* a2 = last ? nA : cA + (size_t)(t + 2) * kstep; const char* b2 = last ? nB : cB + (size_t)(t + 2) * kstep;
;             const char* a3 = a2 + kstep; const char* b3 = b2 + kstep;
;             if (last && has_next) S.a_ready(nxt);
;             if constexpr (Epi::MIDK) { if (t == E.midk_step(nt)) E.midk(acc, cur, wr, wc, fr, fq); }
;             if constexpr (SP2) {
;             PG8_LDB(B0, 0, 0); PG8_LDB(B1, 0, 1); PG8_SCHED; PG8_LDA(At, 0, 0); PG8_STAGE(PG8_SA(1, 1), a1 + hstepA, voffA);
;             PG8_WAIT_V(8); PG8_WAIT_L(0); PG8_BAR; PG8_MMA(0, 0, At, B0); PG8_MMA(0, 1, At, B1); PG8_BAR; PG8_SCHED;
;             PG8_LDA(At, 0, 1); PG8_STAGE(PG8_SB(0, 0), b2, voffB); PG8_STAGE(PG8_SB(0, 1), b2 + hstepB, voffB); PG8_STAGE(PG8_SA(0, 0), a2, voffA);
.LBB0_478:
	ds_read_b128 v[130:133], v170
	ds_read_b128 v[134:137], v170 offset:1024
	ds_read_b128 v[138:141], v170 offset:2048
	ds_read_b128 v[142:145], v170 offset:3072
	ds_read_b128 v[164:167], v171
	ds_read_b128 v[174:177], v171 offset:1024
	ds_read_b128 v[178:181], v171 offset:2048
	ds_read_b128 v[182:185], v171 offset:3072
	s_add_u32 s36, s6, 0xfff80080
	s_addc_u32 s37, s7, -1
	s_cmp_eq_u32 s79, 4
	s_cselect_b32 s59, s27, s37
	s_cselect_b32 s58, s26, s36
	s_cselect_b32 s37, s23, s78
	s_cselect_b32 s36, s25, s77
	v_lshl_add_u64 v[218:219], s[6:7], 0, v[154:155]
	s_add_i32 m0, s31, 0xc000
	ds_read_b128 v[186:189], v172
	ds_read_b128 v[190:193], v172 offset:1024
	ds_read_b128 v[194:197], v172 offset:2048
	ds_read_b128 v[198:201], v172 offset:3072
	ds_read_b128 v[202:205], v172 offset:4096
	ds_read_b128 v[206:209], v172 offset:5120
	ds_read_b128 v[210:213], v172 offset:6144
	ds_read_b128 v[214:217], v172 offset:7168
	global_load_lds_dwordx4 v[218:219], off
	v_lshl_add_u64 v[218:219], s[6:7], 0, v[156:157]
	s_add_i32 m0, s31, 0xe000
	s_nop 0
	global_load_lds_dwordx4 v[218:219], off
	s_waitcnt vmcnt(8)
	s_waitcnt lgkmcnt(0)
	s_barrier
	s_setprio 3
	s_waitcnt lgkmcnt(0)
	v_mfma_f32_16x16x32_bf16 v[126:129], v[130:133], v[186:189], v[126:129]
	v_mfma_f32_16x16x32_bf16 v[126:129], v[134:137], v[190:193], v[126:129]
	v_mfma_f32_16x16x32_bf16 v[122:125], v[138:141], v[186:189], v[122:125]
	v_mfma_f32_16x16x32_bf16 v[122:125], v[142:145], v[190:193], v[122:125]
	v_mfma_f32_16x16x32_bf16 v[118:121], v[130:133], v[194:197], v[118:121]
	v_mfma_f32_16x16x32_bf16 v[118:121], v[134:137], v[198:201], v[118:121]
	v_mfma_f32_16x16x32_bf16 v[114:117], v[138:141], v[194:197], v[114:117]
	v_mfma_f32_16x16x32_bf16 v[114:117], v[142:145], v[198:201], v[114:117]
	v_mfma_f32_16x16x32_bf16 v[110:113], v[130:133], v[202:205], v[110:113]
	v_mfma_f32_16x16x32_bf16 v[110:113], v[134:137], v[206:209], v[110:113]
	v_mfma_f32_16x16x32_bf16 v[102:105], v[138:141], v[202:205], v[102:105]
	v_mfma_f32_16x16x32_bf16 v[102:105], v[142:145], v[206:209], v[102:105]
	v_mfma_f32_16x16x32_bf16 v[78:81], v[130:133], v[210:213], v[78:81]
	v_mfma_f32_16x16x32_bf16 v[78:81], v[134:137], v[214:217], v[78:81]
	v_mfma_f32_16x16x32_bf16 v[74:77], v[138:141], v[210:213], v[74:77]
	v_mfma_f32_16x16x32_bf16 v[74:77], v[142:145], v[214:217], v[74:77]
	s_setprio 0
	s_setprio 3
	v_mfma_f32_16x16x32_bf16 v[106:109], v[164:167], v[186:189], v[106:109]
	v_mfma_f32_16x16x32_bf16 v[106:109], v[174:177], v[190:193], v[106:109]
	v_mfma_f32_16x16x32_bf16 v[98:101], v[178:181], v[186:189], v[98:101]
	v_mfma_f32_16x16x32_bf16 v[98:101], v[182:185], v[190:193], v[98:101]
	v_mfma_f32_16x16x32_bf16 v[94:97], v[164:167], v[194:197], v[94:97]
	v_mfma_f32_16x16x32_bf16 v[94:97], v[174:177], v[198:201], v[94:97]
	v_mfma_f32_16x16x32_bf16 v[90:93], v[178:181], v[194:197], v[90:93]
	v_mfma_f32_16x16x32_bf16 v[90:93], v[182:185], v[198:201], v[90:93]
	v_mfma_f32_16x16x32_bf16 v[86:89], v[164:167], v[202:205], v[86:89]
	v_mfma_f32_16x16x32_bf16 v[86:89], v[174:177], v[206:209], v[86:89]
	v_mfma_f32_16x16x32_bf16 v[82:85], v[178:181], v[202:205], v[82:85]
	v_mfma_f32_16x16x32_bf16 v[82:85], v[182:185], v[206:209], v[82:85]
	v_mfma_f32_16x16x32_bf16 v[70:73], v[164:167], v[210:213], v[70:73]
	v_mfma_f32_16x16x32_bf16 v[70:73], v[174:177], v[214:217], v[70:73]
	v_mfma_f32_16x16x32_bf16 v[66:69], v[178:181], v[210:213], v[66:69]
	v_mfma_f32_16x16x32_bf16 v[66:69], v[182:185], v[214:217], v[66:69]
	s_setprio 0
	s_barrier
	s_add_i32 s83, s72, s44
	v_lshl_add_u64 v[218:219], s[36:37], 0, v[148:149]
	s_mov_b32 m0, s83
	ds_read_b128 v[186:189], v172 offset:16384
	ds_read_b128 v[190:193], v172 offset:17408
	ds_read_b128 v[194:197], v172 offset:18432
	ds_read_b128 v[198:201], v172 offset:19456
	ds_read_b128 v[202:205], v172 offset:20480
	ds_read_b128 v[206:209], v172 offset:21504
	ds_read_b128 v[210:213], v172 offset:22528
	ds_read_b128 v[214:217], v172 offset:23552
	global_load_lds_dwordx4 v[218:219], off
	s_add_i32 m0, s83, 0x2000
	s_add_u32 s84, s36, 0x20000
	v_lshl_add_u64 v[220:221], s[36:37], 0, v[152:153]
	s_addc_u32 s85, s37, 0
	s_add_i32 s83, s73, s44
	global_load_lds_dwordx4 v[220:221], off
	v_lshl_add_u64 v[222:223], s[84:85], 0, v[148:149]
	s_mov_b32 m0, s83
	v_lshl_add_u64 v[224:225], s[58:59], 0, v[150:151]
	global_load_lds_dwordx4 v[222:223], off
	v_lshl_add_u64 v[222:223], s[84:85], 0, v[152:153]
	s_add_i32 m0, s83, 0x2000
	s_nop 0
	global_load_lds_dwordx4 v[222:223], off
	v_lshl_add_u64 v[222:223], s[58:59], 0, v[146:147]
	s_mov_b32 m0, s31
	s_nop 0
	global_load_lds_dwordx4 v[222:223], off
	s_mov_b32 m0, s45
	s_nop 0
	global_load_lds_dwordx4 v[224:225], off
	s_waitcnt vmcnt(8)
	s_waitcnt lgkmcnt(0)
	s_barrier
; #define PG8_STAGE(bufoff, gbase, voff) do { _Pragma("unroll") for (int _i = 0; _i < 2; ++_i) \
;         __builtin_amdgcn_global_load_lds((const unsigned*)((const char*)(gbase) + (voff)[_i]), (PG8_LAS unsigned*)(lds + (bufoff) + ldsw + _i * 8192), 16, 0, 0); } while (0)
; #define PG8_LDA(dst, b, h) do { _Pragma("unroll") for (int m = 0; m < 4; ++m) _Pragma("unroll") for (int k = 0; k < 2; ++k) dst[m][k] = *(const PG8_LAS bf16x8*)(lds + PG8_SA(b, h) + aoff + m * 2048 + k * 1024); } while (0)
; #define PG8_LDB(dst, b, h) do { _Pragma("unroll") for (int n = 0; n < 2; ++n) _Pragma("unroll") for (int k = 0; k < 2; ++k) dst[n][k] = *(const PG8_LAS bf16x8*)(lds + PG8_SB(b, h) + boff + n * 2048 + k * 1024); } while (0)
; #define PG8_MMA(ai, bj, At, Bt) do { __builtin_amdgcn_s_setprio(3); _Pragma("unroll") for (int m = 0; m < 4; ++m) _Pragma("unroll") for (int n = 0; n < 2; ++n) _Pragma("unroll") for (int k = 0; k < 2; ++k) \
;         acc[ai][bj][m][n] = __builtin_amdgcn_mfma_f32_16x16x32_bf16(Bt[n][k], At[m][k], acc[ai][bj][m][n], 0, 0, 0); __builtin_amdgcn_s_setprio(0); } while (0)
; #define PG8_WAIT_V(n) asm volatile("s_waitcnt vmcnt(" #n ")" ::: "memory")
; #define PG8_WAIT_L(n) asm volatile("s_waitcnt lgkmcnt(" #n ")" ::: "memory")
; #define PG8_BAR __builtin_amdgcn_s_barrier()
; #define PG8_SCHED __builtin_amdgcn_sched_barrier(0)
; template <class Epi, class Sched, bool ALIGN_EPI = false, bool SP2 = false>
; __device__ __forceinline__ void gemm_phase(PG8_LAS unsigned char* lds, const Gemm g, const Sched& S, const Epi& E) {
;     ...
;             PG8_WAIT_V(8); PG8_WAIT_L(0); PG8_BAR; PG8_MMA(1, 0, At, B0); PG8_MMA(1, 1, At, B1); PG8_BAR; PG8_SCHED;
;             PG8_LDB(B0, 1, 0); PG8_LDB(B1, 1, 1); PG8_SCHED; PG8_LDA(At, 1, 0); PG8_STAGE(PG8_SA(0, 1), a2 + hstepA, voffA);
;             PG8_WAIT_V(8); PG8_WAIT_L(0); PG8_BAR; PG8_MMA(0, 0, At, B0); PG8_MMA(0, 1, At, B1); PG8_BAR; PG8_SCHED;
	s_setprio 3
	s_waitcnt lgkmcnt(0)
	v_mfma_f32_16x16x32_bf16 v[62:65], v[130:133], v[186:189], v[62:65]
	v_mfma_f32_16x16x32_bf16 v[62:65], v[134:137], v[190:193], v[62:65]
	v_mfma_f32_16x16x32_bf16 v[58:61], v[138:141], v[186:189], v[58:61]
	v_mfma_f32_16x16x32_bf16 v[58:61], v[142:145], v[190:193], v[58:61]
	v_mfma_f32_16x16x32_bf16 v[54:57], v[130:133], v[194:197], v[54:57]
	v_mfma_f32_16x16x32_bf16 v[54:57], v[134:137], v[198:201], v[54:57]
	v_mfma_f32_16x16x32_bf16 v[46:49], v[138:141], v[194:197], v[46:49]
	v_mfma_f32_16x16x32_bf16 v[46:49], v[142:145], v[198:201], v[46:49]
	v_mfma_f32_16x16x32_bf16 v[38:41], v[130:133], v[202:205], v[38:41]
	v_mfma_f32_16x16x32_bf16 v[38:41], v[134:137], v[206:209], v[38:41]
	v_mfma_f32_16x16x32_bf16 v[30:33], v[138:141], v[202:205], v[30:33]
	v_mfma_f32_16x16x32_bf16 v[30:33], v[142:145], v[206:209], v[30:33]
	v_mfma_f32_16x16x32_bf16 v[22:25], v[130:133], v[210:213], v[22:25]
	v_mfma_f32_16x16x32_bf16 v[22:25], v[134:137], v[214:217], v[22:25]
	v_mfma_f32_16x16x32_bf16 v[14:17], v[138:141], v[210:213], v[14:17]
	v_mfma_f32_16x16x32_bf16 v[14:17], v[142:145], v[214:217], v[14:17]
	s_setprio 0
	s_setprio 3
	v_mfma_f32_16x16x32_bf16 v[50:53], v[164:167], v[186:189], v[50:53]
	v_mfma_f32_16x16x32_bf16 v[50:53], v[174:177], v[190:193], v[50:53]
	v_mfma_f32_16x16x32_bf16 v[42:45], v[178:181], v[186:189], v[42:45]
	v_mfma_f32_16x16x32_bf16 v[42:45], v[182:185], v[190:193], v[42:45]
	v_mfma_f32_16x16x32_bf16 v[34:37], v[164:167], v[194:197], v[34:37]
	v_mfma_f32_16x16x32_bf16 v[34:37], v[174:177], v[198:201], v[34:37]
	v_mfma_f32_16x16x32_bf16 v[26:29], v[178:181], v[194:197], v[26:29]
	v_mfma_f32_16x16x32_bf16 v[26:29], v[182:185], v[198:201], v[26:29]
	v_mfma_f32_16x16x32_bf16 v[18:21], v[164:167], v[202:205], v[18:21]
	v_mfma_f32_16x16x32_bf16 v[18:21], v[174:177], v[206:209], v[18:21]
	v_mfma_f32_16x16x32_bf16 v[10:13], v[178:181], v[202:205], v[10:13]
	v_mfma_f32_16x16x32_bf16 v[10:13], v[182:185], v[206:209], v[10:13]
	v_mfma_f32_16x16x32_bf16 v[6:9], v[164:167], v[210:213], v[6:9]
	v_mfma_f32_16x16x32_bf16 v[6:9], v[174:177], v[214:217], v[6:9]
	v_mfma_f32_16x16x32_bf16 v[2:5], v[178:181], v[210:213], v[2:5]
	v_mfma_f32_16x16x32_bf16 v[2:5], v[182:185], v[214:217], v[2:5]
	s_setprio 0
	s_barrier
	s_add_i32 s83, 0, 0x18000
	s_add_i32 s84, 0, 0x1c000
	v_add_u32_e32 v142, s83, v168
	v_add_u32_e32 v173, s84, v168
	ds_read_b128 v[130:133], v142
	ds_read_b128 v[134:137], v142 offset:1024
	ds_read_b128 v[138:141], v142 offset:2048
	ds_read_b128 v[142:145], v142 offset:3072
	ds_read_b128 v[164:167], v173
	ds_read_b128 v[174:177], v173 offset:1024
	ds_read_b128 v[178:181], v173 offset:2048
	ds_read_b128 v[182:185], v173 offset:3072
	s_add_u32 s58, s58, 0x80000
	s_addc_u32 s59, s59, 0
	s_mov_b32 m0, s54
	v_lshl_add_u64 v[226:227], s[58:59], 0, v[146:147]
	ds_read_b128 v[186:189], v172 offset:32768
	ds_read_b128 v[190:193], v172 offset:33792
	ds_read_b128 v[194:197], v172 offset:34816
	ds_read_b128 v[198:201], v172 offset:35840
	ds_read_b128 v[202:205], v172 offset:36864
	ds_read_b128 v[206:209], v172 offset:37888
	ds_read_b128 v[210:213], v172 offset:38912
	ds_read_b128 v[214:217], v172 offset:39936
	global_load_lds_dwordx4 v[226:227], off
	v_lshl_add_u64 v[226:227], s[58:59], 0, v[150:151]
	s_mov_b32 m0, s55
	s_nop 0
	global_load_lds_dwordx4 v[226:227], off
	s_waitcnt vmcnt(8)
	s_waitcnt lgkmcnt(0)
	s_barrier
	s_setprio 3
	s_waitcnt lgkmcnt(0)
	v_mfma_f32_16x16x32_bf16 v[126:129], v[130:133], v[186:189], v[126:129]
	v_mfma_f32_16x16x32_bf16 v[126:129], v[134:137], v[190:193], v[126:129]
	v_mfma_f32_16x16x32_bf16 v[122:125], v[138:141], v[186:189], v[122:125]
	v_mfma_f32_16x16x32_bf16 v[122:125], v[142:145], v[190:193], v[122:125]
	v_mfma_f32_16x16x32_bf16 v[118:121], v[130:133], v[194:197], v[118:121]
	v_mfma_f32_16x16x32_bf16 v[118:121], v[134:137], v[198:201], v[118:121]
	v_mfma_f32_16x16x32_bf16 v[114:117], v[138:141], v[194:197], v[114:117]
	v_mfma_f32_16x16x32_bf16 v[114:117], v[142:145], v[198:201], v[114:117]
	v_mfma_f32_16x16x32_bf16 v[110:113], v[130:133], v[202:205], v[110:113]
	v_mfma_f32_16x16x32_bf16 v[110:113], v[134:137], v[206:209], v[110:113]
	v_mfma_f32_16x16x32_bf16 v[102:105], v[138:141], v[202:205], v[102:105]
	v_mfma_f32_16x16x32_bf16 v[102:105], v[142:145], v[206:209], v[102:105]
	v_mfma_f32_16x16x32_bf16 v[78:81], v[130:133], v[210:213], v[78:81]
	v_mfma_f32_16x16x32_bf16 v[78:81], v[134:137], v[214:217], v[78:81]
	v_mfma_f32_16x16x32_bf16 v[74:77], v[138:141], v[210:213], v[74:77]
	v_mfma_f32_16x16x32_bf16 v[74:77], v[142:145], v[214:217], v[74:77]
	s_setprio 0
	s_setprio 3
	v_mfma_f32_16x16x32_bf16 v[106:109], v[164:167], v[186:189], v[106:109]
	v_mfma_f32_16x16x32_bf16 v[106:109], v[174:177], v[190:193], v[106:109]
	v_mfma_f32_16x16x32_bf16 v[98:101], v[178:181], v[186:189], v[98:101]
	v_mfma_f32_16x16x32_bf16 v[98:101], v[182:185], v[190:193], v[98:101]
	v_mfma_f32_16x16x32_bf16 v[94:97], v[164:167], v[194:197], v[94:97]
	v_mfma_f32_16x16x32_bf16 v[94:97], v[174:177], v[198:201], v[94:97]
	v_mfma_f32_16x16x32_bf16 v[90:93], v[178:181], v[194:197], v[90:93]
	v_mfma_f32_16x16x32_bf16 v[90:93], v[182:185], v[198:201], v[90:93]
	v_mfma_f32_16x16x32_bf16 v[86:89], v[164:167], v[202:205], v[86:89]
	v_mfma_f32_16x16x32_bf16 v[86:89], v[174:177], v[206:209], v[86:89]
	v_mfma_f32_16x16x32_bf16 v[82:85], v[178:181], v[202:205], v[82:85]
	v_mfma_f32_16x16x32_bf16 v[82:85], v[182:185], v[206:209], v[82:85]
	v_mfma_f32_16x16x32_bf16 v[70:73], v[164:167], v[210:213], v[70:73]
	v_mfma_f32_16x16x32_bf16 v[70:73], v[174:177], v[214:217], v[70:73]
	v_mfma_f32_16x16x32_bf16 v[66:69], v[178:181], v[210:213], v[66:69]
	v_mfma_f32_16x16x32_bf16 v[66:69], v[182:185], v[214:217], v[66:69]
	s_setprio 0
	s_barrier
; #define PG8_STAGE(bufoff, gbase, voff) do { _Pragma("unroll") for (int _i = 0; _i < 2; ++_i) \
;         __builtin_amdgcn_global_load_lds((const unsigned*)((const char*)(gbase) + (voff)[_i]), (PG8_LAS unsigned*)(lds + (bufoff) + ldsw + _i * 8192), 16, 0, 0); } while (0)
; #define PG8_LDA(dst, b, h) do { _Pragma("unroll") for (int m = 0; m < 4; ++m) _Pragma("unroll") for (int k = 0; k < 2; ++k) dst[m][k] = *(const PG8_LAS bf16x8*)(lds + PG8_SA(b, h) + aoff + m * 2048 + k * 1024); } while (0)
; #define PG8_MMA(ai, bj, At, Bt) do { __builtin_amdgcn_s_setprio(3); _Pragma("unroll") for (int m = 0; m < 4; ++m) _Pragma("unroll") for (int n = 0; n < 2; ++n) _Pragma("unroll") for (int k = 0; k < 2; ++k) \
;         acc[ai][bj][m][n] = __builtin_amdgcn_mfma_f32_16x16x32_bf16(Bt[n][k], At[m][k], acc[ai][bj][m][n], 0, 0, 0); __builtin_amdgcn_s_setprio(0); } while (0)
; #define PG8_WAIT_V(n) asm volatile("s_waitcnt vmcnt(" #n ")" ::: "memory")
; #define PG8_WAIT_L(n) asm volatile("s_waitcnt lgkmcnt(" #n ")" ::: "memory")
; #define PG8_BAR __builtin_amdgcn_s_barrier()
; #define PG8_SCHED __builtin_amdgcn_sched_barrier(0)
; template <class Epi, class Sched, bool ALIGN_EPI = false, bool SP2 = false>
; __device__ __forceinline__ void gemm_phase(PG8_LAS unsigned char* lds, const Gemm g, const Sched& S, const Epi& E) {
;     ...
;             PG8_LDA(At, 1, 1); PG8_STAGE(PG8_SB(1, 0), b3, voffB); PG8_STAGE(PG8_SB(1, 1), b3 + hstepB, voffB); PG8_STAGE(PG8_SA(1, 0), a3, voffA);
;             PG8_WAIT_V(8); PG8_WAIT_L(0); PG8_BAR; PG8_MMA(1, 0, At, B0); PG8_MMA(1, 1, At, B1); PG8_BAR; PG8_SCHED;
;     ...
;         if constexpr (ALIGN_EPI) { if (wr == 0) PG8_BAR; }
	s_add_i32 s58, s83, s44
	v_lshl_add_u64 v[218:219], v[218:219], 0, s[18:19]
	s_mov_b32 m0, s58
	ds_read_b128 v[186:189], v172 offset:49152
	ds_read_b128 v[190:193], v172 offset:50176
	ds_read_b128 v[194:197], v172 offset:51200
	ds_read_b128 v[198:201], v172 offset:52224
	ds_read_b128 v[202:205], v172 offset:53248
	ds_read_b128 v[206:209], v172 offset:54272
	ds_read_b128 v[210:213], v172 offset:55296
	ds_read_b128 v[214:217], v172 offset:56320
	global_load_lds_dwordx4 v[218:219], off
	s_add_i32 m0, s58, 0x2000
	s_add_u32 s36, s36, 0x20080
	v_lshl_add_u64 v[218:219], v[220:221], 0, s[18:19]
	s_addc_u32 s37, s37, 0
	s_add_i32 s58, s84, s44
	global_load_lds_dwordx4 v[218:219], off
	v_lshl_add_u64 v[218:219], s[36:37], 0, v[148:149]
	s_mov_b32 m0, s58
	s_nop 0
	global_load_lds_dwordx4 v[218:219], off
	v_lshl_add_u64 v[218:219], s[36:37], 0, v[152:153]
	s_add_i32 m0, s58, 0x2000
	s_nop 0
	global_load_lds_dwordx4 v[218:219], off
	v_lshl_add_u64 v[218:219], v[222:223], 0, s[18:19]
	s_mov_b32 m0, s63
	s_nop 0
	global_load_lds_dwordx4 v[218:219], off
	v_lshl_add_u64 v[218:219], v[224:225], 0, s[18:19]
	s_mov_b32 m0, s66
	s_nop 0
	global_load_lds_dwordx4 v[218:219], off
	s_waitcnt vmcnt(8)
	s_waitcnt lgkmcnt(0)
	s_barrier
	s_setprio 3
	s_waitcnt lgkmcnt(0)
	v_mfma_f32_16x16x32_bf16 v[62:65], v[130:133], v[186:189], v[62:65]
	v_mfma_f32_16x16x32_bf16 v[62:65], v[134:137], v[190:193], v[62:65]
	v_mfma_f32_16x16x32_bf16 v[58:61], v[138:141], v[186:189], v[58:61]
	v_mfma_f32_16x16x32_bf16 v[58:61], v[142:145], v[190:193], v[58:61]
	v_mfma_f32_16x16x32_bf16 v[54:57], v[130:133], v[194:197], v[54:57]
	v_mfma_f32_16x16x32_bf16 v[54:57], v[134:137], v[198:201], v[54:57]
	v_mfma_f32_16x16x32_bf16 v[46:49], v[138:141], v[194:197], v[46:49]
	v_mfma_f32_16x16x32_bf16 v[46:49], v[142:145], v[198:201], v[46:49]
	v_mfma_f32_16x16x32_bf16 v[38:41], v[130:133], v[202:205], v[38:41]
	v_mfma_f32_16x16x32_bf16 v[38:41], v[134:137], v[206:209], v[38:41]
	v_mfma_f32_16x16x32_bf16 v[30:33], v[138:141], v[202:205], v[30:33]
	v_mfma_f32_16x16x32_bf16 v[30:33], v[142:145], v[206:209], v[30:33]
	v_mfma_f32_16x16x32_bf16 v[22:25], v[130:133], v[210:213], v[22:25]
	v_mfma_f32_16x16x32_bf16 v[22:25], v[134:137], v[214:217], v[22:25]
	v_mfma_f32_16x16x32_bf16 v[14:17], v[138:141], v[210:213], v[14:17]
	v_mfma_f32_16x16x32_bf16 v[14:17], v[142:145], v[214:217], v[14:17]
	s_setprio 0
	s_setprio 3
	v_mfma_f32_16x16x32_bf16 v[50:53], v[164:167], v[186:189], v[50:53]
	v_mfma_f32_16x16x32_bf16 v[50:53], v[174:177], v[190:193], v[50:53]
	v_mfma_f32_16x16x32_bf16 v[42:45], v[178:181], v[186:189], v[42:45]
	v_mfma_f32_16x16x32_bf16 v[42:45], v[182:185], v[190:193], v[42:45]
	v_mfma_f32_16x16x32_bf16 v[34:37], v[164:167], v[194:197], v[34:37]
	v_mfma_f32_16x16x32_bf16 v[34:37], v[174:177], v[198:201], v[34:37]
	v_mfma_f32_16x16x32_bf16 v[26:29], v[178:181], v[194:197], v[26:29]
	v_mfma_f32_16x16x32_bf16 v[26:29], v[182:185], v[198:201], v[26:29]
	v_mfma_f32_16x16x32_bf16 v[18:21], v[164:167], v[202:205], v[18:21]
	v_mfma_f32_16x16x32_bf16 v[18:21], v[174:177], v[206:209], v[18:21]
	v_mfma_f32_16x16x32_bf16 v[10:13], v[178:181], v[202:205], v[10:13]
	v_mfma_f32_16x16x32_bf16 v[10:13], v[182:185], v[206:209], v[10:13]
	v_mfma_f32_16x16x32_bf16 v[6:9], v[164:167], v[210:213], v[6:9]
	v_mfma_f32_16x16x32_bf16 v[6:9], v[174:177], v[214:217], v[6:9]
	v_mfma_f32_16x16x32_bf16 v[2:5], v[178:181], v[210:213], v[2:5]
	v_mfma_f32_16x16x32_bf16 v[2:5], v[182:185], v[214:217], v[2:5]
	s_setprio 0
	s_barrier
	s_add_i32 s79, s79, 2
	s_add_u32 s6, s6, 0x100
	s_addc_u32 s7, s7, 0
	s_add_u32 s77, s77, 0x100
	s_addc_u32 s78, s78, 0
	s_cmp_gt_u32 s79, 5
	s_cbranch_scc0 .LBB0_478
	s_and_b64 vcc, exec, s[20:21]
	s_cbranch_vccz .LBB0_481
	s_barrier

; #define PG8_STAGE(bufoff, gbase, voff) do { _Pragma("unroll") for (int _i = 0; _i < 2; ++_i) \
;         __builtin_amdgcn_global_load_lds((const unsigned*)((const char*)(gbase) + (voff)[_i]), (PG8_LAS unsigned*)(lds + (bufoff) + ldsw + _i * 8192), 16, 0, 0); } while (0)
; #define PG8_LDA(dst, b, h) do { _Pragma("unroll") for (int m = 0; m < 4; ++m) _Pragma("unroll") for (int k = 0; k < 2; ++k) dst[m][k] = *(const PG8_LAS bf16x8*)(lds + PG8_SA(b, h) + aoff + m * 2048 + k * 1024); } while (0)
; #define PG8_LDB(dst, b, h) do { _Pragma("unroll") for (int n = 0; n < 2; ++n) _Pragma("unroll") for (int k = 0; k < 2; ++k) dst[n][k] = *(const PG8_LAS bf16x8*)(lds + PG8_SB(b, h) + boff + n * 2048 + k * 1024); } while (0)
; #define PG8_MMA(ai, bj, At, Bt) do { __builtin_amdgcn_s_setprio(3); _Pragma("unroll") for (int m = 0; m < 4; ++m) _Pragma("unroll") for (int n = 0; n < 2; ++n) _Pragma("unroll") for (int k = 0; k < 2; ++k) \
;         acc[ai][bj][m][n] = __builtin_amdgcn_mfma_f32_16x16x32_bf16(Bt[n][k], At[m][k], acc[ai][bj][m][n], 0, 0, 0); __builtin_amdgcn_s_setprio(0); } while (0)
; #define PG8_WAIT_V(n) asm volatile("s_waitcnt vmcnt(" #n ")" ::: "memory")
; #define PG8_WAIT_L(n) asm volatile("s_waitcnt lgkmcnt(" #n ")" ::: "memory")
; template <class Epi, class Sched, bool ALIGN_EPI = false, bool SP2 = false>
; __device__ __forceinline__ void gemm_phase(PG8_LAS unsigned char* lds, const Gemm g, const Sched& S, const Epi& E) {
;     ...
;         for (int t = 0; t < nt; t += 2) {
;             const bool last = (t == nt - 2);
;             const char* a1 = cA + (size_t)(t + 1) * kstep;
;             const char* a2 = last ? nA : cA + (size_t)(t + 2) * kstep; const char* b2 = last ? nB : cB + (size_t)(t + 2) * kstep;
;             const char* a3 = a2 + kstep; const char* b3 = b2 + kstep;
;             if (last && has_next) S.a_ready(nxt);
;             if constexpr (Epi::MIDK) { if (t == E.midk_step(nt)) E.midk(acc, cur, wr, wc, fr, fq); }
;             if constexpr (SP2) {
;             PG8_LDB(B0, 0, 0); PG8_LDB(B1, 0, 1); PG8_SCHED; PG8_LDA(At, 0, 0); PG8_STAGE(PG8_SA(1, 1), a1 + hstepA, voffA);
;             PG8_WAIT_V(8); PG8_WAIT_L(0); PG8_BAR; PG8_MMA(0, 0, At, B0); PG8_MMA(0, 1, At, B1); PG8_BAR; PG8_SCHED;
;             PG8_LDA(At, 0, 1); PG8_STAGE(PG8_SB(0, 0), b2, voffB); PG8_STAGE(PG8_SB(0, 1), b2 + hstepB, voffB); PG8_STAGE(PG8_SA(0, 0), a2, voffA);
.LBB0_727:
	v_add_u32_e32 v160, s66, v157
	ds_read_b128 v[130:133], v160
	ds_read_b128 v[164:167], v160 offset:1024
	ds_read_b128 v[168:171], v160 offset:2048
	ds_read_b128 v[172:175], v160 offset:3072
	v_add_u32_e32 v160, s67, v157
	s_add_u32 s0, s28, s30
	ds_read_b128 v[176:179], v160
	ds_read_b128 v[180:183], v160 offset:1024
	ds_read_b128 v[184:187], v160 offset:2048
	ds_read_b128 v[188:191], v160 offset:3072
	s_addc_u32 s1, s29, s31
	s_add_u32 s0, s0, 0x100
	s_addc_u32 s1, s1, 0
	s_add_u32 s84, s79, s30
	s_addc_u32 s85, s81, s31
	s_cmpk_eq_i32 s30, 0x1f00
	s_cselect_b32 s37, s23, s1
	s_cselect_b32 s36, s72, s0
	s_cselect_b32 s1, s75, s85
	s_cselect_b32 s0, s76, s84
	v_lshl_add_u64 v[160:161], v[150:151], 0, s[30:31]
	s_add_i32 m0, s44, 0xc000
	ds_read_b128 v[192:195], v159
	ds_read_b128 v[196:199], v159 offset:1024
	ds_read_b128 v[200:203], v159 offset:2048
	ds_read_b128 v[204:207], v159 offset:3072
	ds_read_b128 v[208:211], v159 offset:4096
	ds_read_b128 v[212:215], v159 offset:5120
	ds_read_b128 v[216:219], v159 offset:6144
	ds_read_b128 v[220:223], v159 offset:7168
	global_load_lds_dwordx4 v[160:161], off
	v_lshl_add_u64 v[160:161], v[152:153], 0, s[30:31]
	s_add_i32 m0, s44, 0xe000
	s_nop 0
	global_load_lds_dwordx4 v[160:161], off
	s_waitcnt vmcnt(8)
	s_waitcnt lgkmcnt(0)
	s_barrier
	s_setprio 3
	s_waitcnt lgkmcnt(0)
	v_mfma_f32_16x16x32_bf16 v[126:129], v[130:133], v[192:195], v[126:129]
	v_mfma_f32_16x16x32_bf16 v[126:129], v[164:167], v[196:199], v[126:129]
	v_mfma_f32_16x16x32_bf16 v[122:125], v[168:171], v[192:195], v[122:125]
	v_mfma_f32_16x16x32_bf16 v[122:125], v[172:175], v[196:199], v[122:125]
	v_mfma_f32_16x16x32_bf16 v[110:113], v[130:133], v[200:203], v[110:113]
	v_mfma_f32_16x16x32_bf16 v[110:113], v[164:167], v[204:207], v[110:113]
	v_mfma_f32_16x16x32_bf16 v[106:109], v[168:171], v[200:203], v[106:109]
	v_mfma_f32_16x16x32_bf16 v[106:109], v[172:175], v[204:207], v[106:109]
	v_mfma_f32_16x16x32_bf16 v[94:97], v[130:133], v[208:211], v[94:97]
	v_mfma_f32_16x16x32_bf16 v[94:97], v[164:167], v[212:215], v[94:97]
	v_mfma_f32_16x16x32_bf16 v[90:93], v[168:171], v[208:211], v[90:93]
	v_mfma_f32_16x16x32_bf16 v[90:93], v[172:175], v[212:215], v[90:93]
	v_mfma_f32_16x16x32_bf16 v[78:81], v[130:133], v[216:219], v[78:81]
	v_mfma_f32_16x16x32_bf16 v[78:81], v[164:167], v[220:223], v[78:81]
	v_mfma_f32_16x16x32_bf16 v[74:77], v[168:171], v[216:219], v[74:77]
	v_mfma_f32_16x16x32_bf16 v[74:77], v[172:175], v[220:223], v[74:77]
	s_setprio 0
	s_setprio 3
	v_mfma_f32_16x16x32_bf16 v[118:121], v[176:179], v[192:195], v[118:121]
	v_mfma_f32_16x16x32_bf16 v[118:121], v[180:183], v[196:199], v[118:121]
	v_mfma_f32_16x16x32_bf16 v[114:117], v[184:187], v[192:195], v[114:117]
	v_mfma_f32_16x16x32_bf16 v[114:117], v[188:191], v[196:199], v[114:117]
	v_mfma_f32_16x16x32_bf16 v[102:105], v[176:179], v[200:203], v[102:105]
	v_mfma_f32_16x16x32_bf16 v[102:105], v[180:183], v[204:207], v[102:105]
	v_mfma_f32_16x16x32_bf16 v[98:101], v[184:187], v[200:203], v[98:101]
	v_mfma_f32_16x16x32_bf16 v[98:101], v[188:191], v[204:207], v[98:101]
	v_mfma_f32_16x16x32_bf16 v[86:89], v[176:179], v[208:211], v[86:89]
	v_mfma_f32_16x16x32_bf16 v[86:89], v[180:183], v[212:215], v[86:89]
	v_mfma_f32_16x16x32_bf16 v[82:85], v[184:187], v[208:211], v[82:85]
	v_mfma_f32_16x16x32_bf16 v[82:85], v[188:191], v[212:215], v[82:85]
	v_mfma_f32_16x16x32_bf16 v[70:73], v[176:179], v[216:219], v[70:73]
	v_mfma_f32_16x16x32_bf16 v[70:73], v[180:183], v[220:223], v[70:73]
	v_mfma_f32_16x16x32_bf16 v[66:69], v[184:187], v[216:219], v[66:69]
	v_mfma_f32_16x16x32_bf16 v[66:69], v[188:191], v[220:223], v[66:69]
	s_setprio 0
	s_barrier
	s_add_i32 s84, s66, s33
	v_lshl_add_u64 v[160:161], s[0:1], 0, v[136:137]
	s_mov_b32 m0, s84
	ds_read_b128 v[192:195], v159 offset:16384
	ds_read_b128 v[196:199], v159 offset:17408
	ds_read_b128 v[200:203], v159 offset:18432
	ds_read_b128 v[204:207], v159 offset:19456
	ds_read_b128 v[208:211], v159 offset:20480
	ds_read_b128 v[212:215], v159 offset:21504
	ds_read_b128 v[216:219], v159 offset:22528
	ds_read_b128 v[220:223], v159 offset:23552
	global_load_lds_dwordx4 v[160:161], off
	s_add_i32 m0, s84, 0x2000
	s_add_u32 s84, s0, 0x100000
	v_lshl_add_u64 v[224:225], s[0:1], 0, v[140:141]
	s_addc_u32 s85, s1, 0
	s_add_i32 s86, s67, s33
	global_load_lds_dwordx4 v[224:225], off
	v_lshl_add_u64 v[226:227], s[84:85], 0, v[136:137]
	s_mov_b32 m0, s86
	v_lshl_add_u64 v[228:229], s[36:37], 0, v[138:139]
	global_load_lds_dwordx4 v[226:227], off
	v_lshl_add_u64 v[226:227], s[84:85], 0, v[140:141]
	s_add_i32 m0, s86, 0x2000
	s_nop 0
	global_load_lds_dwordx4 v[226:227], off
	v_lshl_add_u64 v[226:227], s[36:37], 0, v[134:135]
	s_mov_b32 m0, s44
	s_nop 0
	global_load_lds_dwordx4 v[226:227], off
	s_mov_b32 m0, s45
	s_nop 0
	global_load_lds_dwordx4 v[228:229], off
	s_waitcnt vmcnt(8)
	s_waitcnt lgkmcnt(0)
	s_barrier
; #define PG8_STAGE(bufoff, gbase, voff) do { _Pragma("unroll") for (int _i = 0; _i < 2; ++_i) \
;         __builtin_amdgcn_global_load_lds((const unsigned*)((const char*)(gbase) + (voff)[_i]), (PG8_LAS unsigned*)(lds + (bufoff) + ldsw + _i * 8192), 16, 0, 0); } while (0)
; #define PG8_LDA(dst, b, h) do { _Pragma("unroll") for (int m = 0; m < 4; ++m) _Pragma("unroll") for (int k = 0; k < 2; ++k) dst[m][k] = *(const PG8_LAS bf16x8*)(lds + PG8_SA(b, h) + aoff + m * 2048 + k * 1024); } while (0)
; #define PG8_LDB(dst, b, h) do { _Pragma("unroll") for (int n = 0; n < 2; ++n) _Pragma("unroll") for (int k = 0; k < 2; ++k) dst[n][k] = *(const PG8_LAS bf16x8*)(lds + PG8_SB(b, h) + boff + n * 2048 + k * 1024); } while (0)
; #define PG8_MMA(ai, bj, At, Bt) do { __builtin_amdgcn_s_setprio(3); _Pragma("unroll") for (int m = 0; m < 4; ++m) _Pragma("unroll") for (int n = 0; n < 2; ++n) _Pragma("unroll") for (int k = 0; k < 2; ++k) \
;         acc[ai][bj][m][n] = __builtin_amdgcn_mfma_f32_16x16x32_bf16(Bt[n][k], At[m][k], acc[ai][bj][m][n], 0, 0, 0); __builtin_amdgcn_s_setprio(0); } while (0)
; #define PG8_WAIT_V(n) asm volatile("s_waitcnt vmcnt(" #n ")" ::: "memory")
; #define PG8_WAIT_L(n) asm volatile("s_waitcnt lgkmcnt(" #n ")" ::: "memory")
; #define PG8_BAR __builtin_amdgcn_s_barrier()
; #define PG8_SCHED __builtin_amdgcn_sched_barrier(0)
; template <class Epi, class Sched, bool ALIGN_EPI = false, bool SP2 = false>
; __device__ __forceinline__ void gemm_phase(PG8_LAS unsigned char* lds, const Gemm g, const Sched& S, const Epi& E) {
;     ...
;             PG8_WAIT_V(8); PG8_WAIT_L(0); PG8_BAR; PG8_MMA(1, 0, At, B0); PG8_MMA(1, 1, At, B1); PG8_BAR; PG8_SCHED;
;             PG8_LDB(B0, 1, 0); PG8_LDB(B1, 1, 1); PG8_SCHED; PG8_LDA(At, 1, 0); PG8_STAGE(PG8_SA(0, 1), a2 + hstepA, voffA);
;             PG8_WAIT_V(8); PG8_WAIT_L(0); PG8_BAR; PG8_MMA(0, 0, At, B0); PG8_MMA(0, 1, At, B1); PG8_BAR; PG8_SCHED;
	s_setprio 3
	s_waitcnt lgkmcnt(0)
	v_mfma_f32_16x16x32_bf16 v[62:65], v[130:133], v[192:195], v[62:65]
	v_mfma_f32_16x16x32_bf16 v[62:65], v[164:167], v[196:199], v[62:65]
	v_mfma_f32_16x16x32_bf16 v[58:61], v[168:171], v[192:195], v[58:61]
	v_mfma_f32_16x16x32_bf16 v[58:61], v[172:175], v[196:199], v[58:61]
	v_mfma_f32_16x16x32_bf16 v[46:49], v[130:133], v[200:203], v[46:49]
	v_mfma_f32_16x16x32_bf16 v[46:49], v[164:167], v[204:207], v[46:49]
	v_mfma_f32_16x16x32_bf16 v[42:45], v[168:171], v[200:203], v[42:45]
	v_mfma_f32_16x16x32_bf16 v[42:45], v[172:175], v[204:207], v[42:45]
	v_mfma_f32_16x16x32_bf16 v[30:33], v[130:133], v[208:211], v[30:33]
	v_mfma_f32_16x16x32_bf16 v[30:33], v[164:167], v[212:215], v[30:33]
	v_mfma_f32_16x16x32_bf16 v[26:29], v[168:171], v[208:211], v[26:29]
	v_mfma_f32_16x16x32_bf16 v[26:29], v[172:175], v[212:215], v[26:29]
	v_mfma_f32_16x16x32_bf16 v[14:17], v[130:133], v[216:219], v[14:17]
	v_mfma_f32_16x16x32_bf16 v[14:17], v[164:167], v[220:223], v[14:17]
	v_mfma_f32_16x16x32_bf16 v[10:13], v[168:171], v[216:219], v[10:13]
	v_mfma_f32_16x16x32_bf16 v[10:13], v[172:175], v[220:223], v[10:13]
	s_setprio 0
	s_setprio 3
	v_mfma_f32_16x16x32_bf16 v[54:57], v[176:179], v[192:195], v[54:57]
	v_mfma_f32_16x16x32_bf16 v[54:57], v[180:183], v[196:199], v[54:57]
	v_mfma_f32_16x16x32_bf16 v[50:53], v[184:187], v[192:195], v[50:53]
	v_mfma_f32_16x16x32_bf16 v[50:53], v[188:191], v[196:199], v[50:53]
	v_mfma_f32_16x16x32_bf16 v[38:41], v[176:179], v[200:203], v[38:41]
	v_mfma_f32_16x16x32_bf16 v[38:41], v[180:183], v[204:207], v[38:41]
	v_mfma_f32_16x16x32_bf16 v[34:37], v[184:187], v[200:203], v[34:37]
	v_mfma_f32_16x16x32_bf16 v[34:37], v[188:191], v[204:207], v[34:37]
	v_mfma_f32_16x16x32_bf16 v[22:25], v[176:179], v[208:211], v[22:25]
	v_mfma_f32_16x16x32_bf16 v[22:25], v[180:183], v[212:215], v[22:25]
	v_mfma_f32_16x16x32_bf16 v[18:21], v[184:187], v[208:211], v[18:21]
	v_mfma_f32_16x16x32_bf16 v[18:21], v[188:191], v[212:215], v[18:21]
	v_mfma_f32_16x16x32_bf16 v[6:9], v[176:179], v[216:219], v[6:9]
	v_mfma_f32_16x16x32_bf16 v[6:9], v[180:183], v[220:223], v[6:9]
	v_mfma_f32_16x16x32_bf16 v[2:5], v[184:187], v[216:219], v[2:5]
	v_mfma_f32_16x16x32_bf16 v[2:5], v[188:191], v[220:223], v[2:5]
	s_setprio 0
	s_barrier
	s_add_i32 s84, 0, 0x18000
	v_add_u32_e32 v163, s84, v157
	s_add_i32 s85, 0, 0x1c000
	ds_read_b128 v[130:133], v163
	ds_read_b128 v[164:167], v163 offset:1024
	ds_read_b128 v[168:171], v163 offset:2048
	ds_read_b128 v[172:175], v163 offset:3072
	v_add_u32_e32 v163, s85, v157
	ds_read_b128 v[176:179], v163
	ds_read_b128 v[180:183], v163 offset:1024
	ds_read_b128 v[184:187], v163 offset:2048
	ds_read_b128 v[188:191], v163 offset:3072
	s_add_u32 s36, s36, 0x100000
	s_addc_u32 s37, s37, 0
	s_mov_b32 m0, s54
	v_lshl_add_u64 v[230:231], s[36:37], 0, v[134:135]
	ds_read_b128 v[192:195], v159 offset:32768
	ds_read_b128 v[196:199], v159 offset:33792
	ds_read_b128 v[200:203], v159 offset:34816
	ds_read_b128 v[204:207], v159 offset:35840
	ds_read_b128 v[208:211], v159 offset:36864
	ds_read_b128 v[212:215], v159 offset:37888
	ds_read_b128 v[216:219], v159 offset:38912
	ds_read_b128 v[220:223], v159 offset:39936
	global_load_lds_dwordx4 v[230:231], off
	v_lshl_add_u64 v[230:231], s[36:37], 0, v[138:139]
	s_mov_b32 m0, s55
	s_nop 0
	global_load_lds_dwordx4 v[230:231], off
	s_waitcnt vmcnt(8)
	s_waitcnt lgkmcnt(0)
	s_barrier
	s_setprio 3
	s_waitcnt lgkmcnt(0)
	v_mfma_f32_16x16x32_bf16 v[126:129], v[130:133], v[192:195], v[126:129]
	v_mfma_f32_16x16x32_bf16 v[126:129], v[164:167], v[196:199], v[126:129]
	v_mfma_f32_16x16x32_bf16 v[122:125], v[168:171], v[192:195], v[122:125]
	v_mfma_f32_16x16x32_bf16 v[122:125], v[172:175], v[196:199], v[122:125]
	v_mfma_f32_16x16x32_bf16 v[110:113], v[130:133], v[200:203], v[110:113]
	v_mfma_f32_16x16x32_bf16 v[110:113], v[164:167], v[204:207], v[110:113]
	v_mfma_f32_16x16x32_bf16 v[106:109], v[168:171], v[200:203], v[106:109]
	v_mfma_f32_16x16x32_bf16 v[106:109], v[172:175], v[204:207], v[106:109]
	v_mfma_f32_16x16x32_bf16 v[94:97], v[130:133], v[208:211], v[94:97]
	v_mfma_f32_16x16x32_bf16 v[94:97], v[164:167], v[212:215], v[94:97]
	v_mfma_f32_16x16x32_bf16 v[90:93], v[168:171], v[208:211], v[90:93]
	v_mfma_f32_16x16x32_bf16 v[90:93], v[172:175], v[212:215], v[90:93]
	v_mfma_f32_16x16x32_bf16 v[78:81], v[130:133], v[216:219], v[78:81]
	v_mfma_f32_16x16x32_bf16 v[78:81], v[164:167], v[220:223], v[78:81]
	v_mfma_f32_16x16x32_bf16 v[74:77], v[168:171], v[216:219], v[74:77]
	v_mfma_f32_16x16x32_bf16 v[74:77], v[172:175], v[220:223], v[74:77]
	s_setprio 0
	s_setprio 3
	v_mfma_f32_16x16x32_bf16 v[118:121], v[176:179], v[192:195], v[118:121]
	v_mfma_f32_16x16x32_bf16 v[118:121], v[180:183], v[196:199], v[118:121]
	v_mfma_f32_16x16x32_bf16 v[114:117], v[184:187], v[192:195], v[114:117]
	v_mfma_f32_16x16x32_bf16 v[114:117], v[188:191], v[196:199], v[114:117]
	v_mfma_f32_16x16x32_bf16 v[102:105], v[176:179], v[200:203], v[102:105]
	v_mfma_f32_16x16x32_bf16 v[102:105], v[180:183], v[204:207], v[102:105]
	v_mfma_f32_16x16x32_bf16 v[98:101], v[184:187], v[200:203], v[98:101]
	v_mfma_f32_16x16x32_bf16 v[98:101], v[188:191], v[204:207], v[98:101]
	v_mfma_f32_16x16x32_bf16 v[86:89], v[176:179], v[208:211], v[86:89]
	v_mfma_f32_16x16x32_bf16 v[86:89], v[180:183], v[212:215], v[86:89]
	v_mfma_f32_16x16x32_bf16 v[82:85], v[184:187], v[208:211], v[82:85]
	v_mfma_f32_16x16x32_bf16 v[82:85], v[188:191], v[212:215], v[82:85]
	v_mfma_f32_16x16x32_bf16 v[70:73], v[176:179], v[216:219], v[70:73]
	v_mfma_f32_16x16x32_bf16 v[70:73], v[180:183], v[220:223], v[70:73]
	v_mfma_f32_16x16x32_bf16 v[66:69], v[184:187], v[216:219], v[66:69]
	v_mfma_f32_16x16x32_bf16 v[66:69], v[188:191], v[220:223], v[66:69]
	s_setprio 0
	s_barrier
; #define PG8_STAGE(bufoff, gbase, voff) do { _Pragma("unroll") for (int _i = 0; _i < 2; ++_i) \
;         __builtin_amdgcn_global_load_lds((const unsigned*)((const char*)(gbase) + (voff)[_i]), (PG8_LAS unsigned*)(lds + (bufoff) + ldsw + _i * 8192), 16, 0, 0); } while (0)
; #define PG8_LDA(dst, b, h) do { _Pragma("unroll") for (int m = 0; m < 4; ++m) _Pragma("unroll") for (int k = 0; k < 2; ++k) dst[m][k] = *(const PG8_LAS bf16x8*)(lds + PG8_SA(b, h) + aoff + m * 2048 + k * 1024); } while (0)
; #define PG8_MMA(ai, bj, At, Bt) do { __builtin_amdgcn_s_setprio(3); _Pragma("unroll") for (int m = 0; m < 4; ++m) _Pragma("unroll") for (int n = 0; n < 2; ++n) _Pragma("unroll") for (int k = 0; k < 2; ++k) \
;         acc[ai][bj][m][n] = __builtin_amdgcn_mfma_f32_16x16x32_bf16(Bt[n][k], At[m][k], acc[ai][bj][m][n], 0, 0, 0); __builtin_amdgcn_s_setprio(0); } while (0)
; #define PG8_WAIT_V(n) asm volatile("s_waitcnt vmcnt(" #n ")" ::: "memory")
; #define PG8_WAIT_L(n) asm volatile("s_waitcnt lgkmcnt(" #n ")" ::: "memory")
; #define PG8_BAR __builtin_amdgcn_s_barrier()
; #define PG8_SCHED __builtin_amdgcn_sched_barrier(0)
; template <class Epi, class Sched, bool ALIGN_EPI = false, bool SP2 = false>
; __device__ __forceinline__ void gemm_phase(PG8_LAS unsigned char* lds, const Gemm g, const Sched& S, const Epi& E) {
;     ...
;             PG8_LDA(At, 1, 1); PG8_STAGE(PG8_SB(1, 0), b3, voffB); PG8_STAGE(PG8_SB(1, 1), b3 + hstepB, voffB); PG8_STAGE(PG8_SA(1, 0), a3, voffA);
;             PG8_WAIT_V(8); PG8_WAIT_L(0); PG8_BAR; PG8_MMA(1, 0, At, B0); PG8_MMA(1, 1, At, B1); PG8_BAR; PG8_SCHED;
	s_add_i32 s36, s84, s33
	v_lshl_add_u64 v[160:161], v[160:161], 0, s[10:11]
	s_mov_b32 m0, s36
	ds_read_b128 v[192:195], v159 offset:49152
	ds_read_b128 v[196:199], v159 offset:50176
	ds_read_b128 v[200:203], v159 offset:51200
	ds_read_b128 v[204:207], v159 offset:52224
	ds_read_b128 v[208:211], v159 offset:53248
	ds_read_b128 v[212:215], v159 offset:54272
	ds_read_b128 v[216:219], v159 offset:55296
	ds_read_b128 v[220:223], v159 offset:56320
	global_load_lds_dwordx4 v[160:161], off
	s_add_i32 m0, s36, 0x2000
	s_add_u32 s0, s0, 0x100080
	v_lshl_add_u64 v[160:161], v[224:225], 0, s[10:11]
	s_addc_u32 s1, s1, 0
	s_add_i32 s36, s85, s33
	global_load_lds_dwordx4 v[160:161], off
	v_lshl_add_u64 v[160:161], s[0:1], 0, v[136:137]
	s_mov_b32 m0, s36
	s_nop 0
	global_load_lds_dwordx4 v[160:161], off
	v_lshl_add_u64 v[160:161], s[0:1], 0, v[140:141]
	s_add_i32 m0, s36, 0x2000
	s_nop 0
	global_load_lds_dwordx4 v[160:161], off
	v_lshl_add_u64 v[160:161], v[226:227], 0, s[10:11]
	s_mov_b32 m0, s61
	s_nop 0
	global_load_lds_dwordx4 v[160:161], off
	v_lshl_add_u64 v[160:161], v[228:229], 0, s[10:11]
	s_mov_b32 m0, s62
	s_nop 0
	global_load_lds_dwordx4 v[160:161], off
	s_waitcnt vmcnt(8)
	s_waitcnt lgkmcnt(0)
	s_barrier
	s_setprio 3
	s_waitcnt lgkmcnt(0)
	v_mfma_f32_16x16x32_bf16 v[62:65], v[130:133], v[192:195], v[62:65]
	v_mfma_f32_16x16x32_bf16 v[62:65], v[164:167], v[196:199], v[62:65]
	v_mfma_f32_16x16x32_bf16 v[58:61], v[168:171], v[192:195], v[58:61]
	v_mfma_f32_16x16x32_bf16 v[58:61], v[172:175], v[196:199], v[58:61]
	v_mfma_f32_16x16x32_bf16 v[46:49], v[130:133], v[200:203], v[46:49]
	v_mfma_f32_16x16x32_bf16 v[46:49], v[164:167], v[204:207], v[46:49]
	v_mfma_f32_16x16x32_bf16 v[42:45], v[168:171], v[200:203], v[42:45]
	v_mfma_f32_16x16x32_bf16 v[42:45], v[172:175], v[204:207], v[42:45]
	v_mfma_f32_16x16x32_bf16 v[30:33], v[130:133], v[208:211], v[30:33]
	v_mfma_f32_16x16x32_bf16 v[30:33], v[164:167], v[212:215], v[30:33]
	v_mfma_f32_16x16x32_bf16 v[26:29], v[168:171], v[208:211], v[26:29]
	v_mfma_f32_16x16x32_bf16 v[26:29], v[172:175], v[212:215], v[26:29]
	v_mfma_f32_16x16x32_bf16 v[14:17], v[130:133], v[216:219], v[14:17]
	v_mfma_f32_16x16x32_bf16 v[14:17], v[164:167], v[220:223], v[14:17]
	v_mfma_f32_16x16x32_bf16 v[10:13], v[168:171], v[216:219], v[10:13]
	v_mfma_f32_16x16x32_bf16 v[10:13], v[172:175], v[220:223], v[10:13]
	s_setprio 0
	s_setprio 3
	v_mfma_f32_16x16x32_bf16 v[54:57], v[176:179], v[192:195], v[54:57]
	v_mfma_f32_16x16x32_bf16 v[54:57], v[180:183], v[196:199], v[54:57]
	v_mfma_f32_16x16x32_bf16 v[50:53], v[184:187], v[192:195], v[50:53]
	v_mfma_f32_16x16x32_bf16 v[50:53], v[188:191], v[196:199], v[50:53]
	v_mfma_f32_16x16x32_bf16 v[38:41], v[176:179], v[200:203], v[38:41]
	v_mfma_f32_16x16x32_bf16 v[38:41], v[180:183], v[204:207], v[38:41]
	v_mfma_f32_16x16x32_bf16 v[34:37], v[184:187], v[200:203], v[34:37]
	v_mfma_f32_16x16x32_bf16 v[34:37], v[188:191], v[204:207], v[34:37]
	v_mfma_f32_16x16x32_bf16 v[22:25], v[176:179], v[208:211], v[22:25]
	v_mfma_f32_16x16x32_bf16 v[22:25], v[180:183], v[212:215], v[22:25]
	v_mfma_f32_16x16x32_bf16 v[18:21], v[184:187], v[208:211], v[18:21]
	v_mfma_f32_16x16x32_bf16 v[18:21], v[188:191], v[212:215], v[18:21]
	v_mfma_f32_16x16x32_bf16 v[6:9], v[176:179], v[216:219], v[6:9]
	v_mfma_f32_16x16x32_bf16 v[6:9], v[180:183], v[220:223], v[6:9]
	v_mfma_f32_16x16x32_bf16 v[2:5], v[184:187], v[216:219], v[2:5]
	v_mfma_f32_16x16x32_bf16 v[2:5], v[188:191], v[220:223], v[2:5]
	s_setprio 0
	s_barrier
	s_add_i32 s83, s83, 2
	s_add_u32 s30, s30, 0x100
	s_addc_u32 s31, s31, 0
	s_cmp_gt_u32 s83, 61
	s_cbranch_scc1 .LBB0_730

; #define PG8_STAGE(bufoff, gbase, voff) do { _Pragma("unroll") for (int _i = 0; _i < 2; ++_i) \
;         __builtin_amdgcn_global_load_lds((const unsigned*)((const char*)(gbase) + (voff)[_i]), (PG8_LAS unsigned*)(lds + (bufoff) + ldsw + _i * 8192), 16, 0, 0); } while (0)
; #define PG8_LDA(dst, b, h) do { _Pragma("unroll") for (int m = 0; m < 4; ++m) _Pragma("unroll") for (int k = 0; k < 2; ++k) dst[m][k] = *(const PG8_LAS bf16x8*)(lds + PG8_SA(b, h) + aoff + m * 2048 + k * 1024); } while (0)
; #define PG8_LDB(dst, b, h) do { _Pragma("unroll") for (int n = 0; n < 2; ++n) _Pragma("unroll") for (int k = 0; k < 2; ++k) dst[n][k] = *(const PG8_LAS bf16x8*)(lds + PG8_SB(b, h) + boff + n * 2048 + k * 1024); } while (0)
; #define PG8_MMA(ai, bj, At, Bt) do { __builtin_amdgcn_s_setprio(3); _Pragma("unroll") for (int m = 0; m < 4; ++m) _Pragma("unroll") for (int n = 0; n < 2; ++n) _Pragma("unroll") for (int k = 0; k < 2; ++k) \
;         acc[ai][bj][m][n] = __builtin_amdgcn_mfma_f32_16x16x32_bf16(Bt[n][k], At[m][k], acc[ai][bj][m][n], 0, 0, 0); __builtin_amdgcn_s_setprio(0); } while (0)
; #define PG8_WAIT_V(n) asm volatile("s_waitcnt vmcnt(" #n ")" ::: "memory")
; #define PG8_WAIT_L(n) asm volatile("s_waitcnt lgkmcnt(" #n ")" ::: "memory")
; #define PG8_BAR __builtin_amdgcn_s_barrier()
; #define PG8_SCHED __builtin_amdgcn_sched_barrier(0)
; template <class Epi, class Sched, bool ALIGN_EPI = false, bool SP2 = false>
; __device__ __forceinline__ void gemm_phase(PG8_LAS unsigned char* lds, const Gemm g, const Sched& S, const Epi& E) {
;     ...
;             const char* a1 = cA + (size_t)(t + 1) * kstep;
;             const char* a2 = last ? nA : cA + (size_t)(t + 2) * kstep; const char* b2 = last ? nB : cB + (size_t)(t + 2) * kstep;
;             const char* a3 = a2 + kstep; const char* b3 = b2 + kstep;
;             if (last && has_next) S.a_ready(nxt);
;             if constexpr (Epi::MIDK) { if (t == E.midk_step(nt)) E.midk(acc, cur, wr, wc, fr, fq); }
;             if constexpr (SP2) {
;             PG8_LDB(B0, 0, 0); PG8_LDB(B1, 0, 1); PG8_SCHED; PG8_LDA(At, 0, 0); PG8_STAGE(PG8_SA(1, 1), a1 + hstepA, voffA);
;             PG8_WAIT_V(8); PG8_WAIT_L(0); PG8_BAR; PG8_MMA(0, 0, At, B0); PG8_MMA(0, 1, At, B1); PG8_BAR; PG8_SCHED;
;             PG8_LDA(At, 0, 1); PG8_STAGE(PG8_SB(0, 0), b2, voffB); PG8_STAGE(PG8_SB(0, 1), b2 + hstepB, voffB); PG8_STAGE(PG8_SA(0, 0), a2, voffA);
.LBB0_808:
	v_add_u32_e32 v3, s65, v186
	ds_read_b128 v[134:137], v3
	ds_read_b128 v[138:141], v3 offset:1024
	ds_read_b128 v[142:145], v3 offset:2048
	ds_read_b128 v[146:149], v3 offset:3072
	v_add_u32_e32 v3, s66, v186
	s_add_u32 s36, s28, s30
	ds_read_b128 v[150:153], v3
	ds_read_b128 v[154:157], v3 offset:1024
	ds_read_b128 v[158:161], v3 offset:2048
	ds_read_b128 v[190:193], v3 offset:3072
	s_addc_u32 s37, s29, s31
	s_add_u32 s36, s36, 0x100
	s_addc_u32 s37, s37, 0
	s_add_u32 s86, s83, s30
	s_addc_u32 s87, s84, s31
	s_cmpk_eq_i32 s30, 0x1f00
	s_cselect_b32 s41, s23, s37
	s_cselect_b32 s40, s75, s36
	s_cselect_b32 s37, s77, s87
	s_cselect_b32 s36, s78, s86
	v_lshl_add_u64 v[4:5], v[180:181], 0, s[30:31]
	s_add_i32 m0, s42, 0xc000
	ds_read_b128 v[194:197], v188
	ds_read_b128 v[198:201], v188 offset:1024
	ds_read_b128 v[202:205], v188 offset:2048
	ds_read_b128 v[206:209], v188 offset:3072
	ds_read_b128 v[210:213], v188 offset:4096
	ds_read_b128 v[214:217], v188 offset:5120
	ds_read_b128 v[218:221], v188 offset:6144
	ds_read_b128 v[222:225], v188 offset:7168
	global_load_lds_dwordx4 v[4:5], off
	v_lshl_add_u64 v[4:5], v[182:183], 0, s[30:31]
	s_add_i32 m0, s42, 0xe000
	s_nop 0
	global_load_lds_dwordx4 v[4:5], off
	s_waitcnt vmcnt(8)
	s_waitcnt lgkmcnt(0)
	s_barrier
	s_setprio 3
	s_waitcnt lgkmcnt(0)
	v_mfma_f32_16x16x32_bf16 v[130:133], v[134:137], v[194:197], v[130:133]
	v_mfma_f32_16x16x32_bf16 v[130:133], v[138:141], v[198:201], v[130:133]
	v_mfma_f32_16x16x32_bf16 v[126:129], v[142:145], v[194:197], v[126:129]
	v_mfma_f32_16x16x32_bf16 v[126:129], v[146:149], v[198:201], v[126:129]
	v_mfma_f32_16x16x32_bf16 v[114:117], v[134:137], v[202:205], v[114:117]
	v_mfma_f32_16x16x32_bf16 v[114:117], v[138:141], v[206:209], v[114:117]
	v_mfma_f32_16x16x32_bf16 v[110:113], v[142:145], v[202:205], v[110:113]
	v_mfma_f32_16x16x32_bf16 v[110:113], v[146:149], v[206:209], v[110:113]
	v_mfma_f32_16x16x32_bf16 v[98:101], v[134:137], v[210:213], v[98:101]
	v_mfma_f32_16x16x32_bf16 v[98:101], v[138:141], v[214:217], v[98:101]
	v_mfma_f32_16x16x32_bf16 v[94:97], v[142:145], v[210:213], v[94:97]
	v_mfma_f32_16x16x32_bf16 v[94:97], v[146:149], v[214:217], v[94:97]
	v_mfma_f32_16x16x32_bf16 v[82:85], v[134:137], v[218:221], v[82:85]
	v_mfma_f32_16x16x32_bf16 v[82:85], v[138:141], v[222:225], v[82:85]
	v_mfma_f32_16x16x32_bf16 v[78:81], v[142:145], v[218:221], v[78:81]
	v_mfma_f32_16x16x32_bf16 v[78:81], v[146:149], v[222:225], v[78:81]
	s_setprio 0
	s_setprio 3
	v_mfma_f32_16x16x32_bf16 v[122:125], v[150:153], v[194:197], v[122:125]
	v_mfma_f32_16x16x32_bf16 v[122:125], v[154:157], v[198:201], v[122:125]
	v_mfma_f32_16x16x32_bf16 v[118:121], v[158:161], v[194:197], v[118:121]
	v_mfma_f32_16x16x32_bf16 v[118:121], v[190:193], v[198:201], v[118:121]
	v_mfma_f32_16x16x32_bf16 v[106:109], v[150:153], v[202:205], v[106:109]
	v_mfma_f32_16x16x32_bf16 v[106:109], v[154:157], v[206:209], v[106:109]
	v_mfma_f32_16x16x32_bf16 v[102:105], v[158:161], v[202:205], v[102:105]
	v_mfma_f32_16x16x32_bf16 v[102:105], v[190:193], v[206:209], v[102:105]
	v_mfma_f32_16x16x32_bf16 v[90:93], v[150:153], v[210:213], v[90:93]
	v_mfma_f32_16x16x32_bf16 v[90:93], v[154:157], v[214:217], v[90:93]
	v_mfma_f32_16x16x32_bf16 v[86:89], v[158:161], v[210:213], v[86:89]
	v_mfma_f32_16x16x32_bf16 v[86:89], v[190:193], v[214:217], v[86:89]
	v_mfma_f32_16x16x32_bf16 v[74:77], v[150:153], v[218:221], v[74:77]
	v_mfma_f32_16x16x32_bf16 v[74:77], v[154:157], v[222:225], v[74:77]
	v_mfma_f32_16x16x32_bf16 v[70:73], v[158:161], v[218:221], v[70:73]
	v_mfma_f32_16x16x32_bf16 v[70:73], v[190:193], v[222:225], v[70:73]
	s_setprio 0
	s_barrier
	s_add_i32 s86, s65, s33
	v_lshl_add_u64 v[226:227], s[36:37], 0, v[166:167]
	s_mov_b32 m0, s86
	ds_read_b128 v[194:197], v188 offset:16384
	ds_read_b128 v[198:201], v188 offset:17408
	ds_read_b128 v[202:205], v188 offset:18432
	ds_read_b128 v[206:209], v188 offset:19456
	ds_read_b128 v[210:213], v188 offset:20480
	ds_read_b128 v[214:217], v188 offset:21504
	ds_read_b128 v[218:221], v188 offset:22528
	ds_read_b128 v[222:225], v188 offset:23552
	global_load_lds_dwordx4 v[226:227], off
	s_add_i32 m0, s86, 0x2000
	s_add_u32 s86, s36, 0x100000
	v_lshl_add_u64 v[228:229], s[36:37], 0, v[170:171]
	s_addc_u32 s87, s37, 0
	s_add_i32 s88, s66, s33
	global_load_lds_dwordx4 v[228:229], off
	v_lshl_add_u64 v[4:5], s[86:87], 0, v[166:167]
	s_mov_b32 m0, s88
	v_lshl_add_u64 v[230:231], s[40:41], 0, v[164:165]
	global_load_lds_dwordx4 v[4:5], off
	v_lshl_add_u64 v[4:5], s[86:87], 0, v[170:171]
	s_add_i32 m0, s88, 0x2000
	v_lshl_add_u64 v[232:233], s[40:41], 0, v[168:169]
	global_load_lds_dwordx4 v[4:5], off
	s_mov_b32 m0, s42
	s_nop 0
	global_load_lds_dwordx4 v[230:231], off
	s_mov_b32 m0, s43
	s_nop 0
	global_load_lds_dwordx4 v[232:233], off
	s_waitcnt vmcnt(8)
	s_waitcnt lgkmcnt(0)
	s_barrier
; #define PG8_STAGE(bufoff, gbase, voff) do { _Pragma("unroll") for (int _i = 0; _i < 2; ++_i) \
;         __builtin_amdgcn_global_load_lds((const unsigned*)((const char*)(gbase) + (voff)[_i]), (PG8_LAS unsigned*)(lds + (bufoff) + ldsw + _i * 8192), 16, 0, 0); } while (0)
; #define PG8_LDA(dst, b, h) do { _Pragma("unroll") for (int m = 0; m < 4; ++m) _Pragma("unroll") for (int k = 0; k < 2; ++k) dst[m][k] = *(const PG8_LAS bf16x8*)(lds + PG8_SA(b, h) + aoff + m * 2048 + k * 1024); } while (0)
; #define PG8_LDB(dst, b, h) do { _Pragma("unroll") for (int n = 0; n < 2; ++n) _Pragma("unroll") for (int k = 0; k < 2; ++k) dst[n][k] = *(const PG8_LAS bf16x8*)(lds + PG8_SB(b, h) + boff + n * 2048 + k * 1024); } while (0)
; #define PG8_MMA(ai, bj, At, Bt) do { __builtin_amdgcn_s_setprio(3); _Pragma("unroll") for (int m = 0; m < 4; ++m) _Pragma("unroll") for (int n = 0; n < 2; ++n) _Pragma("unroll") for (int k = 0; k < 2; ++k) \
;         acc[ai][bj][m][n] = __builtin_amdgcn_mfma_f32_16x16x32_bf16(Bt[n][k], At[m][k], acc[ai][bj][m][n], 0, 0, 0); __builtin_amdgcn_s_setprio(0); } while (0)
; #define PG8_WAIT_V(n) asm volatile("s_waitcnt vmcnt(" #n ")" ::: "memory")
; #define PG8_WAIT_L(n) asm volatile("s_waitcnt lgkmcnt(" #n ")" ::: "memory")
; #define PG8_BAR __builtin_amdgcn_s_barrier()
; #define PG8_SCHED __builtin_amdgcn_sched_barrier(0)
; template <class Epi, class Sched, bool ALIGN_EPI = false, bool SP2 = false>
; __device__ __forceinline__ void gemm_phase(PG8_LAS unsigned char* lds, const Gemm g, const Sched& S, const Epi& E) {
;     ...
;             PG8_WAIT_V(8); PG8_WAIT_L(0); PG8_BAR; PG8_MMA(1, 0, At, B0); PG8_MMA(1, 1, At, B1); PG8_BAR; PG8_SCHED;
;             PG8_LDB(B0, 1, 0); PG8_LDB(B1, 1, 1); PG8_SCHED; PG8_LDA(At, 1, 0); PG8_STAGE(PG8_SA(0, 1), a2 + hstepA, voffA);
;             PG8_WAIT_V(8); PG8_WAIT_L(0); PG8_BAR; PG8_MMA(0, 0, At, B0); PG8_MMA(0, 1, At, B1); PG8_BAR; PG8_SCHED;
	s_setprio 3
	s_waitcnt lgkmcnt(0)
	v_mfma_f32_16x16x32_bf16 v[66:69], v[134:137], v[194:197], v[66:69]
	v_mfma_f32_16x16x32_bf16 v[66:69], v[138:141], v[198:201], v[66:69]
	v_mfma_f32_16x16x32_bf16 v[62:65], v[142:145], v[194:197], v[62:65]
	v_mfma_f32_16x16x32_bf16 v[62:65], v[146:149], v[198:201], v[62:65]
	v_mfma_f32_16x16x32_bf16 v[50:53], v[134:137], v[202:205], v[50:53]
	v_mfma_f32_16x16x32_bf16 v[50:53], v[138:141], v[206:209], v[50:53]
	v_mfma_f32_16x16x32_bf16 v[46:49], v[142:145], v[202:205], v[46:49]
	v_mfma_f32_16x16x32_bf16 v[46:49], v[146:149], v[206:209], v[46:49]
	v_mfma_f32_16x16x32_bf16 v[34:37], v[134:137], v[210:213], v[34:37]
	v_mfma_f32_16x16x32_bf16 v[34:37], v[138:141], v[214:217], v[34:37]
	v_mfma_f32_16x16x32_bf16 v[30:33], v[142:145], v[210:213], v[30:33]
	v_mfma_f32_16x16x32_bf16 v[30:33], v[146:149], v[214:217], v[30:33]
	v_mfma_f32_16x16x32_bf16 v[18:21], v[134:137], v[218:221], v[18:21]
	v_mfma_f32_16x16x32_bf16 v[18:21], v[138:141], v[222:225], v[18:21]
	v_mfma_f32_16x16x32_bf16 v[14:17], v[142:145], v[218:221], v[14:17]
	v_mfma_f32_16x16x32_bf16 v[14:17], v[146:149], v[222:225], v[14:17]
	s_setprio 0
	s_setprio 3
	v_mfma_f32_16x16x32_bf16 v[58:61], v[150:153], v[194:197], v[58:61]
	v_mfma_f32_16x16x32_bf16 v[58:61], v[154:157], v[198:201], v[58:61]
	v_mfma_f32_16x16x32_bf16 v[54:57], v[158:161], v[194:197], v[54:57]
	v_mfma_f32_16x16x32_bf16 v[54:57], v[190:193], v[198:201], v[54:57]
	v_mfma_f32_16x16x32_bf16 v[42:45], v[150:153], v[202:205], v[42:45]
	v_mfma_f32_16x16x32_bf16 v[42:45], v[154:157], v[206:209], v[42:45]
	v_mfma_f32_16x16x32_bf16 v[38:41], v[158:161], v[202:205], v[38:41]
	v_mfma_f32_16x16x32_bf16 v[38:41], v[190:193], v[206:209], v[38:41]
	v_mfma_f32_16x16x32_bf16 v[26:29], v[150:153], v[210:213], v[26:29]
	v_mfma_f32_16x16x32_bf16 v[26:29], v[154:157], v[214:217], v[26:29]
	v_mfma_f32_16x16x32_bf16 v[22:25], v[158:161], v[210:213], v[22:25]
	v_mfma_f32_16x16x32_bf16 v[22:25], v[190:193], v[214:217], v[22:25]
	v_mfma_f32_16x16x32_bf16 v[10:13], v[150:153], v[218:221], v[10:13]
	v_mfma_f32_16x16x32_bf16 v[10:13], v[154:157], v[222:225], v[10:13]
	v_mfma_f32_16x16x32_bf16 v[4:7], v[158:161], v[218:221], v[6:9]
	v_mfma_f32_16x16x32_bf16 v[4:7], v[190:193], v[222:225], v[4:7]
	s_setprio 0
	s_barrier
	s_add_i32 s86, 0, 0x18000
	v_add_u32_e32 v3, s86, v186
	s_add_i32 s87, 0, 0x1c000
	ds_read_b128 v[134:137], v3
	ds_read_b128 v[138:141], v3 offset:1024
	ds_read_b128 v[142:145], v3 offset:2048
	ds_read_b128 v[146:149], v3 offset:3072
	v_add_u32_e32 v3, s87, v186
	ds_read_b128 v[150:153], v3
	ds_read_b128 v[154:157], v3 offset:1024
	ds_read_b128 v[158:161], v3 offset:2048
	ds_read_b128 v[190:193], v3 offset:3072
	s_add_u32 s40, s40, 0x100000
	s_addc_u32 s41, s41, 0
	s_mov_b32 m0, s44
	v_lshl_add_u64 v[8:9], s[40:41], 0, v[164:165]
	ds_read_b128 v[194:197], v188 offset:32768
	ds_read_b128 v[198:201], v188 offset:33792
	ds_read_b128 v[202:205], v188 offset:34816
	ds_read_b128 v[206:209], v188 offset:35840
	ds_read_b128 v[210:213], v188 offset:36864
	ds_read_b128 v[214:217], v188 offset:37888
	ds_read_b128 v[218:221], v188 offset:38912
	ds_read_b128 v[222:225], v188 offset:39936
	global_load_lds_dwordx4 v[8:9], off
	v_lshl_add_u64 v[8:9], s[40:41], 0, v[168:169]
	s_mov_b32 m0, s45
	s_nop 0
	global_load_lds_dwordx4 v[8:9], off
	s_waitcnt vmcnt(8)
	s_waitcnt lgkmcnt(0)
	s_barrier
	s_setprio 3
	s_waitcnt lgkmcnt(0)
	v_mfma_f32_16x16x32_bf16 v[130:133], v[134:137], v[194:197], v[130:133]
	v_mfma_f32_16x16x32_bf16 v[130:133], v[138:141], v[198:201], v[130:133]
	v_mfma_f32_16x16x32_bf16 v[126:129], v[142:145], v[194:197], v[126:129]
	v_mfma_f32_16x16x32_bf16 v[126:129], v[146:149], v[198:201], v[126:129]
	v_mfma_f32_16x16x32_bf16 v[114:117], v[134:137], v[202:205], v[114:117]
	v_mfma_f32_16x16x32_bf16 v[114:117], v[138:141], v[206:209], v[114:117]
	v_mfma_f32_16x16x32_bf16 v[110:113], v[142:145], v[202:205], v[110:113]
	v_mfma_f32_16x16x32_bf16 v[110:113], v[146:149], v[206:209], v[110:113]
	v_mfma_f32_16x16x32_bf16 v[98:101], v[134:137], v[210:213], v[98:101]
	v_mfma_f32_16x16x32_bf16 v[98:101], v[138:141], v[214:217], v[98:101]
	v_mfma_f32_16x16x32_bf16 v[94:97], v[142:145], v[210:213], v[94:97]
	v_mfma_f32_16x16x32_bf16 v[94:97], v[146:149], v[214:217], v[94:97]
	v_mfma_f32_16x16x32_bf16 v[82:85], v[134:137], v[218:221], v[82:85]
	v_mfma_f32_16x16x32_bf16 v[82:85], v[138:141], v[222:225], v[82:85]
	v_mfma_f32_16x16x32_bf16 v[78:81], v[142:145], v[218:221], v[78:81]
	v_mfma_f32_16x16x32_bf16 v[78:81], v[146:149], v[222:225], v[78:81]
	s_setprio 0
	s_setprio 3
	v_mfma_f32_16x16x32_bf16 v[122:125], v[150:153], v[194:197], v[122:125]
	v_mfma_f32_16x16x32_bf16 v[122:125], v[154:157], v[198:201], v[122:125]
	v_mfma_f32_16x16x32_bf16 v[118:121], v[158:161], v[194:197], v[118:121]
	v_mfma_f32_16x16x32_bf16 v[118:121], v[190:193], v[198:201], v[118:121]
	v_mfma_f32_16x16x32_bf16 v[106:109], v[150:153], v[202:205], v[106:109]
	v_mfma_f32_16x16x32_bf16 v[106:109], v[154:157], v[206:209], v[106:109]
	v_mfma_f32_16x16x32_bf16 v[102:105], v[158:161], v[202:205], v[102:105]
	v_mfma_f32_16x16x32_bf16 v[102:105], v[190:193], v[206:209], v[102:105]
	v_mfma_f32_16x16x32_bf16 v[90:93], v[150:153], v[210:213], v[90:93]
	v_mfma_f32_16x16x32_bf16 v[90:93], v[154:157], v[214:217], v[90:93]
	v_mfma_f32_16x16x32_bf16 v[86:89], v[158:161], v[210:213], v[86:89]
	v_mfma_f32_16x16x32_bf16 v[86:89], v[190:193], v[214:217], v[86:89]
	v_mfma_f32_16x16x32_bf16 v[74:77], v[150:153], v[218:221], v[74:77]
	v_mfma_f32_16x16x32_bf16 v[74:77], v[154:157], v[222:225], v[74:77]
	v_mfma_f32_16x16x32_bf16 v[70:73], v[158:161], v[218:221], v[70:73]
	v_mfma_f32_16x16x32_bf16 v[70:73], v[190:193], v[222:225], v[70:73]
	s_setprio 0
	s_barrier
; #define PG8_STAGE(bufoff, gbase, voff) do { _Pragma("unroll") for (int _i = 0; _i < 2; ++_i) \
;         __builtin_amdgcn_global_load_lds((const unsigned*)((const char*)(gbase) + (voff)[_i]), (PG8_LAS unsigned*)(lds + (bufoff) + ldsw + _i * 8192), 16, 0, 0); } while (0)
; #define PG8_LDA(dst, b, h) do { _Pragma("unroll") for (int m = 0; m < 4; ++m) _Pragma("unroll") for (int k = 0; k < 2; ++k) dst[m][k] = *(const PG8_LAS bf16x8*)(lds + PG8_SA(b, h) + aoff + m * 2048 + k * 1024); } while (0)
; #define PG8_MMA(ai, bj, At, Bt) do { __builtin_amdgcn_s_setprio(3); _Pragma("unroll") for (int m = 0; m < 4; ++m) _Pragma("unroll") for (int n = 0; n < 2; ++n) _Pragma("unroll") for (int k = 0; k < 2; ++k) \
;         acc[ai][bj][m][n] = __builtin_amdgcn_mfma_f32_16x16x32_bf16(Bt[n][k], At[m][k], acc[ai][bj][m][n], 0, 0, 0); __builtin_amdgcn_s_setprio(0); } while (0)
; #define PG8_WAIT_V(n) asm volatile("s_waitcnt vmcnt(" #n ")" ::: "memory")
; #define PG8_WAIT_L(n) asm volatile("s_waitcnt lgkmcnt(" #n ")" ::: "memory")
; #define PG8_BAR __builtin_amdgcn_s_barrier()
; #define PG8_SCHED __builtin_amdgcn_sched_barrier(0)
; template <class Epi, class Sched, bool ALIGN_EPI = false, bool SP2 = false>
; __device__ __forceinline__ void gemm_phase(PG8_LAS unsigned char* lds, const Gemm g, const Sched& S, const Epi& E) {
;     ...
;             PG8_LDA(At, 1, 1); PG8_STAGE(PG8_SB(1, 0), b3, voffB); PG8_STAGE(PG8_SB(1, 1), b3 + hstepB, voffB); PG8_STAGE(PG8_SA(1, 0), a3, voffA);
;             PG8_WAIT_V(8); PG8_WAIT_L(0); PG8_BAR; PG8_MMA(1, 0, At, B0); PG8_MMA(1, 1, At, B1); PG8_BAR; PG8_SCHED;
	s_add_i32 s40, s86, s33
	v_lshl_add_u64 v[8:9], v[226:227], 0, s[10:11]
	s_mov_b32 m0, s40
	ds_read_b128 v[194:197], v188 offset:49152
	ds_read_b128 v[198:201], v188 offset:50176
	ds_read_b128 v[202:205], v188 offset:51200
	ds_read_b128 v[206:209], v188 offset:52224
	ds_read_b128 v[210:213], v188 offset:53248
	ds_read_b128 v[214:217], v188 offset:54272
	ds_read_b128 v[218:221], v188 offset:55296
	ds_read_b128 v[222:225], v188 offset:56320
	global_load_lds_dwordx4 v[8:9], off
	s_add_i32 m0, s40, 0x2000
	s_add_u32 s36, s36, 0x100080
	v_lshl_add_u64 v[8:9], v[228:229], 0, s[10:11]
	s_addc_u32 s37, s37, 0
	s_add_i32 s40, s87, s33
	global_load_lds_dwordx4 v[8:9], off
	v_lshl_add_u64 v[8:9], s[36:37], 0, v[166:167]
	s_mov_b32 m0, s40
	s_nop 0
	global_load_lds_dwordx4 v[8:9], off
	v_lshl_add_u64 v[8:9], s[36:37], 0, v[170:171]
	s_add_i32 m0, s40, 0x2000
	s_nop 0
	global_load_lds_dwordx4 v[8:9], off
	v_lshl_add_u64 v[8:9], v[230:231], 0, s[10:11]
	s_mov_b32 m0, s60
	s_nop 0
	global_load_lds_dwordx4 v[8:9], off
	v_lshl_add_u64 v[8:9], v[232:233], 0, s[10:11]
	s_mov_b32 m0, s61
	s_nop 0
	global_load_lds_dwordx4 v[8:9], off
	s_waitcnt vmcnt(8)
	s_waitcnt lgkmcnt(0)
	s_barrier
	s_setprio 3
	s_waitcnt lgkmcnt(0)
	v_mfma_f32_16x16x32_bf16 v[66:69], v[134:137], v[194:197], v[66:69]
	v_mfma_f32_16x16x32_bf16 v[66:69], v[138:141], v[198:201], v[66:69]
	v_mfma_f32_16x16x32_bf16 v[62:65], v[142:145], v[194:197], v[62:65]
	v_mfma_f32_16x16x32_bf16 v[62:65], v[146:149], v[198:201], v[62:65]
	v_mfma_f32_16x16x32_bf16 v[50:53], v[134:137], v[202:205], v[50:53]
	v_mfma_f32_16x16x32_bf16 v[50:53], v[138:141], v[206:209], v[50:53]
	v_mfma_f32_16x16x32_bf16 v[46:49], v[142:145], v[202:205], v[46:49]
	v_mfma_f32_16x16x32_bf16 v[46:49], v[146:149], v[206:209], v[46:49]
	v_mfma_f32_16x16x32_bf16 v[34:37], v[134:137], v[210:213], v[34:37]
	v_mfma_f32_16x16x32_bf16 v[34:37], v[138:141], v[214:217], v[34:37]
	v_mfma_f32_16x16x32_bf16 v[30:33], v[142:145], v[210:213], v[30:33]
	v_mfma_f32_16x16x32_bf16 v[30:33], v[146:149], v[214:217], v[30:33]
	v_mfma_f32_16x16x32_bf16 v[18:21], v[134:137], v[218:221], v[18:21]
	v_mfma_f32_16x16x32_bf16 v[18:21], v[138:141], v[222:225], v[18:21]
	v_mfma_f32_16x16x32_bf16 v[14:17], v[142:145], v[218:221], v[14:17]
	v_mfma_f32_16x16x32_bf16 v[14:17], v[146:149], v[222:225], v[14:17]
	s_setprio 0
	s_setprio 3
	v_mfma_f32_16x16x32_bf16 v[58:61], v[150:153], v[194:197], v[58:61]
	v_mfma_f32_16x16x32_bf16 v[54:57], v[158:161], v[194:197], v[54:57]
	v_mfma_f32_16x16x32_bf16 v[42:45], v[150:153], v[202:205], v[42:45]
	v_mfma_f32_16x16x32_bf16 v[38:41], v[158:161], v[202:205], v[38:41]
	v_mfma_f32_16x16x32_bf16 v[26:29], v[150:153], v[210:213], v[26:29]
	v_mfma_f32_16x16x32_bf16 v[22:25], v[158:161], v[210:213], v[22:25]
	v_mfma_f32_16x16x32_bf16 v[8:11], v[150:153], v[218:221], v[10:13]
	v_mfma_f32_16x16x32_bf16 v[4:7], v[158:161], v[218:221], v[4:7]
	v_mfma_f32_16x16x32_bf16 v[58:61], v[154:157], v[198:201], v[58:61]
	v_mfma_f32_16x16x32_bf16 v[54:57], v[190:193], v[198:201], v[54:57]
	v_mfma_f32_16x16x32_bf16 v[42:45], v[154:157], v[206:209], v[42:45]
	v_mfma_f32_16x16x32_bf16 v[38:41], v[190:193], v[206:209], v[38:41]
	v_mfma_f32_16x16x32_bf16 v[26:29], v[154:157], v[214:217], v[26:29]
	v_mfma_f32_16x16x32_bf16 v[22:25], v[190:193], v[214:217], v[22:25]
	v_mfma_f32_16x16x32_bf16 v[10:13], v[154:157], v[222:225], v[8:11]
	v_mfma_f32_16x16x32_bf16 v[6:9], v[190:193], v[222:225], v[4:7]
	s_setprio 0
	s_barrier
	s_add_i32 s85, s85, 2
	s_add_u32 s30, s30, 0x100
	s_addc_u32 s31, s31, 0
	s_cmp_gt_u32 s85, 61
	s_cbranch_scc1 .LBB0_811

; #define PG8_STAGE(bufoff, gbase, voff) do { _Pragma("unroll") for (int _i = 0; _i < 2; ++_i) \
;         __builtin_amdgcn_global_load_lds((const unsigned*)((const char*)(gbase) + (voff)[_i]), (PG8_LAS unsigned*)(lds + (bufoff) + ldsw + _i * 8192), 16, 0, 0); } while (0)
; #define PG8_LDA(dst, b, h) do { _Pragma("unroll") for (int m = 0; m < 4; ++m) _Pragma("unroll") for (int k = 0; k < 2; ++k) dst[m][k] = *(const PG8_LAS bf16x8*)(lds + PG8_SA(b, h) + aoff + m * 2048 + k * 1024); } while (0)
; #define PG8_LDB(dst, b, h) do { _Pragma("unroll") for (int n = 0; n < 2; ++n) _Pragma("unroll") for (int k = 0; k < 2; ++k) dst[n][k] = *(const PG8_LAS bf16x8*)(lds + PG8_SB(b, h) + boff + n * 2048 + k * 1024); } while (0)
; #define PG8_MMA(ai, bj, At, Bt) do { __builtin_amdgcn_s_setprio(3); _Pragma("unroll") for (int m = 0; m < 4; ++m) _Pragma("unroll") for (int n = 0; n < 2; ++n) _Pragma("unroll") for (int k = 0; k < 2; ++k) \
;         acc[ai][bj][m][n] = __builtin_amdgcn_mfma_f32_16x16x32_bf16(Bt[n][k], At[m][k], acc[ai][bj][m][n], 0, 0, 0); __builtin_amdgcn_s_setprio(0); } while (0)
; #define PG8_WAIT_V(n) asm volatile("s_waitcnt vmcnt(" #n ")" ::: "memory")
; #define PG8_WAIT_L(n) asm volatile("s_waitcnt lgkmcnt(" #n ")" ::: "memory")
; #define PG8_BAR __builtin_amdgcn_s_barrier()
; #define PG8_SCHED __builtin_amdgcn_sched_barrier(0)
; template <class Epi, class Sched, bool ALIGN_EPI = false, bool SP2 = false>
; __device__ __forceinline__ void gemm_phase(PG8_LAS unsigned char* lds, const Gemm g, const Sched& S, const Epi& E) {
;     ...
;             const char* a1 = cA + (size_t)(t + 1) * kstep;
;             const char* a2 = last ? nA : cA + (size_t)(t + 2) * kstep; const char* b2 = last ? nB : cB + (size_t)(t + 2) * kstep;
;             const char* a3 = a2 + kstep; const char* b3 = b2 + kstep;
;             if (last && has_next) S.a_ready(nxt);
;             if constexpr (Epi::MIDK) { if (t == E.midk_step(nt)) E.midk(acc, cur, wr, wc, fr, fq); }
;             if constexpr (SP2) {
;             PG8_LDB(B0, 0, 0); PG8_LDB(B1, 0, 1); PG8_SCHED; PG8_LDA(At, 0, 0); PG8_STAGE(PG8_SA(1, 1), a1 + hstepA, voffA);
;             PG8_WAIT_V(8); PG8_WAIT_L(0); PG8_BAR; PG8_MMA(0, 0, At, B0); PG8_MMA(0, 1, At, B1); PG8_BAR; PG8_SCHED;
;             PG8_LDA(At, 0, 1); PG8_STAGE(PG8_SB(0, 0), b2, voffB); PG8_STAGE(PG8_SB(0, 1), b2 + hstepB, voffB); PG8_STAGE(PG8_SA(0, 0), a2, voffA);
.LBB0_908:
	ds_read_b128 v[158:161], v155
	ds_read_b128 v[164:167], v155 offset:1024
	ds_read_b128 v[168:171], v155 offset:2048
	ds_read_b128 v[172:175], v155 offset:3072
	ds_read_b128 v[176:179], v156
	ds_read_b128 v[180:183], v156 offset:1024
	ds_read_b128 v[184:187], v156 offset:2048
	ds_read_b128 v[188:191], v156 offset:3072
	s_add_u32 s26, s24, 0xfff00080
	s_addc_u32 s27, s25, -1
	s_cmp_eq_u32 s55, 60
	s_cselect_b32 s29, s17, s27
	s_cselect_b32 s28, s47, s26
	s_cselect_b32 s27, s15, s54
	s_cselect_b32 s26, s52, s53
	v_lshl_add_u64 v[146:147], s[24:25], 0, v[138:139]
	s_add_i32 m0, s23, 0xc000
	ds_read_b128 v[192:195], v157
	ds_read_b128 v[196:199], v157 offset:1024
	ds_read_b128 v[200:203], v157 offset:2048
	ds_read_b128 v[204:207], v157 offset:3072
	ds_read_b128 v[208:211], v157 offset:4096
	ds_read_b128 v[212:215], v157 offset:5120
	ds_read_b128 v[216:219], v157 offset:6144
	ds_read_b128 v[220:223], v157 offset:7168
	global_load_lds_dwordx4 v[146:147], off
	v_lshl_add_u64 v[146:147], s[24:25], 0, v[140:141]
	s_add_i32 m0, s23, 0xe000
	s_nop 0
	global_load_lds_dwordx4 v[146:147], off
	s_waitcnt vmcnt(8)
	s_waitcnt lgkmcnt(0)
	s_barrier
	s_setprio 3
	s_waitcnt lgkmcnt(0)
	v_mfma_f32_16x16x32_bf16 v[126:129], v[158:161], v[192:195], v[126:129]
	v_mfma_f32_16x16x32_bf16 v[126:129], v[164:167], v[196:199], v[126:129]
	v_mfma_f32_16x16x32_bf16 v[122:125], v[168:171], v[192:195], v[122:125]
	v_mfma_f32_16x16x32_bf16 v[122:125], v[172:175], v[196:199], v[122:125]
	v_mfma_f32_16x16x32_bf16 v[114:117], v[158:161], v[200:203], v[114:117]
	v_mfma_f32_16x16x32_bf16 v[114:117], v[164:167], v[204:207], v[114:117]
	v_mfma_f32_16x16x32_bf16 v[106:109], v[168:171], v[200:203], v[106:109]
	v_mfma_f32_16x16x32_bf16 v[106:109], v[172:175], v[204:207], v[106:109]
	v_mfma_f32_16x16x32_bf16 v[98:101], v[158:161], v[208:211], v[98:101]
	v_mfma_f32_16x16x32_bf16 v[98:101], v[164:167], v[212:215], v[98:101]
	v_mfma_f32_16x16x32_bf16 v[90:93], v[168:171], v[208:211], v[90:93]
	v_mfma_f32_16x16x32_bf16 v[90:93], v[172:175], v[212:215], v[90:93]
	v_mfma_f32_16x16x32_bf16 v[82:85], v[158:161], v[216:219], v[82:85]
	v_mfma_f32_16x16x32_bf16 v[82:85], v[164:167], v[220:223], v[82:85]
	v_mfma_f32_16x16x32_bf16 v[74:77], v[168:171], v[216:219], v[74:77]
	v_mfma_f32_16x16x32_bf16 v[74:77], v[172:175], v[220:223], v[74:77]
	s_setprio 0
	s_setprio 3
	v_mfma_f32_16x16x32_bf16 v[118:121], v[176:179], v[192:195], v[118:121]
	v_mfma_f32_16x16x32_bf16 v[118:121], v[180:183], v[196:199], v[118:121]
	v_mfma_f32_16x16x32_bf16 v[110:113], v[184:187], v[192:195], v[110:113]
	v_mfma_f32_16x16x32_bf16 v[110:113], v[188:191], v[196:199], v[110:113]
	v_mfma_f32_16x16x32_bf16 v[102:105], v[176:179], v[200:203], v[102:105]
	v_mfma_f32_16x16x32_bf16 v[102:105], v[180:183], v[204:207], v[102:105]
	v_mfma_f32_16x16x32_bf16 v[94:97], v[184:187], v[200:203], v[94:97]
	v_mfma_f32_16x16x32_bf16 v[94:97], v[188:191], v[204:207], v[94:97]
	v_mfma_f32_16x16x32_bf16 v[86:89], v[176:179], v[208:211], v[86:89]
	v_mfma_f32_16x16x32_bf16 v[86:89], v[180:183], v[212:215], v[86:89]
	v_mfma_f32_16x16x32_bf16 v[78:81], v[184:187], v[208:211], v[78:81]
	v_mfma_f32_16x16x32_bf16 v[78:81], v[188:191], v[212:215], v[78:81]
	v_mfma_f32_16x16x32_bf16 v[70:73], v[176:179], v[216:219], v[70:73]
	v_mfma_f32_16x16x32_bf16 v[70:73], v[180:183], v[220:223], v[70:73]
	v_mfma_f32_16x16x32_bf16 v[66:69], v[184:187], v[216:219], v[66:69]
	v_mfma_f32_16x16x32_bf16 v[66:69], v[188:191], v[220:223], v[66:69]
	s_setprio 0
	s_barrier
	s_add_i32 s56, s42, s30
	v_lshl_add_u64 v[146:147], s[26:27], 0, v[134:135]
	s_mov_b32 m0, s56
	ds_read_b128 v[192:195], v157 offset:16384
	ds_read_b128 v[196:199], v157 offset:17408
	ds_read_b128 v[200:203], v157 offset:18432
	ds_read_b128 v[204:207], v157 offset:19456
	ds_read_b128 v[208:211], v157 offset:20480
	ds_read_b128 v[212:215], v157 offset:21504
	ds_read_b128 v[216:219], v157 offset:22528
	ds_read_b128 v[220:223], v157 offset:23552
	global_load_lds_dwordx4 v[146:147], off
	s_add_i32 m0, s56, 0x2000
	s_add_u32 s56, s26, 0x100000
	v_lshl_add_u64 v[224:225], s[26:27], 0, v[130:131]
	s_addc_u32 s57, s27, 0
	s_add_i32 s58, s43, s30
	global_load_lds_dwordx4 v[224:225], off
	v_lshl_add_u64 v[226:227], s[56:57], 0, v[134:135]
	s_mov_b32 m0, s58
	v_lshl_add_u64 v[228:229], s[28:29], 0, v[132:133]
	global_load_lds_dwordx4 v[226:227], off
	v_lshl_add_u64 v[226:227], s[56:57], 0, v[130:131]
	s_add_i32 m0, s58, 0x2000
	s_nop 0
	global_load_lds_dwordx4 v[226:227], off
	v_lshl_add_u64 v[226:227], s[28:29], 0, v[136:137]
	s_mov_b32 m0, s23
	s_nop 0
	global_load_lds_dwordx4 v[226:227], off
	s_mov_b32 m0, s33
	s_nop 0
	global_load_lds_dwordx4 v[228:229], off
	s_waitcnt vmcnt(8)
	s_waitcnt lgkmcnt(0)
	s_barrier
; #define PG8_STAGE(bufoff, gbase, voff) do { _Pragma("unroll") for (int _i = 0; _i < 2; ++_i) \
;         __builtin_amdgcn_global_load_lds((const unsigned*)((const char*)(gbase) + (voff)[_i]), (PG8_LAS unsigned*)(lds + (bufoff) + ldsw + _i * 8192), 16, 0, 0); } while (0)
; #define PG8_LDA(dst, b, h) do { _Pragma("unroll") for (int m = 0; m < 4; ++m) _Pragma("unroll") for (int k = 0; k < 2; ++k) dst[m][k] = *(const PG8_LAS bf16x8*)(lds + PG8_SA(b, h) + aoff + m * 2048 + k * 1024); } while (0)
; #define PG8_LDB(dst, b, h) do { _Pragma("unroll") for (int n = 0; n < 2; ++n) _Pragma("unroll") for (int k = 0; k < 2; ++k) dst[n][k] = *(const PG8_LAS bf16x8*)(lds + PG8_SB(b, h) + boff + n * 2048 + k * 1024); } while (0)
; #define PG8_MMA(ai, bj, At, Bt) do { __builtin_amdgcn_s_setprio(3); _Pragma("unroll") for (int m = 0; m < 4; ++m) _Pragma("unroll") for (int n = 0; n < 2; ++n) _Pragma("unroll") for (int k = 0; k < 2; ++k) \
;         acc[ai][bj][m][n] = __builtin_amdgcn_mfma_f32_16x16x32_bf16(Bt[n][k], At[m][k], acc[ai][bj][m][n], 0, 0, 0); __builtin_amdgcn_s_setprio(0); } while (0)
; #define PG8_WAIT_V(n) asm volatile("s_waitcnt vmcnt(" #n ")" ::: "memory")
; #define PG8_WAIT_L(n) asm volatile("s_waitcnt lgkmcnt(" #n ")" ::: "memory")
; #define PG8_BAR __builtin_amdgcn_s_barrier()
; #define PG8_SCHED __builtin_amdgcn_sched_barrier(0)
; template <class Epi, class Sched, bool ALIGN_EPI = false, bool SP2 = false>
; __device__ __forceinline__ void gemm_phase(PG8_LAS unsigned char* lds, const Gemm g, const Sched& S, const Epi& E) {
;     ...
;             PG8_WAIT_V(8); PG8_WAIT_L(0); PG8_BAR; PG8_MMA(1, 0, At, B0); PG8_MMA(1, 1, At, B1); PG8_BAR; PG8_SCHED;
;             PG8_LDB(B0, 1, 0); PG8_LDB(B1, 1, 1); PG8_SCHED; PG8_LDA(At, 1, 0); PG8_STAGE(PG8_SA(0, 1), a2 + hstepA, voffA);
;             PG8_WAIT_V(8); PG8_WAIT_L(0); PG8_BAR; PG8_MMA(0, 0, At, B0); PG8_MMA(0, 1, At, B1); PG8_BAR; PG8_SCHED;
	s_setprio 3
	s_waitcnt lgkmcnt(0)
	v_mfma_f32_16x16x32_bf16 v[62:65], v[158:161], v[192:195], v[62:65]
	v_mfma_f32_16x16x32_bf16 v[62:65], v[164:167], v[196:199], v[62:65]
	v_mfma_f32_16x16x32_bf16 v[58:61], v[168:171], v[192:195], v[58:61]
	v_mfma_f32_16x16x32_bf16 v[58:61], v[172:175], v[196:199], v[58:61]
	v_mfma_f32_16x16x32_bf16 v[50:53], v[158:161], v[200:203], v[50:53]
	v_mfma_f32_16x16x32_bf16 v[50:53], v[164:167], v[204:207], v[50:53]
	v_mfma_f32_16x16x32_bf16 v[42:45], v[168:171], v[200:203], v[42:45]
	v_mfma_f32_16x16x32_bf16 v[42:45], v[172:175], v[204:207], v[42:45]
	v_mfma_f32_16x16x32_bf16 v[34:37], v[158:161], v[208:211], v[34:37]
	v_mfma_f32_16x16x32_bf16 v[34:37], v[164:167], v[212:215], v[34:37]
	v_mfma_f32_16x16x32_bf16 v[26:29], v[168:171], v[208:211], v[26:29]
	v_mfma_f32_16x16x32_bf16 v[26:29], v[172:175], v[212:215], v[26:29]
	v_mfma_f32_16x16x32_bf16 v[14:17], v[158:161], v[216:219], v[14:17]
	v_mfma_f32_16x16x32_bf16 v[14:17], v[164:167], v[220:223], v[14:17]
	v_mfma_f32_16x16x32_bf16 v[10:13], v[168:171], v[216:219], v[10:13]
	v_mfma_f32_16x16x32_bf16 v[10:13], v[172:175], v[220:223], v[10:13]
	s_setprio 0
	s_setprio 3
	v_mfma_f32_16x16x32_bf16 v[54:57], v[176:179], v[192:195], v[54:57]
	v_mfma_f32_16x16x32_bf16 v[54:57], v[180:183], v[196:199], v[54:57]
	v_mfma_f32_16x16x32_bf16 v[46:49], v[184:187], v[192:195], v[46:49]
	v_mfma_f32_16x16x32_bf16 v[46:49], v[188:191], v[196:199], v[46:49]
	v_mfma_f32_16x16x32_bf16 v[38:41], v[176:179], v[200:203], v[38:41]
	v_mfma_f32_16x16x32_bf16 v[38:41], v[180:183], v[204:207], v[38:41]
	v_mfma_f32_16x16x32_bf16 v[30:33], v[184:187], v[200:203], v[30:33]
	v_mfma_f32_16x16x32_bf16 v[30:33], v[188:191], v[204:207], v[30:33]
	v_mfma_f32_16x16x32_bf16 v[22:25], v[176:179], v[208:211], v[22:25]
	v_mfma_f32_16x16x32_bf16 v[22:25], v[180:183], v[212:215], v[22:25]
	v_mfma_f32_16x16x32_bf16 v[18:21], v[184:187], v[208:211], v[18:21]
	v_mfma_f32_16x16x32_bf16 v[18:21], v[188:191], v[212:215], v[18:21]
	v_mfma_f32_16x16x32_bf16 v[6:9], v[176:179], v[216:219], v[6:9]
	v_mfma_f32_16x16x32_bf16 v[6:9], v[180:183], v[220:223], v[6:9]
	v_mfma_f32_16x16x32_bf16 v[2:5], v[184:187], v[216:219], v[2:5]
	v_mfma_f32_16x16x32_bf16 v[2:5], v[188:191], v[220:223], v[2:5]
	s_setprio 0
	s_barrier
	s_add_i32 s56, 0, 0x18000
	v_add_u32_e32 v148, s56, v151
	s_add_i32 s57, 0, 0x1c000
	ds_read_b128 v[158:161], v148
	ds_read_b128 v[164:167], v148 offset:1024
	ds_read_b128 v[168:171], v148 offset:2048
	ds_read_b128 v[172:175], v148 offset:3072
	v_add_u32_e32 v148, s57, v151
	ds_read_b128 v[176:179], v148
	ds_read_b128 v[180:183], v148 offset:1024
	ds_read_b128 v[184:187], v148 offset:2048
	ds_read_b128 v[188:191], v148 offset:3072
	s_add_u32 s28, s28, 0x100000
	s_addc_u32 s29, s29, 0
	s_mov_b32 m0, s36
	v_lshl_add_u64 v[230:231], s[28:29], 0, v[136:137]
	ds_read_b128 v[192:195], v157 offset:32768
	ds_read_b128 v[196:199], v157 offset:33792
	ds_read_b128 v[200:203], v157 offset:34816
	ds_read_b128 v[204:207], v157 offset:35840
	ds_read_b128 v[208:211], v157 offset:36864
	ds_read_b128 v[212:215], v157 offset:37888
	ds_read_b128 v[216:219], v157 offset:38912
	ds_read_b128 v[220:223], v157 offset:39936
	global_load_lds_dwordx4 v[230:231], off
	v_lshl_add_u64 v[230:231], s[28:29], 0, v[132:133]
	s_mov_b32 m0, s37
	s_nop 0
	global_load_lds_dwordx4 v[230:231], off
	s_waitcnt vmcnt(8)
	s_waitcnt lgkmcnt(0)
	s_barrier
	s_setprio 3
	s_waitcnt lgkmcnt(0)
	v_mfma_f32_16x16x32_bf16 v[126:129], v[158:161], v[192:195], v[126:129]
	v_mfma_f32_16x16x32_bf16 v[126:129], v[164:167], v[196:199], v[126:129]
	v_mfma_f32_16x16x32_bf16 v[122:125], v[168:171], v[192:195], v[122:125]
	v_mfma_f32_16x16x32_bf16 v[122:125], v[172:175], v[196:199], v[122:125]
	v_mfma_f32_16x16x32_bf16 v[114:117], v[158:161], v[200:203], v[114:117]
	v_mfma_f32_16x16x32_bf16 v[114:117], v[164:167], v[204:207], v[114:117]
	v_mfma_f32_16x16x32_bf16 v[106:109], v[168:171], v[200:203], v[106:109]
	v_mfma_f32_16x16x32_bf16 v[106:109], v[172:175], v[204:207], v[106:109]
	v_mfma_f32_16x16x32_bf16 v[98:101], v[158:161], v[208:211], v[98:101]
	v_mfma_f32_16x16x32_bf16 v[98:101], v[164:167], v[212:215], v[98:101]
	v_mfma_f32_16x16x32_bf16 v[90:93], v[168:171], v[208:211], v[90:93]
	v_mfma_f32_16x16x32_bf16 v[90:93], v[172:175], v[212:215], v[90:93]
	v_mfma_f32_16x16x32_bf16 v[82:85], v[158:161], v[216:219], v[82:85]
	v_mfma_f32_16x16x32_bf16 v[82:85], v[164:167], v[220:223], v[82:85]
	v_mfma_f32_16x16x32_bf16 v[74:77], v[168:171], v[216:219], v[74:77]
	v_mfma_f32_16x16x32_bf16 v[74:77], v[172:175], v[220:223], v[74:77]
	s_setprio 0
	s_setprio 3
	v_mfma_f32_16x16x32_bf16 v[118:121], v[176:179], v[192:195], v[118:121]
	v_mfma_f32_16x16x32_bf16 v[118:121], v[180:183], v[196:199], v[118:121]
	v_mfma_f32_16x16x32_bf16 v[110:113], v[184:187], v[192:195], v[110:113]
	v_mfma_f32_16x16x32_bf16 v[110:113], v[188:191], v[196:199], v[110:113]
	v_mfma_f32_16x16x32_bf16 v[102:105], v[176:179], v[200:203], v[102:105]
	v_mfma_f32_16x16x32_bf16 v[102:105], v[180:183], v[204:207], v[102:105]
	v_mfma_f32_16x16x32_bf16 v[94:97], v[184:187], v[200:203], v[94:97]
	v_mfma_f32_16x16x32_bf16 v[94:97], v[188:191], v[204:207], v[94:97]
	v_mfma_f32_16x16x32_bf16 v[86:89], v[176:179], v[208:211], v[86:89]
	v_mfma_f32_16x16x32_bf16 v[86:89], v[180:183], v[212:215], v[86:89]
	v_mfma_f32_16x16x32_bf16 v[78:81], v[184:187], v[208:211], v[78:81]
	v_mfma_f32_16x16x32_bf16 v[78:81], v[188:191], v[212:215], v[78:81]
	v_mfma_f32_16x16x32_bf16 v[70:73], v[176:179], v[216:219], v[70:73]
	v_mfma_f32_16x16x32_bf16 v[70:73], v[180:183], v[220:223], v[70:73]
	v_mfma_f32_16x16x32_bf16 v[66:69], v[184:187], v[216:219], v[66:69]
	v_mfma_f32_16x16x32_bf16 v[66:69], v[188:191], v[220:223], v[66:69]
	s_setprio 0
	s_barrier
; #define PG8_STAGE(bufoff, gbase, voff) do { _Pragma("unroll") for (int _i = 0; _i < 2; ++_i) \
;         __builtin_amdgcn_global_load_lds((const unsigned*)((const char*)(gbase) + (voff)[_i]), (PG8_LAS unsigned*)(lds + (bufoff) + ldsw + _i * 8192), 16, 0, 0); } while (0)
; #define PG8_LDA(dst, b, h) do { _Pragma("unroll") for (int m = 0; m < 4; ++m) _Pragma("unroll") for (int k = 0; k < 2; ++k) dst[m][k] = *(const PG8_LAS bf16x8*)(lds + PG8_SA(b, h) + aoff + m * 2048 + k * 1024); } while (0)
; #define PG8_MMA(ai, bj, At, Bt) do { __builtin_amdgcn_s_setprio(3); _Pragma("unroll") for (int m = 0; m < 4; ++m) _Pragma("unroll") for (int n = 0; n < 2; ++n) _Pragma("unroll") for (int k = 0; k < 2; ++k) \
;         acc[ai][bj][m][n] = __builtin_amdgcn_mfma_f32_16x16x32_bf16(Bt[n][k], At[m][k], acc[ai][bj][m][n], 0, 0, 0); __builtin_amdgcn_s_setprio(0); } while (0)
; #define PG8_WAIT_V(n) asm volatile("s_waitcnt vmcnt(" #n ")" ::: "memory")
; #define PG8_WAIT_L(n) asm volatile("s_waitcnt lgkmcnt(" #n ")" ::: "memory")
; #define PG8_BAR __builtin_amdgcn_s_barrier()
; #define PG8_SCHED __builtin_amdgcn_sched_barrier(0)
; template <class Epi, class Sched, bool ALIGN_EPI = false, bool SP2 = false>
; __device__ __forceinline__ void gemm_phase(PG8_LAS unsigned char* lds, const Gemm g, const Sched& S, const Epi& E) {
;     ...
;             PG8_LDA(At, 1, 1); PG8_STAGE(PG8_SB(1, 0), b3, voffB); PG8_STAGE(PG8_SB(1, 1), b3 + hstepB, voffB); PG8_STAGE(PG8_SA(1, 0), a3, voffA);
;             PG8_WAIT_V(8); PG8_WAIT_L(0); PG8_BAR; PG8_MMA(1, 0, At, B0); PG8_MMA(1, 1, At, B1); PG8_BAR; PG8_SCHED;
;     ...
;         if constexpr (ALIGN_EPI) { if (wr == 0) PG8_BAR; }
	s_add_i32 s28, s56, s30
	v_lshl_add_u64 v[146:147], v[146:147], 0, s[12:13]
	s_mov_b32 m0, s28
	ds_read_b128 v[192:195], v157 offset:49152
	ds_read_b128 v[196:199], v157 offset:50176
	ds_read_b128 v[200:203], v157 offset:51200
	ds_read_b128 v[204:207], v157 offset:52224
	ds_read_b128 v[208:211], v157 offset:53248
	ds_read_b128 v[212:215], v157 offset:54272
	ds_read_b128 v[216:219], v157 offset:55296
	ds_read_b128 v[220:223], v157 offset:56320
	global_load_lds_dwordx4 v[146:147], off
	s_add_i32 m0, s28, 0x2000
	s_add_u32 s26, s26, 0x100080
	v_lshl_add_u64 v[146:147], v[224:225], 0, s[12:13]
	s_addc_u32 s27, s27, 0
	s_add_i32 s28, s57, s30
	global_load_lds_dwordx4 v[146:147], off
	v_lshl_add_u64 v[146:147], s[26:27], 0, v[134:135]
	s_mov_b32 m0, s28
	s_nop 0
	global_load_lds_dwordx4 v[146:147], off
	v_lshl_add_u64 v[146:147], s[26:27], 0, v[130:131]
	s_add_i32 m0, s28, 0x2000
	s_nop 0
	global_load_lds_dwordx4 v[146:147], off
	v_lshl_add_u64 v[146:147], v[226:227], 0, s[12:13]
	s_mov_b32 m0, s39
	s_nop 0
	global_load_lds_dwordx4 v[146:147], off
	v_lshl_add_u64 v[146:147], v[228:229], 0, s[12:13]
	s_mov_b32 m0, s40
	s_nop 0
	global_load_lds_dwordx4 v[146:147], off
	s_waitcnt vmcnt(8)
	s_waitcnt lgkmcnt(0)
	s_barrier
	s_setprio 3
	s_waitcnt lgkmcnt(0)
	v_mfma_f32_16x16x32_bf16 v[62:65], v[158:161], v[192:195], v[62:65]
	v_mfma_f32_16x16x32_bf16 v[62:65], v[164:167], v[196:199], v[62:65]
	v_mfma_f32_16x16x32_bf16 v[58:61], v[168:171], v[192:195], v[58:61]
	v_mfma_f32_16x16x32_bf16 v[58:61], v[172:175], v[196:199], v[58:61]
	v_mfma_f32_16x16x32_bf16 v[50:53], v[158:161], v[200:203], v[50:53]
	v_mfma_f32_16x16x32_bf16 v[50:53], v[164:167], v[204:207], v[50:53]
	v_mfma_f32_16x16x32_bf16 v[42:45], v[168:171], v[200:203], v[42:45]
	v_mfma_f32_16x16x32_bf16 v[42:45], v[172:175], v[204:207], v[42:45]
	v_mfma_f32_16x16x32_bf16 v[34:37], v[158:161], v[208:211], v[34:37]
	v_mfma_f32_16x16x32_bf16 v[34:37], v[164:167], v[212:215], v[34:37]
	v_mfma_f32_16x16x32_bf16 v[26:29], v[168:171], v[208:211], v[26:29]
	v_mfma_f32_16x16x32_bf16 v[26:29], v[172:175], v[212:215], v[26:29]
	v_mfma_f32_16x16x32_bf16 v[14:17], v[158:161], v[216:219], v[14:17]
	v_mfma_f32_16x16x32_bf16 v[14:17], v[164:167], v[220:223], v[14:17]
	v_mfma_f32_16x16x32_bf16 v[10:13], v[168:171], v[216:219], v[10:13]
	v_mfma_f32_16x16x32_bf16 v[10:13], v[172:175], v[220:223], v[10:13]
	s_setprio 0
	s_setprio 3
	v_mfma_f32_16x16x32_bf16 v[54:57], v[176:179], v[192:195], v[54:57]
	v_mfma_f32_16x16x32_bf16 v[54:57], v[180:183], v[196:199], v[54:57]
	v_mfma_f32_16x16x32_bf16 v[46:49], v[184:187], v[192:195], v[46:49]
	v_mfma_f32_16x16x32_bf16 v[46:49], v[188:191], v[196:199], v[46:49]
	v_mfma_f32_16x16x32_bf16 v[38:41], v[176:179], v[200:203], v[38:41]
	v_mfma_f32_16x16x32_bf16 v[38:41], v[180:183], v[204:207], v[38:41]
	v_mfma_f32_16x16x32_bf16 v[30:33], v[184:187], v[200:203], v[30:33]
	v_mfma_f32_16x16x32_bf16 v[30:33], v[188:191], v[204:207], v[30:33]
	v_mfma_f32_16x16x32_bf16 v[22:25], v[176:179], v[208:211], v[22:25]
	v_mfma_f32_16x16x32_bf16 v[22:25], v[180:183], v[212:215], v[22:25]
	v_mfma_f32_16x16x32_bf16 v[18:21], v[184:187], v[208:211], v[18:21]
	v_mfma_f32_16x16x32_bf16 v[18:21], v[188:191], v[212:215], v[18:21]
	v_mfma_f32_16x16x32_bf16 v[6:9], v[176:179], v[216:219], v[6:9]
	v_mfma_f32_16x16x32_bf16 v[6:9], v[180:183], v[220:223], v[6:9]
	v_mfma_f32_16x16x32_bf16 v[2:5], v[184:187], v[216:219], v[2:5]
	v_mfma_f32_16x16x32_bf16 v[2:5], v[188:191], v[220:223], v[2:5]
	s_setprio 0
	s_barrier
	s_add_i32 s55, s55, 2
	s_add_u32 s24, s24, 0x100
	s_addc_u32 s25, s25, 0
	s_add_u32 s53, s53, 0x100
	s_addc_u32 s54, s54, 0
	s_cmp_gt_u32 s55, 61
	s_cbranch_scc0 .LBB0_908
	s_and_b64 vcc, exec, s[0:1]
	s_cbranch_vccz .LBB0_911
	s_barrier

; #define PG8_STAGE(bufoff, gbase, voff) do { _Pragma("unroll") for (int _i = 0; _i < 2; ++_i) \
;         __builtin_amdgcn_global_load_lds((const unsigned*)((const char*)(gbase) + (voff)[_i]), (PG8_LAS unsigned*)(lds + (bufoff) + ldsw + _i * 8192), 16, 0, 0); } while (0)
; #define PG8_LDA(dst, b, h) do { _Pragma("unroll") for (int m = 0; m < 4; ++m) _Pragma("unroll") for (int k = 0; k < 2; ++k) dst[m][k] = *(const PG8_LAS bf16x8*)(lds + PG8_SA(b, h) + aoff + m * 2048 + k * 1024); } while (0)
; #define PG8_LDB(dst, b, h) do { _Pragma("unroll") for (int n = 0; n < 2; ++n) _Pragma("unroll") for (int k = 0; k < 2; ++k) dst[n][k] = *(const PG8_LAS bf16x8*)(lds + PG8_SB(b, h) + boff + n * 2048 + k * 1024); } while (0)
; #define PG8_MMA(ai, bj, At, Bt) do { __builtin_amdgcn_s_setprio(3); _Pragma("unroll") for (int m = 0; m < 4; ++m) _Pragma("unroll") for (int n = 0; n < 2; ++n) _Pragma("unroll") for (int k = 0; k < 2; ++k) \
;         acc[ai][bj][m][n] = __builtin_amdgcn_mfma_f32_16x16x32_bf16(Bt[n][k], At[m][k], acc[ai][bj][m][n], 0, 0, 0); __builtin_amdgcn_s_setprio(0); } while (0)
; #define PG8_WAIT_V(n) asm volatile("s_waitcnt vmcnt(" #n ")" ::: "memory")
; #define PG8_WAIT_L(n) asm volatile("s_waitcnt lgkmcnt(" #n ")" ::: "memory")
; #define PG8_BAR __builtin_amdgcn_s_barrier()
; #define PG8_SCHED __builtin_amdgcn_sched_barrier(0)
; template <class Epi, class Sched, bool ALIGN_EPI = false, bool SP2 = false>
; __device__ __forceinline__ void gemm_phase(PG8_LAS unsigned char* lds, const Gemm g, const Sched& S, const Epi& E) {
;     ...
;             const char* a1 = cA + (size_t)(t + 1) * kstep;
;             const char* a2 = last ? nA : cA + (size_t)(t + 2) * kstep; const char* b2 = last ? nB : cB + (size_t)(t + 2) * kstep;
;             const char* a3 = a2 + kstep; const char* b3 = b2 + kstep;
;             if (last && has_next) S.a_ready(nxt);
;             if constexpr (Epi::MIDK) { if (t == E.midk_step(nt)) E.midk(acc, cur, wr, wc, fr, fq); }
;             if constexpr (SP2) {
;             PG8_LDB(B0, 0, 0); PG8_LDB(B1, 0, 1); PG8_SCHED; PG8_LDA(At, 0, 0); PG8_STAGE(PG8_SA(1, 1), a1 + hstepA, voffA);
;             PG8_WAIT_V(8); PG8_WAIT_L(0); PG8_BAR; PG8_MMA(0, 0, At, B0); PG8_MMA(0, 1, At, B1); PG8_BAR; PG8_SCHED;
;             PG8_LDA(At, 0, 1); PG8_STAGE(PG8_SB(0, 0), b2, voffB); PG8_STAGE(PG8_SB(0, 1), b2 + hstepB, voffB); PG8_STAGE(PG8_SA(0, 0), a2, voffA);
.LBB0_975:
	v_add_u32_e32 v144, s46, v206
	v_add_u32_e32 v160, s47, v206
	s_add_u32 s28, s2, s12
	ds_read_b128 v[132:135], v144
	ds_read_b128 v[136:139], v144 offset:1024
	ds_read_b128 v[140:143], v144 offset:2048
	ds_read_b128 v[144:147], v144 offset:3072
	ds_read_b128 v[148:151], v160
	ds_read_b128 v[152:155], v160 offset:1024
	ds_read_b128 v[156:159], v160 offset:2048
	ds_read_b128 v[160:163], v160 offset:3072
	s_addc_u32 s29, s3, s13
	s_add_u32 s28, s28, 0x21500100
	s_addc_u32 s29, s29, 0
	s_add_u32 s81, s44, s12
	s_addc_u32 s82, s45, s13
	s_cmpk_eq_i32 s12, 0x5500
	s_cselect_b32 s31, s1, s29
	s_cselect_b32 s30, s0, s28
	s_cselect_b32 s29, s11, s82
	s_cselect_b32 s28, s10, s81
	s_mov_b32 m0, s71
	v_lshl_add_u64 v[234:235], v[2:3], 0, s[12:13]
	ds_read_b128 v[164:167], v207
	ds_read_b128 v[168:171], v207 offset:1024
	ds_read_b128 v[210:213], v207 offset:2048
	ds_read_b128 v[214:217], v207 offset:3072
	ds_read_b128 v[218:221], v207 offset:4096
	ds_read_b128 v[222:225], v207 offset:5120
	ds_read_b128 v[226:229], v207 offset:6144
	ds_read_b128 v[230:233], v207 offset:7168
	global_load_lds_dwordx4 v[234:235], off
	v_lshl_add_u64 v[234:235], v[200:201], 0, s[12:13]
	s_mov_b32 m0, s72
	s_nop 0
	global_load_lds_dwordx4 v[234:235], off
	s_waitcnt vmcnt(8)
	s_waitcnt lgkmcnt(0)
	s_barrier
	s_setprio 3
	s_waitcnt lgkmcnt(0)
	v_mfma_f32_16x16x32_bf16 v[128:131], v[132:135], v[164:167], v[128:131]
	v_mfma_f32_16x16x32_bf16 v[128:131], v[136:139], v[168:171], v[128:131]
	v_mfma_f32_16x16x32_bf16 v[124:127], v[140:143], v[164:167], v[124:127]
	v_mfma_f32_16x16x32_bf16 v[124:127], v[144:147], v[168:171], v[124:127]
	v_mfma_f32_16x16x32_bf16 v[100:103], v[132:135], v[210:213], v[100:103]
	v_mfma_f32_16x16x32_bf16 v[100:103], v[136:139], v[214:217], v[100:103]
	v_mfma_f32_16x16x32_bf16 v[96:99], v[140:143], v[210:213], v[96:99]
	v_mfma_f32_16x16x32_bf16 v[96:99], v[144:147], v[214:217], v[96:99]
	v_mfma_f32_16x16x32_bf16 v[112:115], v[132:135], v[218:221], v[112:115]
	v_mfma_f32_16x16x32_bf16 v[112:115], v[136:139], v[222:225], v[112:115]
	v_mfma_f32_16x16x32_bf16 v[108:111], v[140:143], v[218:221], v[108:111]
	v_mfma_f32_16x16x32_bf16 v[108:111], v[144:147], v[222:225], v[108:111]
	v_mfma_f32_16x16x32_bf16 v[80:83], v[132:135], v[226:229], v[80:83]
	v_mfma_f32_16x16x32_bf16 v[80:83], v[136:139], v[230:233], v[80:83]
	v_mfma_f32_16x16x32_bf16 v[76:79], v[140:143], v[226:229], v[76:79]
	v_mfma_f32_16x16x32_bf16 v[76:79], v[144:147], v[230:233], v[76:79]
	s_setprio 0
	s_setprio 3
	v_mfma_f32_16x16x32_bf16 v[120:123], v[148:151], v[164:167], v[120:123]
	v_mfma_f32_16x16x32_bf16 v[120:123], v[152:155], v[168:171], v[120:123]
	v_mfma_f32_16x16x32_bf16 v[116:119], v[156:159], v[164:167], v[116:119]
	v_mfma_f32_16x16x32_bf16 v[116:119], v[160:163], v[168:171], v[116:119]
	v_mfma_f32_16x16x32_bf16 v[92:95], v[148:151], v[210:213], v[92:95]
	v_mfma_f32_16x16x32_bf16 v[92:95], v[152:155], v[214:217], v[92:95]
	v_mfma_f32_16x16x32_bf16 v[88:91], v[156:159], v[210:213], v[88:91]
	v_mfma_f32_16x16x32_bf16 v[88:91], v[160:163], v[214:217], v[88:91]
	v_mfma_f32_16x16x32_bf16 v[104:107], v[148:151], v[218:221], v[104:107]
	v_mfma_f32_16x16x32_bf16 v[104:107], v[152:155], v[222:225], v[104:107]
	v_mfma_f32_16x16x32_bf16 v[84:87], v[156:159], v[218:221], v[84:87]
	v_mfma_f32_16x16x32_bf16 v[84:87], v[160:163], v[222:225], v[84:87]
	v_mfma_f32_16x16x32_bf16 v[72:75], v[148:151], v[226:229], v[72:75]
	v_mfma_f32_16x16x32_bf16 v[72:75], v[152:155], v[230:233], v[72:75]
	v_mfma_f32_16x16x32_bf16 v[68:71], v[156:159], v[226:229], v[68:71]
	v_mfma_f32_16x16x32_bf16 v[68:71], v[160:163], v[230:233], v[68:71]
	s_setprio 0
	s_barrier
	s_mov_b32 m0, s73
	v_lshl_add_u64 v[234:235], s[28:29], 0, v[174:175]
	s_add_u32 s82, s28, 0x2b0000
	ds_read_b128 v[164:167], v207 offset:16384
	ds_read_b128 v[168:171], v207 offset:17408
	ds_read_b128 v[210:213], v207 offset:18432
	ds_read_b128 v[214:217], v207 offset:19456
	ds_read_b128 v[218:221], v207 offset:20480
	ds_read_b128 v[222:225], v207 offset:21504
	ds_read_b128 v[226:229], v207 offset:22528
	ds_read_b128 v[230:233], v207 offset:23552
	global_load_lds_dwordx4 v[234:235], off
	v_lshl_add_u64 v[236:237], s[28:29], 0, v[178:179]
	s_mov_b32 m0, s74
	s_addc_u32 s83, s29, 0
	global_load_lds_dwordx4 v[236:237], off
	v_lshl_add_u64 v[238:239], s[82:83], 0, v[174:175]
	s_mov_b32 m0, s75
	v_lshl_add_u64 v[240:241], s[30:31], 0, v[176:177]
	global_load_lds_dwordx4 v[238:239], off
	v_lshl_add_u64 v[238:239], s[82:83], 0, v[178:179]
	s_mov_b32 m0, s76
	s_nop 0
	global_load_lds_dwordx4 v[238:239], off
	v_lshl_add_u64 v[238:239], s[30:31], 0, v[172:173]
	s_mov_b32 m0, s42
	s_nop 0
	global_load_lds_dwordx4 v[238:239], off
	s_mov_b32 m0, s54
	s_nop 0
	global_load_lds_dwordx4 v[240:241], off
	s_waitcnt vmcnt(8)
	s_waitcnt lgkmcnt(0)
	s_barrier
; #define PG8_STAGE(bufoff, gbase, voff) do { _Pragma("unroll") for (int _i = 0; _i < 2; ++_i) \
;         __builtin_amdgcn_global_load_lds((const unsigned*)((const char*)(gbase) + (voff)[_i]), (PG8_LAS unsigned*)(lds + (bufoff) + ldsw + _i * 8192), 16, 0, 0); } while (0)
; #define PG8_LDA(dst, b, h) do { _Pragma("unroll") for (int m = 0; m < 4; ++m) _Pragma("unroll") for (int k = 0; k < 2; ++k) dst[m][k] = *(const PG8_LAS bf16x8*)(lds + PG8_SA(b, h) + aoff + m * 2048 + k * 1024); } while (0)
; #define PG8_LDB(dst, b, h) do { _Pragma("unroll") for (int n = 0; n < 2; ++n) _Pragma("unroll") for (int k = 0; k < 2; ++k) dst[n][k] = *(const PG8_LAS bf16x8*)(lds + PG8_SB(b, h) + boff + n * 2048 + k * 1024); } while (0)
; #define PG8_MMA(ai, bj, At, Bt) do { __builtin_amdgcn_s_setprio(3); _Pragma("unroll") for (int m = 0; m < 4; ++m) _Pragma("unroll") for (int n = 0; n < 2; ++n) _Pragma("unroll") for (int k = 0; k < 2; ++k) \
;         acc[ai][bj][m][n] = __builtin_amdgcn_mfma_f32_16x16x32_bf16(Bt[n][k], At[m][k], acc[ai][bj][m][n], 0, 0, 0); __builtin_amdgcn_s_setprio(0); } while (0)
; #define PG8_WAIT_V(n) asm volatile("s_waitcnt vmcnt(" #n ")" ::: "memory")
; #define PG8_WAIT_L(n) asm volatile("s_waitcnt lgkmcnt(" #n ")" ::: "memory")
; #define PG8_BAR __builtin_amdgcn_s_barrier()
; #define PG8_SCHED __builtin_amdgcn_sched_barrier(0)
; template <class Epi, class Sched, bool ALIGN_EPI = false, bool SP2 = false>
; __device__ __forceinline__ void gemm_phase(PG8_LAS unsigned char* lds, const Gemm g, const Sched& S, const Epi& E) {
;     ...
;             PG8_WAIT_V(8); PG8_WAIT_L(0); PG8_BAR; PG8_MMA(1, 0, At, B0); PG8_MMA(1, 1, At, B1); PG8_BAR; PG8_SCHED;
;             PG8_LDB(B0, 1, 0); PG8_LDB(B1, 1, 1); PG8_SCHED; PG8_LDA(At, 1, 0); PG8_STAGE(PG8_SA(0, 1), a2 + hstepA, voffA);
;             PG8_WAIT_V(8); PG8_WAIT_L(0); PG8_BAR; PG8_MMA(0, 0, At, B0); PG8_MMA(0, 1, At, B1); PG8_BAR; PG8_SCHED;
	s_setprio 3
	s_waitcnt lgkmcnt(0)
	v_mfma_f32_16x16x32_bf16 v[64:67], v[132:135], v[164:167], v[64:67]
	v_mfma_f32_16x16x32_bf16 v[64:67], v[136:139], v[168:171], v[64:67]
	v_mfma_f32_16x16x32_bf16 v[60:63], v[140:143], v[164:167], v[60:63]
	v_mfma_f32_16x16x32_bf16 v[60:63], v[144:147], v[168:171], v[60:63]
	v_mfma_f32_16x16x32_bf16 v[48:51], v[132:135], v[210:213], v[48:51]
	v_mfma_f32_16x16x32_bf16 v[48:51], v[136:139], v[214:217], v[48:51]
	v_mfma_f32_16x16x32_bf16 v[44:47], v[140:143], v[210:213], v[44:47]
	v_mfma_f32_16x16x32_bf16 v[44:47], v[144:147], v[214:217], v[44:47]
	v_mfma_f32_16x16x32_bf16 v[32:35], v[132:135], v[218:221], v[32:35]
	v_mfma_f32_16x16x32_bf16 v[32:35], v[136:139], v[222:225], v[32:35]
	v_mfma_f32_16x16x32_bf16 v[28:31], v[140:143], v[218:221], v[28:31]
	v_mfma_f32_16x16x32_bf16 v[28:31], v[144:147], v[222:225], v[28:31]
	v_mfma_f32_16x16x32_bf16 v[16:19], v[132:135], v[226:229], v[16:19]
	v_mfma_f32_16x16x32_bf16 v[16:19], v[136:139], v[230:233], v[16:19]
	v_mfma_f32_16x16x32_bf16 v[12:15], v[140:143], v[226:229], v[12:15]
	v_mfma_f32_16x16x32_bf16 v[12:15], v[144:147], v[230:233], v[12:15]
	s_setprio 0
	s_setprio 3
	v_mfma_f32_16x16x32_bf16 v[56:59], v[148:151], v[164:167], v[56:59]
	v_mfma_f32_16x16x32_bf16 v[56:59], v[152:155], v[168:171], v[56:59]
	v_mfma_f32_16x16x32_bf16 v[52:55], v[156:159], v[164:167], v[52:55]
	v_mfma_f32_16x16x32_bf16 v[52:55], v[160:163], v[168:171], v[52:55]
	v_mfma_f32_16x16x32_bf16 v[40:43], v[148:151], v[210:213], v[40:43]
	v_mfma_f32_16x16x32_bf16 v[40:43], v[152:155], v[214:217], v[40:43]
	v_mfma_f32_16x16x32_bf16 v[36:39], v[156:159], v[210:213], v[36:39]
	v_mfma_f32_16x16x32_bf16 v[36:39], v[160:163], v[214:217], v[36:39]
	v_mfma_f32_16x16x32_bf16 v[24:27], v[148:151], v[218:221], v[24:27]
	v_mfma_f32_16x16x32_bf16 v[24:27], v[152:155], v[222:225], v[24:27]
	v_mfma_f32_16x16x32_bf16 v[20:23], v[156:159], v[218:221], v[20:23]
	v_mfma_f32_16x16x32_bf16 v[20:23], v[160:163], v[222:225], v[20:23]
	v_mfma_f32_16x16x32_bf16 v[8:11], v[148:151], v[226:229], v[8:11]
	v_mfma_f32_16x16x32_bf16 v[8:11], v[152:155], v[230:233], v[8:11]
	v_mfma_f32_16x16x32_bf16 v[4:7], v[156:159], v[226:229], v[4:7]
	v_mfma_f32_16x16x32_bf16 v[4:7], v[160:163], v[230:233], v[4:7]
	s_setprio 0
	s_barrier
	v_add_u32_e32 v144, s52, v206
	v_add_u32_e32 v160, s53, v206
	ds_read_b128 v[132:135], v144
	ds_read_b128 v[136:139], v144 offset:1024
	ds_read_b128 v[140:143], v144 offset:2048
	ds_read_b128 v[144:147], v144 offset:3072
	ds_read_b128 v[148:151], v160
	ds_read_b128 v[152:155], v160 offset:1024
	ds_read_b128 v[156:159], v160 offset:2048
	ds_read_b128 v[160:163], v160 offset:3072
	s_add_u32 s30, s30, 0x2b0000
	s_addc_u32 s31, s31, 0
	s_mov_b32 m0, s55
	v_lshl_add_u64 v[242:243], s[30:31], 0, v[172:173]
	ds_read_b128 v[164:167], v207 offset:32768
	ds_read_b128 v[168:171], v207 offset:33792
	ds_read_b128 v[210:213], v207 offset:34816
	ds_read_b128 v[214:217], v207 offset:35840
	ds_read_b128 v[218:221], v207 offset:36864
	ds_read_b128 v[222:225], v207 offset:37888
	ds_read_b128 v[226:229], v207 offset:38912
	ds_read_b128 v[230:233], v207 offset:39936
	global_load_lds_dwordx4 v[242:243], off
	v_lshl_add_u64 v[242:243], s[30:31], 0, v[176:177]
	s_mov_b32 m0, s56
	s_nop 0
	global_load_lds_dwordx4 v[242:243], off
	s_waitcnt vmcnt(8)
	s_waitcnt lgkmcnt(0)
	s_barrier
	s_setprio 3
	s_waitcnt lgkmcnt(0)
	v_mfma_f32_16x16x32_bf16 v[128:131], v[132:135], v[164:167], v[128:131]
	v_mfma_f32_16x16x32_bf16 v[128:131], v[136:139], v[168:171], v[128:131]
	v_mfma_f32_16x16x32_bf16 v[124:127], v[140:143], v[164:167], v[124:127]
	v_mfma_f32_16x16x32_bf16 v[124:127], v[144:147], v[168:171], v[124:127]
	v_mfma_f32_16x16x32_bf16 v[100:103], v[132:135], v[210:213], v[100:103]
	v_mfma_f32_16x16x32_bf16 v[100:103], v[136:139], v[214:217], v[100:103]
	v_mfma_f32_16x16x32_bf16 v[96:99], v[140:143], v[210:213], v[96:99]
	v_mfma_f32_16x16x32_bf16 v[96:99], v[144:147], v[214:217], v[96:99]
	v_mfma_f32_16x16x32_bf16 v[112:115], v[132:135], v[218:221], v[112:115]
	v_mfma_f32_16x16x32_bf16 v[112:115], v[136:139], v[222:225], v[112:115]
	v_mfma_f32_16x16x32_bf16 v[108:111], v[140:143], v[218:221], v[108:111]
	v_mfma_f32_16x16x32_bf16 v[108:111], v[144:147], v[222:225], v[108:111]
	v_mfma_f32_16x16x32_bf16 v[80:83], v[132:135], v[226:229], v[80:83]
	v_mfma_f32_16x16x32_bf16 v[80:83], v[136:139], v[230:233], v[80:83]
	v_mfma_f32_16x16x32_bf16 v[76:79], v[140:143], v[226:229], v[76:79]
	v_mfma_f32_16x16x32_bf16 v[76:79], v[144:147], v[230:233], v[76:79]
	s_setprio 0
	s_setprio 3
	v_mfma_f32_16x16x32_bf16 v[120:123], v[148:151], v[164:167], v[120:123]
	v_mfma_f32_16x16x32_bf16 v[120:123], v[152:155], v[168:171], v[120:123]
	v_mfma_f32_16x16x32_bf16 v[116:119], v[156:159], v[164:167], v[116:119]
	v_mfma_f32_16x16x32_bf16 v[116:119], v[160:163], v[168:171], v[116:119]
	v_mfma_f32_16x16x32_bf16 v[92:95], v[148:151], v[210:213], v[92:95]
	v_mfma_f32_16x16x32_bf16 v[92:95], v[152:155], v[214:217], v[92:95]
	v_mfma_f32_16x16x32_bf16 v[88:91], v[156:159], v[210:213], v[88:91]
	v_mfma_f32_16x16x32_bf16 v[88:91], v[160:163], v[214:217], v[88:91]
	v_mfma_f32_16x16x32_bf16 v[104:107], v[148:151], v[218:221], v[104:107]
	v_mfma_f32_16x16x32_bf16 v[104:107], v[152:155], v[222:225], v[104:107]
	v_mfma_f32_16x16x32_bf16 v[84:87], v[156:159], v[218:221], v[84:87]
	v_mfma_f32_16x16x32_bf16 v[84:87], v[160:163], v[222:225], v[84:87]
	v_mfma_f32_16x16x32_bf16 v[72:75], v[148:151], v[226:229], v[72:75]
	v_mfma_f32_16x16x32_bf16 v[72:75], v[152:155], v[230:233], v[72:75]
	v_mfma_f32_16x16x32_bf16 v[68:71], v[156:159], v[226:229], v[68:71]
	v_mfma_f32_16x16x32_bf16 v[68:71], v[160:163], v[230:233], v[68:71]
	s_setprio 0
	s_barrier
; #define PG8_STAGE(bufoff, gbase, voff) do { _Pragma("unroll") for (int _i = 0; _i < 2; ++_i) \
;         __builtin_amdgcn_global_load_lds((const unsigned*)((const char*)(gbase) + (voff)[_i]), (PG8_LAS unsigned*)(lds + (bufoff) + ldsw + _i * 8192), 16, 0, 0); } while (0)
; #define PG8_LDA(dst, b, h) do { _Pragma("unroll") for (int m = 0; m < 4; ++m) _Pragma("unroll") for (int k = 0; k < 2; ++k) dst[m][k] = *(const PG8_LAS bf16x8*)(lds + PG8_SA(b, h) + aoff + m * 2048 + k * 1024); } while (0)
; #define PG8_MMA(ai, bj, At, Bt) do { __builtin_amdgcn_s_setprio(3); _Pragma("unroll") for (int m = 0; m < 4; ++m) _Pragma("unroll") for (int n = 0; n < 2; ++n) _Pragma("unroll") for (int k = 0; k < 2; ++k) \
;         acc[ai][bj][m][n] = __builtin_amdgcn_mfma_f32_16x16x32_bf16(Bt[n][k], At[m][k], acc[ai][bj][m][n], 0, 0, 0); __builtin_amdgcn_s_setprio(0); } while (0)
; #define PG8_WAIT_V(n) asm volatile("s_waitcnt vmcnt(" #n ")" ::: "memory")
; #define PG8_WAIT_L(n) asm volatile("s_waitcnt lgkmcnt(" #n ")" ::: "memory")
; #define PG8_BAR __builtin_amdgcn_s_barrier()
; #define PG8_SCHED __builtin_amdgcn_sched_barrier(0)
; template <class Epi, class Sched, bool ALIGN_EPI = false, bool SP2 = false>
; __device__ __forceinline__ void gemm_phase(PG8_LAS unsigned char* lds, const Gemm g, const Sched& S, const Epi& E) {
;     ...
;             PG8_LDA(At, 1, 1); PG8_STAGE(PG8_SB(1, 0), b3, voffB); PG8_STAGE(PG8_SB(1, 1), b3 + hstepB, voffB); PG8_STAGE(PG8_SA(1, 0), a3, voffA);
;             PG8_WAIT_V(8); PG8_WAIT_L(0); PG8_BAR; PG8_MMA(1, 0, At, B0); PG8_MMA(1, 1, At, B1); PG8_BAR; PG8_SCHED;
	s_mov_b32 m0, s77
	v_lshl_add_u64 v[234:235], v[234:235], 0, s[4:5]
	s_add_u32 s28, s28, 0x2b0080
	ds_read_b128 v[164:167], v207 offset:49152
	ds_read_b128 v[168:171], v207 offset:50176
	ds_read_b128 v[210:213], v207 offset:51200
	ds_read_b128 v[214:217], v207 offset:52224
	ds_read_b128 v[218:221], v207 offset:53248
	ds_read_b128 v[222:225], v207 offset:54272
	ds_read_b128 v[226:229], v207 offset:55296
	ds_read_b128 v[230:233], v207 offset:56320
	global_load_lds_dwordx4 v[234:235], off
	v_lshl_add_u64 v[234:235], v[236:237], 0, s[4:5]
	s_mov_b32 m0, s78
	s_addc_u32 s29, s29, 0
	global_load_lds_dwordx4 v[234:235], off
	v_lshl_add_u64 v[234:235], s[28:29], 0, v[174:175]
	s_mov_b32 m0, s79
	s_nop 0
	global_load_lds_dwordx4 v[234:235], off
	v_lshl_add_u64 v[234:235], s[28:29], 0, v[178:179]
	s_mov_b32 m0, s80
	s_nop 0
	global_load_lds_dwordx4 v[234:235], off
	v_lshl_add_u64 v[234:235], v[238:239], 0, s[4:5]
	s_mov_b32 m0, s57
	s_nop 0
	global_load_lds_dwordx4 v[234:235], off
	v_lshl_add_u64 v[234:235], v[240:241], 0, s[4:5]
	s_mov_b32 m0, s58
	s_nop 0
	global_load_lds_dwordx4 v[234:235], off
	s_waitcnt vmcnt(8)
	s_waitcnt lgkmcnt(0)
	s_barrier
	s_setprio 3
	s_waitcnt lgkmcnt(0)
	v_mfma_f32_16x16x32_bf16 v[64:67], v[132:135], v[164:167], v[64:67]
	v_mfma_f32_16x16x32_bf16 v[64:67], v[136:139], v[168:171], v[64:67]
	v_mfma_f32_16x16x32_bf16 v[60:63], v[140:143], v[164:167], v[60:63]
	v_mfma_f32_16x16x32_bf16 v[60:63], v[144:147], v[168:171], v[60:63]
	v_mfma_f32_16x16x32_bf16 v[48:51], v[132:135], v[210:213], v[48:51]
	v_mfma_f32_16x16x32_bf16 v[48:51], v[136:139], v[214:217], v[48:51]
	v_mfma_f32_16x16x32_bf16 v[44:47], v[140:143], v[210:213], v[44:47]
	v_mfma_f32_16x16x32_bf16 v[44:47], v[144:147], v[214:217], v[44:47]
	v_mfma_f32_16x16x32_bf16 v[32:35], v[132:135], v[218:221], v[32:35]
	v_mfma_f32_16x16x32_bf16 v[32:35], v[136:139], v[222:225], v[32:35]
	v_mfma_f32_16x16x32_bf16 v[28:31], v[140:143], v[218:221], v[28:31]
	v_mfma_f32_16x16x32_bf16 v[28:31], v[144:147], v[222:225], v[28:31]
	v_mfma_f32_16x16x32_bf16 v[16:19], v[132:135], v[226:229], v[16:19]
	v_mfma_f32_16x16x32_bf16 v[16:19], v[136:139], v[230:233], v[16:19]
	v_mfma_f32_16x16x32_bf16 v[12:15], v[140:143], v[226:229], v[12:15]
	v_mfma_f32_16x16x32_bf16 v[12:15], v[144:147], v[230:233], v[12:15]
	s_setprio 0
	s_setprio 3
	v_mfma_f32_16x16x32_bf16 v[56:59], v[148:151], v[164:167], v[56:59]
	v_mfma_f32_16x16x32_bf16 v[56:59], v[152:155], v[168:171], v[56:59]
	v_mfma_f32_16x16x32_bf16 v[52:55], v[156:159], v[164:167], v[52:55]
	v_mfma_f32_16x16x32_bf16 v[52:55], v[160:163], v[168:171], v[52:55]
	v_mfma_f32_16x16x32_bf16 v[40:43], v[148:151], v[210:213], v[40:43]
	v_mfma_f32_16x16x32_bf16 v[40:43], v[152:155], v[214:217], v[40:43]
	v_mfma_f32_16x16x32_bf16 v[36:39], v[156:159], v[210:213], v[36:39]
	v_mfma_f32_16x16x32_bf16 v[36:39], v[160:163], v[214:217], v[36:39]
	v_mfma_f32_16x16x32_bf16 v[24:27], v[148:151], v[218:221], v[24:27]
	v_mfma_f32_16x16x32_bf16 v[24:27], v[152:155], v[222:225], v[24:27]
	v_mfma_f32_16x16x32_bf16 v[20:23], v[156:159], v[218:221], v[20:23]
	v_mfma_f32_16x16x32_bf16 v[20:23], v[160:163], v[222:225], v[20:23]
	v_mfma_f32_16x16x32_bf16 v[8:11], v[148:151], v[226:229], v[8:11]
	v_mfma_f32_16x16x32_bf16 v[8:11], v[152:155], v[230:233], v[8:11]
	v_mfma_f32_16x16x32_bf16 v[4:7], v[156:159], v[226:229], v[4:7]
	v_mfma_f32_16x16x32_bf16 v[4:7], v[160:163], v[230:233], v[4:7]
	s_setprio 0
	s_barrier
	s_add_i32 s61, s61, 2
	s_add_u32 s12, s12, 0x100
	s_addc_u32 s13, s13, 0
	s_cmpk_gt_u32 s61, 0xa9
	s_cbranch_scc1 .LBB0_978

; #define PG8_STAGE(bufoff, gbase, voff) do { _Pragma("unroll") for (int _i = 0; _i < 2; ++_i) \
;         __builtin_amdgcn_global_load_lds((const unsigned*)((const char*)(gbase) + (voff)[_i]), (PG8_LAS unsigned*)(lds + (bufoff) + ldsw + _i * 8192), 16, 0, 0); } while (0)
; #define PG8_LDA(dst, b, h) do { _Pragma("unroll") for (int m = 0; m < 4; ++m) _Pragma("unroll") for (int k = 0; k < 2; ++k) dst[m][k] = *(const PG8_LAS bf16x8*)(lds + PG8_SA(b, h) + aoff + m * 2048 + k * 1024); } while (0)
; #define PG8_LDB(dst, b, h) do { _Pragma("unroll") for (int n = 0; n < 2; ++n) _Pragma("unroll") for (int k = 0; k < 2; ++k) dst[n][k] = *(const PG8_LAS bf16x8*)(lds + PG8_SB(b, h) + boff + n * 2048 + k * 1024); } while (0)
; #define PG8_MMA(ai, bj, At, Bt) do { __builtin_amdgcn_s_setprio(3); _Pragma("unroll") for (int m = 0; m < 4; ++m) _Pragma("unroll") for (int n = 0; n < 2; ++n) _Pragma("unroll") for (int k = 0; k < 2; ++k) \
;         acc[ai][bj][m][n] = __builtin_amdgcn_mfma_f32_16x16x32_bf16(Bt[n][k], At[m][k], acc[ai][bj][m][n], 0, 0, 0); __builtin_amdgcn_s_setprio(0); } while (0)
; #define PG8_WAIT_V(n) asm volatile("s_waitcnt vmcnt(" #n ")" ::: "memory")
; #define PG8_WAIT_L(n) asm volatile("s_waitcnt lgkmcnt(" #n ")" ::: "memory")
; #define PG8_BAR __builtin_amdgcn_s_barrier()
; #define PG8_SCHED __builtin_amdgcn_sched_barrier(0)
; template <class Epi, class Sched, bool ALIGN_EPI = false, bool SP2 = false>
; __device__ __forceinline__ void gemm_phase(PG8_LAS unsigned char* lds, const Gemm g, const Sched& S, const Epi& E) {
;     ...
;             const char* a1 = cA + (size_t)(t + 1) * kstep;
;             const char* a2 = last ? nA : cA + (size_t)(t + 2) * kstep; const char* b2 = last ? nB : cB + (size_t)(t + 2) * kstep;
;             const char* a3 = a2 + kstep; const char* b3 = b2 + kstep;
;             if (last && has_next) S.a_ready(nxt);
;             if constexpr (Epi::MIDK) { if (t == E.midk_step(nt)) E.midk(acc, cur, wr, wc, fr, fq); }
;             if constexpr (SP2) {
;             PG8_LDB(B0, 0, 0); PG8_LDB(B1, 0, 1); PG8_SCHED; PG8_LDA(At, 0, 0); PG8_STAGE(PG8_SA(1, 1), a1 + hstepA, voffA);
;             PG8_WAIT_V(8); PG8_WAIT_L(0); PG8_BAR; PG8_MMA(0, 0, At, B0); PG8_MMA(0, 1, At, B1); PG8_BAR; PG8_SCHED;
;             PG8_LDA(At, 0, 1); PG8_STAGE(PG8_SB(0, 0), b2, voffB); PG8_STAGE(PG8_SB(0, 1), b2 + hstepB, voffB); PG8_STAGE(PG8_SA(0, 0), a2, voffA);
.LBB0_1018:
	v_add_u32_e32 v142, s46, v189
	v_add_u32_e32 v158, s47, v189
	s_add_u32 s40, s20, s22
	ds_read_b128 v[130:133], v142
	ds_read_b128 v[134:137], v142 offset:1024
	ds_read_b128 v[138:141], v142 offset:2048
	ds_read_b128 v[142:145], v142 offset:3072
	ds_read_b128 v[146:149], v158
	ds_read_b128 v[150:153], v158 offset:1024
	ds_read_b128 v[154:157], v158 offset:2048
	ds_read_b128 v[158:161], v158 offset:3072
	s_addc_u32 s41, s21, s23
	s_add_u32 s40, s40, 0x21500100
	s_addc_u32 s41, s41, 0
	s_add_u32 s87, s44, s22
	s_addc_u32 s88, s45, s23
	s_cmpk_eq_i32 s22, 0x5500
	s_cselect_b32 s43, s17, s41
	s_cselect_b32 s42, s16, s40
	s_cselect_b32 s41, s11, s88
	s_cselect_b32 s40, s10, s87
	s_mov_b32 m0, s77
	v_lshl_add_u64 v[186:187], v[0:1], 0, s[22:23]
	ds_read_b128 v[162:165], v180
	ds_read_b128 v[166:169], v180 offset:1024
	ds_read_b128 v[182:185], v180 offset:2048
	ds_read_b128 v[190:193], v180 offset:3072
	ds_read_b128 v[194:197], v180 offset:4096
	ds_read_b128 v[208:211], v180 offset:5120
	ds_read_b128 v[212:215], v180 offset:6144
	ds_read_b128 v[216:219], v180 offset:7168
	global_load_lds_dwordx4 v[186:187], off
	v_lshl_add_u64 v[186:187], v[170:171], 0, s[22:23]
	s_mov_b32 m0, s78
	s_nop 0
	global_load_lds_dwordx4 v[186:187], off
	s_waitcnt vmcnt(8)
	s_waitcnt lgkmcnt(0)
	s_barrier
	s_setprio 3
	s_waitcnt lgkmcnt(0)
	v_mfma_f32_16x16x32_bf16 v[126:129], v[130:133], v[162:165], v[126:129]
	v_mfma_f32_16x16x32_bf16 v[126:129], v[134:137], v[166:169], v[126:129]
	v_mfma_f32_16x16x32_bf16 v[122:125], v[138:141], v[162:165], v[122:125]
	v_mfma_f32_16x16x32_bf16 v[122:125], v[142:145], v[166:169], v[122:125]
	v_mfma_f32_16x16x32_bf16 v[98:101], v[130:133], v[182:185], v[98:101]
	v_mfma_f32_16x16x32_bf16 v[98:101], v[134:137], v[190:193], v[98:101]
	v_mfma_f32_16x16x32_bf16 v[94:97], v[138:141], v[182:185], v[94:97]
	v_mfma_f32_16x16x32_bf16 v[94:97], v[142:145], v[190:193], v[94:97]
	v_mfma_f32_16x16x32_bf16 v[110:113], v[130:133], v[194:197], v[110:113]
	v_mfma_f32_16x16x32_bf16 v[110:113], v[134:137], v[208:211], v[110:113]
	v_mfma_f32_16x16x32_bf16 v[106:109], v[138:141], v[194:197], v[106:109]
	v_mfma_f32_16x16x32_bf16 v[106:109], v[142:145], v[208:211], v[106:109]
	v_mfma_f32_16x16x32_bf16 v[78:81], v[130:133], v[212:215], v[78:81]
	v_mfma_f32_16x16x32_bf16 v[78:81], v[134:137], v[216:219], v[78:81]
	v_mfma_f32_16x16x32_bf16 v[74:77], v[138:141], v[212:215], v[74:77]
	v_mfma_f32_16x16x32_bf16 v[74:77], v[142:145], v[216:219], v[74:77]
	s_setprio 0
	s_setprio 3
	v_mfma_f32_16x16x32_bf16 v[118:121], v[146:149], v[162:165], v[118:121]
	v_mfma_f32_16x16x32_bf16 v[118:121], v[150:153], v[166:169], v[118:121]
	v_mfma_f32_16x16x32_bf16 v[114:117], v[154:157], v[162:165], v[114:117]
	v_mfma_f32_16x16x32_bf16 v[114:117], v[158:161], v[166:169], v[114:117]
	v_mfma_f32_16x16x32_bf16 v[90:93], v[146:149], v[182:185], v[90:93]
	v_mfma_f32_16x16x32_bf16 v[90:93], v[150:153], v[190:193], v[90:93]
	v_mfma_f32_16x16x32_bf16 v[86:89], v[154:157], v[182:185], v[86:89]
	v_mfma_f32_16x16x32_bf16 v[86:89], v[158:161], v[190:193], v[86:89]
	v_mfma_f32_16x16x32_bf16 v[102:105], v[146:149], v[194:197], v[102:105]
	v_mfma_f32_16x16x32_bf16 v[102:105], v[150:153], v[208:211], v[102:105]
	v_mfma_f32_16x16x32_bf16 v[82:85], v[154:157], v[194:197], v[82:85]
	v_mfma_f32_16x16x32_bf16 v[82:85], v[158:161], v[208:211], v[82:85]
	v_mfma_f32_16x16x32_bf16 v[70:73], v[146:149], v[212:215], v[70:73]
	v_mfma_f32_16x16x32_bf16 v[70:73], v[150:153], v[216:219], v[70:73]
	v_mfma_f32_16x16x32_bf16 v[66:69], v[154:157], v[212:215], v[66:69]
	v_mfma_f32_16x16x32_bf16 v[66:69], v[158:161], v[216:219], v[66:69]
	s_setprio 0
	s_barrier
	s_mov_b32 m0, s79
	v_lshl_add_u64 v[186:187], s[40:41], 0, v[174:175]
	s_add_u32 s88, s40, 0x2b0000
	ds_read_b128 v[162:165], v180 offset:16384
	ds_read_b128 v[166:169], v180 offset:17408
	ds_read_b128 v[182:185], v180 offset:18432
	ds_read_b128 v[190:193], v180 offset:19456
	ds_read_b128 v[194:197], v180 offset:20480
	ds_read_b128 v[208:211], v180 offset:21504
	ds_read_b128 v[212:215], v180 offset:22528
	ds_read_b128 v[216:219], v180 offset:23552
	global_load_lds_dwordx4 v[186:187], off
	v_lshl_add_u64 v[198:199], s[40:41], 0, v[178:179]
	s_mov_b32 m0, s80
	s_addc_u32 s89, s41, 0
	global_load_lds_dwordx4 v[198:199], off
	v_lshl_add_u64 v[204:205], s[88:89], 0, v[174:175]
	s_mov_b32 m0, s81
	v_lshl_add_u64 v[220:221], s[42:43], 0, v[176:177]
	global_load_lds_dwordx4 v[204:205], off
	v_lshl_add_u64 v[204:205], s[88:89], 0, v[178:179]
	s_mov_b32 m0, s82
	s_nop 0
	global_load_lds_dwordx4 v[204:205], off
	v_lshl_add_u64 v[204:205], s[42:43], 0, v[172:173]
	s_mov_b32 m0, s58
	s_nop 0
	global_load_lds_dwordx4 v[204:205], off
	s_mov_b32 m0, s60
	s_nop 0
	global_load_lds_dwordx4 v[220:221], off
	s_waitcnt vmcnt(8)
	s_waitcnt lgkmcnt(0)
	s_barrier
; #define PG8_STAGE(bufoff, gbase, voff) do { _Pragma("unroll") for (int _i = 0; _i < 2; ++_i) \
;         __builtin_amdgcn_global_load_lds((const unsigned*)((const char*)(gbase) + (voff)[_i]), (PG8_LAS unsigned*)(lds + (bufoff) + ldsw + _i * 8192), 16, 0, 0); } while (0)
; #define PG8_LDA(dst, b, h) do { _Pragma("unroll") for (int m = 0; m < 4; ++m) _Pragma("unroll") for (int k = 0; k < 2; ++k) dst[m][k] = *(const PG8_LAS bf16x8*)(lds + PG8_SA(b, h) + aoff + m * 2048 + k * 1024); } while (0)
; #define PG8_LDB(dst, b, h) do { _Pragma("unroll") for (int n = 0; n < 2; ++n) _Pragma("unroll") for (int k = 0; k < 2; ++k) dst[n][k] = *(const PG8_LAS bf16x8*)(lds + PG8_SB(b, h) + boff + n * 2048 + k * 1024); } while (0)
; #define PG8_MMA(ai, bj, At, Bt) do { __builtin_amdgcn_s_setprio(3); _Pragma("unroll") for (int m = 0; m < 4; ++m) _Pragma("unroll") for (int n = 0; n < 2; ++n) _Pragma("unroll") for (int k = 0; k < 2; ++k) \
;         acc[ai][bj][m][n] = __builtin_amdgcn_mfma_f32_16x16x32_bf16(Bt[n][k], At[m][k], acc[ai][bj][m][n], 0, 0, 0); __builtin_amdgcn_s_setprio(0); } while (0)
; #define PG8_WAIT_V(n) asm volatile("s_waitcnt vmcnt(" #n ")" ::: "memory")
; #define PG8_WAIT_L(n) asm volatile("s_waitcnt lgkmcnt(" #n ")" ::: "memory")
; #define PG8_BAR __builtin_amdgcn_s_barrier()
; #define PG8_SCHED __builtin_amdgcn_sched_barrier(0)
; template <class Epi, class Sched, bool ALIGN_EPI = false, bool SP2 = false>
; __device__ __forceinline__ void gemm_phase(PG8_LAS unsigned char* lds, const Gemm g, const Sched& S, const Epi& E) {
;     ...
;             PG8_WAIT_V(8); PG8_WAIT_L(0); PG8_BAR; PG8_MMA(1, 0, At, B0); PG8_MMA(1, 1, At, B1); PG8_BAR; PG8_SCHED;
;             PG8_LDB(B0, 1, 0); PG8_LDB(B1, 1, 1); PG8_SCHED; PG8_LDA(At, 1, 0); PG8_STAGE(PG8_SA(0, 1), a2 + hstepA, voffA);
;             PG8_WAIT_V(8); PG8_WAIT_L(0); PG8_BAR; PG8_MMA(0, 0, At, B0); PG8_MMA(0, 1, At, B1); PG8_BAR; PG8_SCHED;
	s_setprio 3
	s_waitcnt lgkmcnt(0)
	v_mfma_f32_16x16x32_bf16 v[62:65], v[130:133], v[162:165], v[62:65]
	v_mfma_f32_16x16x32_bf16 v[62:65], v[134:137], v[166:169], v[62:65]
	v_mfma_f32_16x16x32_bf16 v[58:61], v[138:141], v[162:165], v[58:61]
	v_mfma_f32_16x16x32_bf16 v[58:61], v[142:145], v[166:169], v[58:61]
	v_mfma_f32_16x16x32_bf16 v[46:49], v[130:133], v[182:185], v[46:49]
	v_mfma_f32_16x16x32_bf16 v[46:49], v[134:137], v[190:193], v[46:49]
	v_mfma_f32_16x16x32_bf16 v[42:45], v[138:141], v[182:185], v[42:45]
	v_mfma_f32_16x16x32_bf16 v[42:45], v[142:145], v[190:193], v[42:45]
	v_mfma_f32_16x16x32_bf16 v[30:33], v[130:133], v[194:197], v[30:33]
	v_mfma_f32_16x16x32_bf16 v[30:33], v[134:137], v[208:211], v[30:33]
	v_mfma_f32_16x16x32_bf16 v[26:29], v[138:141], v[194:197], v[26:29]
	v_mfma_f32_16x16x32_bf16 v[26:29], v[142:145], v[208:211], v[26:29]
	v_mfma_f32_16x16x32_bf16 v[14:17], v[130:133], v[212:215], v[14:17]
	v_mfma_f32_16x16x32_bf16 v[14:17], v[134:137], v[216:219], v[14:17]
	v_mfma_f32_16x16x32_bf16 v[10:13], v[138:141], v[212:215], v[10:13]
	v_mfma_f32_16x16x32_bf16 v[10:13], v[142:145], v[216:219], v[10:13]
	s_setprio 0
	s_setprio 3
	v_mfma_f32_16x16x32_bf16 v[54:57], v[146:149], v[162:165], v[54:57]
	v_mfma_f32_16x16x32_bf16 v[54:57], v[150:153], v[166:169], v[54:57]
	v_mfma_f32_16x16x32_bf16 v[50:53], v[154:157], v[162:165], v[50:53]
	v_mfma_f32_16x16x32_bf16 v[50:53], v[158:161], v[166:169], v[50:53]
	v_mfma_f32_16x16x32_bf16 v[38:41], v[146:149], v[182:185], v[38:41]
	v_mfma_f32_16x16x32_bf16 v[38:41], v[150:153], v[190:193], v[38:41]
	v_mfma_f32_16x16x32_bf16 v[34:37], v[154:157], v[182:185], v[34:37]
	v_mfma_f32_16x16x32_bf16 v[34:37], v[158:161], v[190:193], v[34:37]
	v_mfma_f32_16x16x32_bf16 v[22:25], v[146:149], v[194:197], v[22:25]
	v_mfma_f32_16x16x32_bf16 v[22:25], v[150:153], v[208:211], v[22:25]
	v_mfma_f32_16x16x32_bf16 v[18:21], v[154:157], v[194:197], v[18:21]
	v_mfma_f32_16x16x32_bf16 v[18:21], v[158:161], v[208:211], v[18:21]
	v_mfma_f32_16x16x32_bf16 v[6:9], v[146:149], v[212:215], v[6:9]
	v_mfma_f32_16x16x32_bf16 v[6:9], v[150:153], v[216:219], v[6:9]
	v_mfma_f32_16x16x32_bf16 v[2:5], v[154:157], v[212:215], v[2:5]
	v_mfma_f32_16x16x32_bf16 v[2:5], v[158:161], v[216:219], v[2:5]
	s_setprio 0
	s_barrier
	v_add_u32_e32 v142, s52, v189
	v_add_u32_e32 v158, s53, v189
	ds_read_b128 v[130:133], v142
	ds_read_b128 v[134:137], v142 offset:1024
	ds_read_b128 v[138:141], v142 offset:2048
	ds_read_b128 v[142:145], v142 offset:3072
	ds_read_b128 v[146:149], v158
	ds_read_b128 v[150:153], v158 offset:1024
	ds_read_b128 v[154:157], v158 offset:2048
	ds_read_b128 v[158:161], v158 offset:3072
	s_add_u32 s42, s42, 0x2b0000
	s_addc_u32 s43, s43, 0
	s_mov_b32 m0, s61
	v_lshl_add_u64 v[222:223], s[42:43], 0, v[172:173]
	ds_read_b128 v[162:165], v180 offset:32768
	ds_read_b128 v[166:169], v180 offset:33792
	ds_read_b128 v[182:185], v180 offset:34816
	ds_read_b128 v[190:193], v180 offset:35840
	ds_read_b128 v[194:197], v180 offset:36864
	ds_read_b128 v[208:211], v180 offset:37888
	ds_read_b128 v[212:215], v180 offset:38912
	ds_read_b128 v[216:219], v180 offset:39936
	global_load_lds_dwordx4 v[222:223], off
	v_lshl_add_u64 v[222:223], s[42:43], 0, v[176:177]
	s_mov_b32 m0, s62
	s_nop 0
	global_load_lds_dwordx4 v[222:223], off
	s_waitcnt vmcnt(8)
	s_waitcnt lgkmcnt(0)
	s_barrier
	s_setprio 3
	s_waitcnt lgkmcnt(0)
	v_mfma_f32_16x16x32_bf16 v[126:129], v[130:133], v[162:165], v[126:129]
	v_mfma_f32_16x16x32_bf16 v[126:129], v[134:137], v[166:169], v[126:129]
	v_mfma_f32_16x16x32_bf16 v[122:125], v[138:141], v[162:165], v[122:125]
	v_mfma_f32_16x16x32_bf16 v[122:125], v[142:145], v[166:169], v[122:125]
	v_mfma_f32_16x16x32_bf16 v[98:101], v[130:133], v[182:185], v[98:101]
	v_mfma_f32_16x16x32_bf16 v[98:101], v[134:137], v[190:193], v[98:101]
	v_mfma_f32_16x16x32_bf16 v[94:97], v[138:141], v[182:185], v[94:97]
	v_mfma_f32_16x16x32_bf16 v[94:97], v[142:145], v[190:193], v[94:97]
	v_mfma_f32_16x16x32_bf16 v[110:113], v[130:133], v[194:197], v[110:113]
	v_mfma_f32_16x16x32_bf16 v[110:113], v[134:137], v[208:211], v[110:113]
	v_mfma_f32_16x16x32_bf16 v[106:109], v[138:141], v[194:197], v[106:109]
	v_mfma_f32_16x16x32_bf16 v[106:109], v[142:145], v[208:211], v[106:109]
	v_mfma_f32_16x16x32_bf16 v[78:81], v[130:133], v[212:215], v[78:81]
	v_mfma_f32_16x16x32_bf16 v[78:81], v[134:137], v[216:219], v[78:81]
	v_mfma_f32_16x16x32_bf16 v[74:77], v[138:141], v[212:215], v[74:77]
	v_mfma_f32_16x16x32_bf16 v[74:77], v[142:145], v[216:219], v[74:77]
	s_setprio 0
	s_setprio 3
	v_mfma_f32_16x16x32_bf16 v[118:121], v[146:149], v[162:165], v[118:121]
	v_mfma_f32_16x16x32_bf16 v[118:121], v[150:153], v[166:169], v[118:121]
	v_mfma_f32_16x16x32_bf16 v[114:117], v[154:157], v[162:165], v[114:117]
	v_mfma_f32_16x16x32_bf16 v[114:117], v[158:161], v[166:169], v[114:117]
	v_mfma_f32_16x16x32_bf16 v[90:93], v[146:149], v[182:185], v[90:93]
	v_mfma_f32_16x16x32_bf16 v[90:93], v[150:153], v[190:193], v[90:93]
	v_mfma_f32_16x16x32_bf16 v[86:89], v[154:157], v[182:185], v[86:89]
	v_mfma_f32_16x16x32_bf16 v[86:89], v[158:161], v[190:193], v[86:89]
	v_mfma_f32_16x16x32_bf16 v[102:105], v[146:149], v[194:197], v[102:105]
	v_mfma_f32_16x16x32_bf16 v[102:105], v[150:153], v[208:211], v[102:105]
	v_mfma_f32_16x16x32_bf16 v[82:85], v[154:157], v[194:197], v[82:85]
	v_mfma_f32_16x16x32_bf16 v[82:85], v[158:161], v[208:211], v[82:85]
	v_mfma_f32_16x16x32_bf16 v[70:73], v[146:149], v[212:215], v[70:73]
	v_mfma_f32_16x16x32_bf16 v[70:73], v[150:153], v[216:219], v[70:73]
	v_mfma_f32_16x16x32_bf16 v[66:69], v[154:157], v[212:215], v[66:69]
	v_mfma_f32_16x16x32_bf16 v[66:69], v[158:161], v[216:219], v[66:69]
	s_setprio 0
	s_barrier
; #define PG8_STAGE(bufoff, gbase, voff) do { _Pragma("unroll") for (int _i = 0; _i < 2; ++_i) \
;         __builtin_amdgcn_global_load_lds((const unsigned*)((const char*)(gbase) + (voff)[_i]), (PG8_LAS unsigned*)(lds + (bufoff) + ldsw + _i * 8192), 16, 0, 0); } while (0)
; #define PG8_LDA(dst, b, h) do { _Pragma("unroll") for (int m = 0; m < 4; ++m) _Pragma("unroll") for (int k = 0; k < 2; ++k) dst[m][k] = *(const PG8_LAS bf16x8*)(lds + PG8_SA(b, h) + aoff + m * 2048 + k * 1024); } while (0)
; #define PG8_MMA(ai, bj, At, Bt) do { __builtin_amdgcn_s_setprio(3); _Pragma("unroll") for (int m = 0; m < 4; ++m) _Pragma("unroll") for (int n = 0; n < 2; ++n) _Pragma("unroll") for (int k = 0; k < 2; ++k) \
;         acc[ai][bj][m][n] = __builtin_amdgcn_mfma_f32_16x16x32_bf16(Bt[n][k], At[m][k], acc[ai][bj][m][n], 0, 0, 0); __builtin_amdgcn_s_setprio(0); } while (0)
; #define PG8_WAIT_V(n) asm volatile("s_waitcnt vmcnt(" #n ")" ::: "memory")
; #define PG8_WAIT_L(n) asm volatile("s_waitcnt lgkmcnt(" #n ")" ::: "memory")
; #define PG8_BAR __builtin_amdgcn_s_barrier()
; #define PG8_SCHED __builtin_amdgcn_sched_barrier(0)
; template <class Epi, class Sched, bool ALIGN_EPI = false, bool SP2 = false>
; __device__ __forceinline__ void gemm_phase(PG8_LAS unsigned char* lds, const Gemm g, const Sched& S, const Epi& E) {
;     ...
;             PG8_LDA(At, 1, 1); PG8_STAGE(PG8_SB(1, 0), b3, voffB); PG8_STAGE(PG8_SB(1, 1), b3 + hstepB, voffB); PG8_STAGE(PG8_SA(1, 0), a3, voffA);
;             PG8_WAIT_V(8); PG8_WAIT_L(0); PG8_BAR; PG8_MMA(1, 0, At, B0); PG8_MMA(1, 1, At, B1); PG8_BAR; PG8_SCHED;
	s_mov_b32 m0, s83
	v_lshl_add_u64 v[186:187], v[186:187], 0, s[18:19]
	s_add_u32 s40, s40, 0x2b0080
	ds_read_b128 v[162:165], v180 offset:49152
	ds_read_b128 v[166:169], v180 offset:50176
	ds_read_b128 v[182:185], v180 offset:51200
	ds_read_b128 v[190:193], v180 offset:52224
	ds_read_b128 v[194:197], v180 offset:53248
	ds_read_b128 v[208:211], v180 offset:54272
	ds_read_b128 v[212:215], v180 offset:55296
	ds_read_b128 v[216:219], v180 offset:56320
	global_load_lds_dwordx4 v[186:187], off
	v_lshl_add_u64 v[186:187], v[198:199], 0, s[18:19]
	s_mov_b32 m0, s84
	s_addc_u32 s41, s41, 0
	global_load_lds_dwordx4 v[186:187], off
	v_lshl_add_u64 v[186:187], s[40:41], 0, v[174:175]
	s_mov_b32 m0, s85
	s_nop 0
	global_load_lds_dwordx4 v[186:187], off
	v_lshl_add_u64 v[186:187], s[40:41], 0, v[178:179]
	s_mov_b32 m0, s86
	s_nop 0
	global_load_lds_dwordx4 v[186:187], off
	v_lshl_add_u64 v[186:187], v[204:205], 0, s[18:19]
	s_mov_b32 m0, s63
	s_nop 0
	global_load_lds_dwordx4 v[186:187], off
	v_lshl_add_u64 v[186:187], v[220:221], 0, s[18:19]
	s_mov_b32 m0, s64
	s_nop 0
	global_load_lds_dwordx4 v[186:187], off
	s_waitcnt vmcnt(8)
	s_waitcnt lgkmcnt(0)
	s_barrier
	s_setprio 3
	s_waitcnt lgkmcnt(0)
	v_mfma_f32_16x16x32_bf16 v[62:65], v[130:133], v[162:165], v[62:65]
	v_mfma_f32_16x16x32_bf16 v[62:65], v[134:137], v[166:169], v[62:65]
	v_mfma_f32_16x16x32_bf16 v[58:61], v[138:141], v[162:165], v[58:61]
	v_mfma_f32_16x16x32_bf16 v[58:61], v[142:145], v[166:169], v[58:61]
	v_mfma_f32_16x16x32_bf16 v[46:49], v[130:133], v[182:185], v[46:49]
	v_mfma_f32_16x16x32_bf16 v[46:49], v[134:137], v[190:193], v[46:49]
	v_mfma_f32_16x16x32_bf16 v[42:45], v[138:141], v[182:185], v[42:45]
	v_mfma_f32_16x16x32_bf16 v[42:45], v[142:145], v[190:193], v[42:45]
	v_mfma_f32_16x16x32_bf16 v[30:33], v[130:133], v[194:197], v[30:33]
	v_mfma_f32_16x16x32_bf16 v[30:33], v[134:137], v[208:211], v[30:33]
	v_mfma_f32_16x16x32_bf16 v[26:29], v[138:141], v[194:197], v[26:29]
	v_mfma_f32_16x16x32_bf16 v[26:29], v[142:145], v[208:211], v[26:29]
	v_mfma_f32_16x16x32_bf16 v[14:17], v[130:133], v[212:215], v[14:17]
	v_mfma_f32_16x16x32_bf16 v[14:17], v[134:137], v[216:219], v[14:17]
	v_mfma_f32_16x16x32_bf16 v[10:13], v[138:141], v[212:215], v[10:13]
	v_mfma_f32_16x16x32_bf16 v[10:13], v[142:145], v[216:219], v[10:13]
	s_setprio 0
	s_setprio 3
	v_mfma_f32_16x16x32_bf16 v[54:57], v[146:149], v[162:165], v[54:57]
	v_mfma_f32_16x16x32_bf16 v[54:57], v[150:153], v[166:169], v[54:57]
	v_mfma_f32_16x16x32_bf16 v[50:53], v[154:157], v[162:165], v[50:53]
	v_mfma_f32_16x16x32_bf16 v[50:53], v[158:161], v[166:169], v[50:53]
	v_mfma_f32_16x16x32_bf16 v[38:41], v[146:149], v[182:185], v[38:41]
	v_mfma_f32_16x16x32_bf16 v[38:41], v[150:153], v[190:193], v[38:41]
	v_mfma_f32_16x16x32_bf16 v[34:37], v[154:157], v[182:185], v[34:37]
	v_mfma_f32_16x16x32_bf16 v[34:37], v[158:161], v[190:193], v[34:37]
	v_mfma_f32_16x16x32_bf16 v[22:25], v[146:149], v[194:197], v[22:25]
	v_mfma_f32_16x16x32_bf16 v[22:25], v[150:153], v[208:211], v[22:25]
	v_mfma_f32_16x16x32_bf16 v[18:21], v[154:157], v[194:197], v[18:21]
	v_mfma_f32_16x16x32_bf16 v[18:21], v[158:161], v[208:211], v[18:21]
	v_mfma_f32_16x16x32_bf16 v[6:9], v[146:149], v[212:215], v[6:9]
	v_mfma_f32_16x16x32_bf16 v[6:9], v[150:153], v[216:219], v[6:9]
	v_mfma_f32_16x16x32_bf16 v[2:5], v[154:157], v[212:215], v[2:5]
	v_mfma_f32_16x16x32_bf16 v[2:5], v[158:161], v[216:219], v[2:5]
	s_setprio 0
	s_barrier
	s_add_i32 s67, s67, 2
	s_add_u32 s22, s22, 0x100
	s_addc_u32 s23, s23, 0
	s_cmpk_gt_u32 s67, 0xa9
	s_cbranch_scc1 .LBB0_1021
